# second measurement of the static-priority variant (v15 + static prio for waves 4-7, no per-phase flips)
# speedup vs baseline: 1.0045x; 1.0012x over previous
; __global__ void __launch_bounds__(512, 2) fwd_megakernel(Prm p) {
;     ...
;     const int tid = threadIdx.x, lane = tid & 63, wave = __builtin_amdgcn_readfirstlane(tid >> 6);
;     const int gw = blockIdx.x * 8 + wave, NGW = gridDim.x * 8, gtid = blockIdx.x * 512 + tid, GT = gridDim.x * 512;
.LBB0_5:
	s_or_b64 exec, exec, s[2:3]
	s_load_dwordx16 s[68:83], s[0:1], 0x40
	s_load_dwordx16 s[12:27], s[0:1], 0x80
	s_load_dwordx4 s[4:7], s[0:1], 0x140
	v_and_b32_e32 v152, 63, v154
	v_lshrrev_b32_e32 v158, 3, v152
	v_lshlrev_b32_e32 v161, 4, v154
	s_waitcnt lgkmcnt(0)
	v_writelane_b32 v254, s4, 45
	s_nop 1
	v_writelane_b32 v254, s5, 46
	v_writelane_b32 v254, s6, 47
	v_writelane_b32 v254, s7, 48
	s_nop 0
	v_readlane_b32 s2, v254, 9
	s_lshr_b32 s3, s2, 6
	s_cmp_ge_u32 s3, 4
	s_cbranch_scc0 .Lprio_done
	s_setprio 1
.Lprio_done:
	s_lshl_b32 s2, s84, 3
	v_writelane_b32 v254, s3, 49
	s_add_i32 s4, s3, s2
	s_lshl_b32 s2, s88, 3
	v_writelane_b32 v254, s2, 50
	s_cmpk_gt_i32 s4, 0x4ff
	s_nop 0
	v_writelane_b32 v254, s3, 51
	s_mov_b32 s2, s4
	v_writelane_b32 v254, s2, 52
	s_nop 1
	v_writelane_b32 v254, s3, 53
	s_cbranch_scc1 .LBB0_76

; #define PG8_STAGE(bufoff, gbase, voff) do { _Pragma("unroll") for (int _i = 0; _i < 2; ++_i) \
;         __builtin_amdgcn_global_load_lds((const unsigned*)((const char*)(gbase) + (voff)[_i]), (PG8_LAS unsigned*)(lds + (bufoff) + ldsw + _i * 8192), 16, 0, 0); } while (0)
; #define PG8_LDA(dst, b, h) do { _Pragma("unroll") for (int m = 0; m < 4; ++m) _Pragma("unroll") for (int k = 0; k < 2; ++k) dst[m][k] = *(const PG8_LAS bf16x8*)(lds + PG8_SA(b, h) + aoff + m * 2048 + k * 1024); } while (0)
; #define PG8_LDB(dst, b, h) do { _Pragma("unroll") for (int n = 0; n < 2; ++n) _Pragma("unroll") for (int k = 0; k < 2; ++k) dst[n][k] = *(const PG8_LAS bf16x8*)(lds + PG8_SB(b, h) + boff + n * 2048 + k * 1024); } while (0)
; #define PG8_MMA(ai, bj, At, Bt) do { __builtin_amdgcn_s_setprio(1); _Pragma("unroll") for (int m = 0; m < 4; ++m) _Pragma("unroll") for (int n = 0; n < 2; ++n) _Pragma("unroll") for (int k = 0; k < 2; ++k) \
;         acc[ai][bj][m][n] = __builtin_amdgcn_mfma_f32_16x16x32_bf16(Bt[n][k], At[m][k], acc[ai][bj][m][n], 0, 0, 0); __builtin_amdgcn_s_setprio(0); } while (0)
; #define PG8_WAIT_L(n) asm volatile("s_waitcnt lgkmcnt(" #n ")" ::: "memory")
; #define PG8_BAR __builtin_amdgcn_s_barrier()
; #define PG8_SCHED __builtin_amdgcn_sched_barrier(0)
; template <class Epi, class Sched>
; __device__ __forceinline__ void gemm_phase(PG8_LAS unsigned char* lds, const Gemm g, const Sched& S, const Epi& E) {
;     ...
;             PG8_LDB(B0, 0, 0); PG8_SCHED; PG8_LDA(At, 0, 0); PG8_STAGE(PG8_SA(1, 1), a1 + hstep, voffA);
;             PG8_WAIT_L(8); PG8_BAR; PG8_WAIT_L(0); PG8_MMA(0, 0, At, B0); PG8_BAR; PG8_SCHED;
;             PG8_LDB(B1, 0, 1); PG8_STAGE(PG8_SB(0, 0), b2, voffB);
;             PG8_BAR; PG8_WAIT_L(0); PG8_MMA(0, 1, At, B1); PG8_BAR;
;             PG8_LDA(At, 0, 1); PG8_STAGE(PG8_SA(0, 0), a2, voffA);
;             PG8_BAR; PG8_WAIT_L(0); PG8_MMA(1, 0, At, B0); PG8_BAR; PG8_SCHED;
.LBB0_194:
	v_add_u32_e32 v14, s6, v155
	ds_read_b128 v[24:27], v14
	ds_read_b128 v[32:35], v14 offset:1024
	ds_read_b128 v[36:39], v14 offset:2048
	ds_read_b128 v[144:147], v14 offset:3072
	s_add_u32 s22, s0, 0xfffc0080
	s_addc_u32 s23, s1, -1
	s_and_b64 s[20:21], s[20:21], exec
	s_cselect_b32 s23, s11, s23
	s_cselect_b32 s22, s15, s22
	s_cselect_b32 s21, s13, s2
	s_cselect_b32 s20, vcc_lo, vcc_hi
	v_lshl_add_u64 v[14:15], s[0:1], 0, v[176:177]
	s_add_i32 m0, s25, 0xc000
	ds_read_b128 v[148:151], v163
	ds_read_b128 v[192:195], v163 offset:1024
	ds_read_b128 v[196:199], v163 offset:2048
	ds_read_b128 v[200:203], v163 offset:3072
	ds_read_b128 v[210:213], v163 offset:4096
	ds_read_b128 v[214:217], v163 offset:5120
	ds_read_b128 v[218:221], v163 offset:6144
	ds_read_b128 v[222:225], v163 offset:7168
	global_load_lds_dwordx4 v[14:15], off
	s_add_i32 m0, s25, 0xe000
	v_lshl_add_u64 v[14:15], s[0:1], 0, v[178:179]
	global_load_lds_dwordx4 v[14:15], off
	s_waitcnt lgkmcnt(8)
	s_barrier
	s_waitcnt lgkmcnt(0)
	v_mfma_f32_16x16x32_bf16 v[140:143], v[24:27], v[148:151], v[140:143]
	v_mfma_f32_16x16x32_bf16 v[136:139], v[36:39], v[148:151], v[136:139]
	v_mfma_f32_16x16x32_bf16 v[124:127], v[24:27], v[196:199], v[124:127]
	v_mfma_f32_16x16x32_bf16 v[120:123], v[36:39], v[196:199], v[120:123]
	v_mfma_f32_16x16x32_bf16 v[108:111], v[24:27], v[210:213], v[108:111]
	v_mfma_f32_16x16x32_bf16 v[104:107], v[36:39], v[210:213], v[104:107]
	v_mfma_f32_16x16x32_bf16 v[92:95], v[24:27], v[218:221], v[92:95]
	v_mfma_f32_16x16x32_bf16 v[88:91], v[36:39], v[218:221], v[88:91]
	v_mfma_f32_16x16x32_bf16 v[140:143], v[32:35], v[192:195], v[140:143]
	v_mfma_f32_16x16x32_bf16 v[136:139], v[144:147], v[192:195], v[136:139]
	v_mfma_f32_16x16x32_bf16 v[124:127], v[32:35], v[200:203], v[124:127]
	v_mfma_f32_16x16x32_bf16 v[120:123], v[144:147], v[200:203], v[120:123]
	v_mfma_f32_16x16x32_bf16 v[108:111], v[32:35], v[214:217], v[108:111]
	v_mfma_f32_16x16x32_bf16 v[104:107], v[144:147], v[214:217], v[104:107]
	v_mfma_f32_16x16x32_bf16 v[92:95], v[32:35], v[222:225], v[92:95]
	v_mfma_f32_16x16x32_bf16 v[88:91], v[144:147], v[222:225], v[88:91]
	s_barrier
	s_add_i32 s96, s6, s9
	v_add_u32_e32 v14, s8, v155
	v_lshl_add_u64 v[204:205], s[20:21], 0, v[166:167]
	s_mov_b32 m0, s96
	ds_read_b128 v[226:229], v14
	ds_read_b128 v[230:233], v14 offset:1024
	ds_read_b128 v[234:237], v14 offset:2048
	ds_read_b128 v[238:241], v14 offset:3072
	global_load_lds_dwordx4 v[204:205], off
	s_add_i32 m0, s96, 0x2000
	v_lshl_add_u64 v[242:243], s[20:21], 0, v[170:171]
	global_load_lds_dwordx4 v[242:243], off
	s_barrier
	s_waitcnt lgkmcnt(0)
	v_mfma_f32_16x16x32_bf16 v[132:135], v[226:229], v[148:151], v[132:135]
	v_mfma_f32_16x16x32_bf16 v[128:131], v[234:237], v[148:151], v[128:131]
	v_mfma_f32_16x16x32_bf16 v[116:119], v[226:229], v[196:199], v[116:119]
	v_mfma_f32_16x16x32_bf16 v[112:115], v[234:237], v[196:199], v[112:115]
	v_mfma_f32_16x16x32_bf16 v[100:103], v[226:229], v[210:213], v[100:103]
	v_mfma_f32_16x16x32_bf16 v[96:99], v[234:237], v[210:213], v[96:99]
	v_mfma_f32_16x16x32_bf16 v[84:87], v[226:229], v[218:221], v[84:87]
	v_mfma_f32_16x16x32_bf16 v[80:83], v[234:237], v[218:221], v[80:83]
	v_mfma_f32_16x16x32_bf16 v[132:135], v[230:233], v[192:195], v[132:135]
	v_mfma_f32_16x16x32_bf16 v[128:131], v[238:241], v[192:195], v[128:131]
	v_mfma_f32_16x16x32_bf16 v[116:119], v[230:233], v[200:203], v[116:119]
	v_mfma_f32_16x16x32_bf16 v[112:115], v[238:241], v[200:203], v[112:115]
	v_mfma_f32_16x16x32_bf16 v[100:103], v[230:233], v[214:217], v[100:103]
	v_mfma_f32_16x16x32_bf16 v[96:99], v[238:241], v[214:217], v[96:99]
	v_mfma_f32_16x16x32_bf16 v[84:87], v[230:233], v[222:225], v[84:87]
	v_mfma_f32_16x16x32_bf16 v[80:83], v[238:241], v[222:225], v[80:83]
	s_mov_b32 m0, s25
	v_lshl_add_u64 v[244:245], s[22:23], 0, v[164:165]
	s_barrier
	ds_read_b128 v[148:151], v163 offset:16384
	ds_read_b128 v[192:195], v163 offset:17408
	ds_read_b128 v[196:199], v163 offset:18432
	ds_read_b128 v[200:203], v163 offset:19456
	ds_read_b128 v[210:213], v163 offset:20480
	ds_read_b128 v[214:217], v163 offset:21504
	ds_read_b128 v[218:221], v163 offset:22528
	ds_read_b128 v[222:225], v163 offset:23552
	global_load_lds_dwordx4 v[244:245], off
	s_mov_b32 m0, s26
	v_lshl_add_u64 v[246:247], s[22:23], 0, v[168:169]
	global_load_lds_dwordx4 v[246:247], off
	s_barrier
	s_waitcnt lgkmcnt(0)
	v_mfma_f32_16x16x32_bf16 v[76:79], v[24:27], v[148:151], v[76:79]
	v_mfma_f32_16x16x32_bf16 v[72:75], v[36:39], v[148:151], v[72:75]
	v_mfma_f32_16x16x32_bf16 v[60:63], v[24:27], v[196:199], v[60:63]
	v_mfma_f32_16x16x32_bf16 v[56:59], v[36:39], v[196:199], v[56:59]
	v_mfma_f32_16x16x32_bf16 v[44:47], v[24:27], v[210:213], v[44:47]
	v_mfma_f32_16x16x32_bf16 v[40:43], v[36:39], v[210:213], v[40:43]
	v_mfma_f32_16x16x32_bf16 v[14:17], v[24:27], v[218:221], v[16:19]
	v_mfma_f32_16x16x32_bf16 v[8:11], v[36:39], v[218:221], v[8:11]
	v_mfma_f32_16x16x32_bf16 v[76:79], v[32:35], v[192:195], v[76:79]
	v_mfma_f32_16x16x32_bf16 v[72:75], v[144:147], v[192:195], v[72:75]
	v_mfma_f32_16x16x32_bf16 v[60:63], v[32:35], v[200:203], v[60:63]
	v_mfma_f32_16x16x32_bf16 v[56:59], v[144:147], v[200:203], v[56:59]
	v_mfma_f32_16x16x32_bf16 v[44:47], v[32:35], v[214:217], v[44:47]
	v_mfma_f32_16x16x32_bf16 v[40:43], v[144:147], v[214:217], v[40:43]
	v_mfma_f32_16x16x32_bf16 v[14:17], v[32:35], v[222:225], v[14:17]
	v_mfma_f32_16x16x32_bf16 v[8:11], v[144:147], v[222:225], v[8:11]
	s_barrier
; #define PG8_STAGE(bufoff, gbase, voff) do { _Pragma("unroll") for (int _i = 0; _i < 2; ++_i) \
;         __builtin_amdgcn_global_load_lds((const unsigned*)((const char*)(gbase) + (voff)[_i]), (PG8_LAS unsigned*)(lds + (bufoff) + ldsw + _i * 8192), 16, 0, 0); } while (0)
; #define PG8_LDA(dst, b, h) do { _Pragma("unroll") for (int m = 0; m < 4; ++m) _Pragma("unroll") for (int k = 0; k < 2; ++k) dst[m][k] = *(const PG8_LAS bf16x8*)(lds + PG8_SA(b, h) + aoff + m * 2048 + k * 1024); } while (0)
; #define PG8_LDB(dst, b, h) do { _Pragma("unroll") for (int n = 0; n < 2; ++n) _Pragma("unroll") for (int k = 0; k < 2; ++k) dst[n][k] = *(const PG8_LAS bf16x8*)(lds + PG8_SB(b, h) + boff + n * 2048 + k * 1024); } while (0)
; #define PG8_MMA(ai, bj, At, Bt) do { __builtin_amdgcn_s_setprio(1); _Pragma("unroll") for (int m = 0; m < 4; ++m) _Pragma("unroll") for (int n = 0; n < 2; ++n) _Pragma("unroll") for (int k = 0; k < 2; ++k) \
;         acc[ai][bj][m][n] = __builtin_amdgcn_mfma_f32_16x16x32_bf16(Bt[n][k], At[m][k], acc[ai][bj][m][n], 0, 0, 0); __builtin_amdgcn_s_setprio(0); } while (0)
; #define PG8_WAIT_V(n) asm volatile("s_waitcnt vmcnt(" #n ")" ::: "memory")
; #define PG8_WAIT_L(n) asm volatile("s_waitcnt lgkmcnt(" #n ")" ::: "memory")
; #define PG8_BAR __builtin_amdgcn_s_barrier()
; #define PG8_SCHED __builtin_amdgcn_sched_barrier(0)
; template <class Epi, class Sched>
; __device__ __forceinline__ void gemm_phase(PG8_LAS unsigned char* lds, const Gemm g, const Sched& S, const Epi& E) {
;     ...
;             PG8_STAGE(PG8_SB(0, 1), b2 + hstep, voffB);
;             PG8_WAIT_V(6); PG8_BAR; PG8_MMA(1, 1, At, B1); PG8_BAR;
;             PG8_LDB(B0, 1, 0); PG8_SCHED; PG8_LDA(At, 1, 0); PG8_STAGE(PG8_SA(0, 1), a2 + hstep, voffA);
;             PG8_WAIT_L(8); PG8_BAR; PG8_WAIT_L(0); PG8_MMA(0, 0, At, B0); PG8_BAR; PG8_SCHED;
	s_add_u32 s96, s20, 0x40000
	s_addc_u32 s97, s21, 0
	s_add_i32 s30, s8, s9
	s_mov_b32 m0, s30
	v_lshl_add_u64 v[18:19], s[96:97], 0, v[166:167]
	global_load_lds_dwordx4 v[18:19], off
	s_add_i32 m0, s30, 0x2000
	v_lshl_add_u64 v[18:19], s[96:97], 0, v[170:171]
	global_load_lds_dwordx4 v[18:19], off
	s_waitcnt vmcnt(6)
	s_barrier
	v_mfma_f32_16x16x32_bf16 v[48:51], v[234:237], v[196:199], v[48:51]
	v_mfma_f32_16x16x32_bf16 v[28:31], v[226:229], v[210:213], v[28:31]
	v_mfma_f32_16x16x32_bf16 v[18:21], v[234:237], v[210:213], v[20:23]
	v_mfma_f32_16x16x32_bf16 v[4:7], v[226:229], v[218:221], v[4:7]
	v_mfma_f32_16x16x32_bf16 v[0:3], v[234:237], v[218:221], v[0:3]
	v_mfma_f32_16x16x32_bf16 v[24:27], v[226:229], v[148:151], v[68:71]
	v_mfma_f32_16x16x32_bf16 v[32:35], v[234:237], v[148:151], v[64:67]
	v_mfma_f32_16x16x32_bf16 v[36:39], v[226:229], v[196:199], v[52:55]
	v_mfma_f32_16x16x32_bf16 v[48:51], v[238:241], v[200:203], v[48:51]
	v_mfma_f32_16x16x32_bf16 v[28:31], v[230:233], v[214:217], v[28:31]
	v_mfma_f32_16x16x32_bf16 v[20:23], v[238:241], v[214:217], v[18:21]
	v_mfma_f32_16x16x32_bf16 v[4:7], v[230:233], v[222:225], v[4:7]
	v_mfma_f32_16x16x32_bf16 v[0:3], v[238:241], v[222:225], v[0:3]
	v_mfma_f32_16x16x32_bf16 v[24:27], v[230:233], v[192:195], v[24:27]
	v_mfma_f32_16x16x32_bf16 v[32:35], v[238:241], v[192:195], v[32:35]
	v_mfma_f32_16x16x32_bf16 v[36:39], v[230:233], v[200:203], v[36:39]
	s_add_i32 s30, 0, 0x18000
	v_add_u32_e32 v18, s30, v155
	s_barrier
	ds_read_b128 v[52:55], v18
	ds_read_b128 v[64:67], v18 offset:1024
	ds_read_b128 v[68:71], v18 offset:2048
	ds_read_b128 v[144:147], v18 offset:3072
	s_add_u32 s22, s22, 0x40000
	s_addc_u32 s23, s23, 0
	s_mov_b32 m0, s27
	v_lshl_add_u64 v[18:19], s[22:23], 0, v[164:165]
	ds_read_b128 v[148:151], v163 offset:32768
	ds_read_b128 v[192:195], v163 offset:33792
	ds_read_b128 v[196:199], v163 offset:34816
	ds_read_b128 v[200:203], v163 offset:35840
	ds_read_b128 v[210:213], v163 offset:36864
	ds_read_b128 v[214:217], v163 offset:37888
	ds_read_b128 v[218:221], v163 offset:38912
	ds_read_b128 v[222:225], v163 offset:39936
	global_load_lds_dwordx4 v[18:19], off
	s_mov_b32 m0, s31
	v_lshl_add_u64 v[18:19], s[22:23], 0, v[168:169]
	global_load_lds_dwordx4 v[18:19], off
	s_waitcnt lgkmcnt(8)
	s_barrier
	s_waitcnt lgkmcnt(0)
	v_mfma_f32_16x16x32_bf16 v[140:143], v[52:55], v[148:151], v[140:143]
	v_mfma_f32_16x16x32_bf16 v[136:139], v[68:71], v[148:151], v[136:139]
	v_mfma_f32_16x16x32_bf16 v[124:127], v[52:55], v[196:199], v[124:127]
	v_mfma_f32_16x16x32_bf16 v[120:123], v[68:71], v[196:199], v[120:123]
	v_mfma_f32_16x16x32_bf16 v[108:111], v[52:55], v[210:213], v[108:111]
	v_mfma_f32_16x16x32_bf16 v[104:107], v[68:71], v[210:213], v[104:107]
	v_mfma_f32_16x16x32_bf16 v[92:95], v[52:55], v[218:221], v[92:95]
	v_mfma_f32_16x16x32_bf16 v[88:91], v[68:71], v[218:221], v[88:91]
	v_mfma_f32_16x16x32_bf16 v[140:143], v[64:67], v[192:195], v[140:143]
	v_mfma_f32_16x16x32_bf16 v[136:139], v[144:147], v[192:195], v[136:139]
	v_mfma_f32_16x16x32_bf16 v[124:127], v[64:67], v[200:203], v[124:127]
	v_mfma_f32_16x16x32_bf16 v[120:123], v[144:147], v[200:203], v[120:123]
	v_mfma_f32_16x16x32_bf16 v[108:111], v[64:67], v[214:217], v[108:111]
	v_mfma_f32_16x16x32_bf16 v[104:107], v[144:147], v[214:217], v[104:107]
	v_mfma_f32_16x16x32_bf16 v[92:95], v[64:67], v[222:225], v[92:95]
	v_mfma_f32_16x16x32_bf16 v[88:91], v[144:147], v[222:225], v[88:91]
	s_barrier
	s_add_i32 s22, 0, 0x1c000
	v_add_u32_e32 v18, s22, v155
	s_add_i32 s23, s30, s9
	ds_read_b128 v[226:229], v18
	ds_read_b128 v[230:233], v18 offset:1024
	ds_read_b128 v[234:237], v18 offset:2048
	ds_read_b128 v[238:241], v18 offset:3072
	s_mov_b32 m0, s23
	v_lshl_add_u64 v[18:19], v[204:205], 0, s[4:5]
	global_load_lds_dwordx4 v[18:19], off
	s_add_i32 m0, s23, 0x2000
	v_lshl_add_u64 v[18:19], v[242:243], 0, s[4:5]
	global_load_lds_dwordx4 v[18:19], off
	s_barrier
; #define PG8_STAGE(bufoff, gbase, voff) do { _Pragma("unroll") for (int _i = 0; _i < 2; ++_i) \
;         __builtin_amdgcn_global_load_lds((const unsigned*)((const char*)(gbase) + (voff)[_i]), (PG8_LAS unsigned*)(lds + (bufoff) + ldsw + _i * 8192), 16, 0, 0); } while (0)
; #define PG8_LDA(dst, b, h) do { _Pragma("unroll") for (int m = 0; m < 4; ++m) _Pragma("unroll") for (int k = 0; k < 2; ++k) dst[m][k] = *(const PG8_LAS bf16x8*)(lds + PG8_SA(b, h) + aoff + m * 2048 + k * 1024); } while (0)
; #define PG8_LDB(dst, b, h) do { _Pragma("unroll") for (int n = 0; n < 2; ++n) _Pragma("unroll") for (int k = 0; k < 2; ++k) dst[n][k] = *(const PG8_LAS bf16x8*)(lds + PG8_SB(b, h) + boff + n * 2048 + k * 1024); } while (0)
; #define PG8_MMA(ai, bj, At, Bt) do { __builtin_amdgcn_s_setprio(1); _Pragma("unroll") for (int m = 0; m < 4; ++m) _Pragma("unroll") for (int n = 0; n < 2; ++n) _Pragma("unroll") for (int k = 0; k < 2; ++k) \
;         acc[ai][bj][m][n] = __builtin_amdgcn_mfma_f32_16x16x32_bf16(Bt[n][k], At[m][k], acc[ai][bj][m][n], 0, 0, 0); __builtin_amdgcn_s_setprio(0); } while (0)
; #define PG8_WAIT_V(n) asm volatile("s_waitcnt vmcnt(" #n ")" ::: "memory")
; #define PG8_WAIT_L(n) asm volatile("s_waitcnt lgkmcnt(" #n ")" ::: "memory")
; #define PG8_BAR __builtin_amdgcn_s_barrier()
; #define PG8_SCHED __builtin_amdgcn_sched_barrier(0)
; template <class Epi, class Sched>
; __device__ __forceinline__ void gemm_phase(PG8_LAS unsigned char* lds, const Gemm g, const Sched& S, const Epi& E) {
;     ...
;             PG8_LDB(B1, 1, 1); PG8_STAGE(PG8_SB(1, 0), b3, voffB);
;             PG8_BAR; PG8_WAIT_L(0); PG8_MMA(0, 1, At, B1); PG8_BAR;
;             PG8_LDA(At, 1, 1); PG8_STAGE(PG8_SA(1, 0), a3, voffA);
;             PG8_BAR; PG8_WAIT_L(0); PG8_MMA(1, 0, At, B0); PG8_BAR; PG8_SCHED;
;             PG8_STAGE(PG8_SB(1, 1), b3 + hstep, voffB);
;             PG8_WAIT_V(6); PG8_BAR; PG8_MMA(1, 1, At, B1); PG8_BAR;
;         }
	s_waitcnt lgkmcnt(0)
	v_mfma_f32_16x16x32_bf16 v[132:135], v[226:229], v[148:151], v[132:135]
	v_mfma_f32_16x16x32_bf16 v[128:131], v[234:237], v[148:151], v[128:131]
	v_mfma_f32_16x16x32_bf16 v[116:119], v[226:229], v[196:199], v[116:119]
	v_mfma_f32_16x16x32_bf16 v[112:115], v[234:237], v[196:199], v[112:115]
	v_mfma_f32_16x16x32_bf16 v[100:103], v[226:229], v[210:213], v[100:103]
	v_mfma_f32_16x16x32_bf16 v[96:99], v[234:237], v[210:213], v[96:99]
	v_mfma_f32_16x16x32_bf16 v[84:87], v[226:229], v[218:221], v[84:87]
	v_mfma_f32_16x16x32_bf16 v[80:83], v[234:237], v[218:221], v[80:83]
	v_mfma_f32_16x16x32_bf16 v[132:135], v[230:233], v[192:195], v[132:135]
	v_mfma_f32_16x16x32_bf16 v[128:131], v[238:241], v[192:195], v[128:131]
	v_mfma_f32_16x16x32_bf16 v[116:119], v[230:233], v[200:203], v[116:119]
	v_mfma_f32_16x16x32_bf16 v[112:115], v[238:241], v[200:203], v[112:115]
	v_mfma_f32_16x16x32_bf16 v[100:103], v[230:233], v[214:217], v[100:103]
	v_mfma_f32_16x16x32_bf16 v[96:99], v[238:241], v[214:217], v[96:99]
	v_mfma_f32_16x16x32_bf16 v[84:87], v[230:233], v[222:225], v[84:87]
	v_mfma_f32_16x16x32_bf16 v[80:83], v[238:241], v[222:225], v[80:83]
	s_mov_b32 m0, s33
	v_lshl_add_u64 v[18:19], v[244:245], 0, s[4:5]
	s_barrier
	ds_read_b128 v[148:151], v163 offset:49152
	ds_read_b128 v[192:195], v163 offset:50176
	ds_read_b128 v[196:199], v163 offset:51200
	ds_read_b128 v[200:203], v163 offset:52224
	ds_read_b128 v[210:213], v163 offset:53248
	ds_read_b128 v[214:217], v163 offset:54272
	ds_read_b128 v[218:221], v163 offset:55296
	ds_read_b128 v[222:225], v163 offset:56320
	global_load_lds_dwordx4 v[18:19], off
	s_mov_b32 m0, s7
	v_lshl_add_u64 v[18:19], v[246:247], 0, s[4:5]
	global_load_lds_dwordx4 v[18:19], off
	s_barrier
	s_waitcnt lgkmcnt(0)
	v_mfma_f32_16x16x32_bf16 v[76:79], v[52:55], v[148:151], v[76:79]
	v_mfma_f32_16x16x32_bf16 v[72:75], v[68:71], v[148:151], v[72:75]
	v_mfma_f32_16x16x32_bf16 v[60:63], v[52:55], v[196:199], v[60:63]
	v_mfma_f32_16x16x32_bf16 v[56:59], v[68:71], v[196:199], v[56:59]
	v_mfma_f32_16x16x32_bf16 v[44:47], v[52:55], v[210:213], v[44:47]
	v_mfma_f32_16x16x32_bf16 v[40:43], v[68:71], v[210:213], v[40:43]
	v_mfma_f32_16x16x32_bf16 v[14:17], v[52:55], v[218:221], v[14:17]
	v_mfma_f32_16x16x32_bf16 v[8:11], v[68:71], v[218:221], v[8:11]
	v_mfma_f32_16x16x32_bf16 v[76:79], v[64:67], v[192:195], v[76:79]
	v_mfma_f32_16x16x32_bf16 v[72:75], v[144:147], v[192:195], v[72:75]
	v_mfma_f32_16x16x32_bf16 v[60:63], v[64:67], v[200:203], v[60:63]
	v_mfma_f32_16x16x32_bf16 v[56:59], v[144:147], v[200:203], v[56:59]
	v_mfma_f32_16x16x32_bf16 v[44:47], v[64:67], v[214:217], v[44:47]
	v_mfma_f32_16x16x32_bf16 v[40:43], v[144:147], v[214:217], v[40:43]
	v_mfma_f32_16x16x32_bf16 v[16:19], v[64:67], v[222:225], v[14:17]
	v_mfma_f32_16x16x32_bf16 v[8:11], v[144:147], v[222:225], v[8:11]
	s_barrier
	s_add_u32 s20, s20, 0x40080
	s_addc_u32 s21, s21, 0
	s_add_i32 s22, s22, s9
	s_mov_b32 m0, s22
	v_lshl_add_u64 v[14:15], s[20:21], 0, v[166:167]
	global_load_lds_dwordx4 v[14:15], off
	s_add_i32 m0, s22, 0x2000
	v_lshl_add_u64 v[14:15], s[20:21], 0, v[170:171]
	global_load_lds_dwordx4 v[14:15], off
	s_waitcnt vmcnt(6)
	s_barrier
	v_mfma_f32_16x16x32_bf16 v[24:27], v[226:229], v[148:151], v[24:27]
	v_mfma_f32_16x16x32_bf16 v[68:71], v[230:233], v[192:195], v[24:27]
	v_mfma_f32_16x16x32_bf16 v[24:27], v[234:237], v[148:151], v[32:35]
	v_mfma_f32_16x16x32_bf16 v[64:67], v[238:241], v[192:195], v[24:27]
	v_mfma_f32_16x16x32_bf16 v[24:27], v[226:229], v[196:199], v[36:39]
	v_mfma_f32_16x16x32_bf16 v[52:55], v[230:233], v[200:203], v[24:27]
	v_mfma_f32_16x16x32_bf16 v[24:27], v[234:237], v[196:199], v[48:51]
	v_mfma_f32_16x16x32_bf16 v[48:51], v[238:241], v[200:203], v[24:27]
	v_mfma_f32_16x16x32_bf16 v[24:27], v[226:229], v[210:213], v[28:31]
	v_mfma_f32_16x16x32_bf16 v[20:23], v[234:237], v[210:213], v[20:23]
	v_mfma_f32_16x16x32_bf16 v[4:7], v[226:229], v[218:221], v[4:7]
	v_mfma_f32_16x16x32_bf16 v[0:3], v[234:237], v[218:221], v[0:3]
	v_mfma_f32_16x16x32_bf16 v[28:31], v[230:233], v[214:217], v[24:27]
	v_mfma_f32_16x16x32_bf16 v[20:23], v[238:241], v[214:217], v[20:23]
	v_mfma_f32_16x16x32_bf16 v[4:7], v[230:233], v[222:225], v[4:7]
	v_mfma_f32_16x16x32_bf16 v[0:3], v[238:241], v[222:225], v[0:3]
	s_add_i32 s3, s3, 2
	s_add_u32 s0, s0, 0x100
	s_addc_u32 s1, s1, 0
	s_add_u32 vcc_hi, vcc_hi, 0x100
	s_addc_u32 s2, s2, 0
	s_cmp_lt_u32 s3, 14
	s_barrier
	s_cbranch_scc0 .LBB0_197

; #define PG8_STAGE(bufoff, gbase, voff) do { _Pragma("unroll") for (int _i = 0; _i < 2; ++_i) \
;         __builtin_amdgcn_global_load_lds((const unsigned*)((const char*)(gbase) + (voff)[_i]), (PG8_LAS unsigned*)(lds + (bufoff) + ldsw + _i * 8192), 16, 0, 0); } while (0)
; #define PG8_LDA(dst, b, h) do { _Pragma("unroll") for (int m = 0; m < 4; ++m) _Pragma("unroll") for (int k = 0; k < 2; ++k) dst[m][k] = *(const PG8_LAS bf16x8*)(lds + PG8_SA(b, h) + aoff + m * 2048 + k * 1024); } while (0)
; #define PG8_LDB(dst, b, h) do { _Pragma("unroll") for (int n = 0; n < 2; ++n) _Pragma("unroll") for (int k = 0; k < 2; ++k) dst[n][k] = *(const PG8_LAS bf16x8*)(lds + PG8_SB(b, h) + boff + n * 2048 + k * 1024); } while (0)
; #define PG8_MMA(ai, bj, At, Bt) do { __builtin_amdgcn_s_setprio(1); _Pragma("unroll") for (int m = 0; m < 4; ++m) _Pragma("unroll") for (int n = 0; n < 2; ++n) _Pragma("unroll") for (int k = 0; k < 2; ++k) \
;         acc[ai][bj][m][n] = __builtin_amdgcn_mfma_f32_16x16x32_bf16(Bt[n][k], At[m][k], acc[ai][bj][m][n], 0, 0, 0); __builtin_amdgcn_s_setprio(0); } while (0)
; #define PG8_WAIT_L(n) asm volatile("s_waitcnt lgkmcnt(" #n ")" ::: "memory")
; #define PG8_BAR __builtin_amdgcn_s_barrier()
; #define PG8_SCHED __builtin_amdgcn_sched_barrier(0)
; template <class Epi, class Sched>
; __device__ __forceinline__ void gemm_phase(PG8_LAS unsigned char* lds, const Gemm g, const Sched& S, const Epi& E) {
;     ...
;             PG8_LDB(B0, 0, 0); PG8_SCHED; PG8_LDA(At, 0, 0); PG8_STAGE(PG8_SA(1, 1), a1 + hstep, voffA);
;             PG8_WAIT_L(8); PG8_BAR; PG8_WAIT_L(0); PG8_MMA(0, 0, At, B0); PG8_BAR; PG8_SCHED;
;             PG8_LDB(B1, 0, 1); PG8_STAGE(PG8_SB(0, 0), b2, voffB);
;             PG8_BAR; PG8_WAIT_L(0); PG8_MMA(0, 1, At, B1); PG8_BAR;
;             PG8_LDA(At, 0, 1); PG8_STAGE(PG8_SA(0, 0), a2, voffA);
;             PG8_BAR; PG8_WAIT_L(0); PG8_MMA(1, 0, At, B0); PG8_BAR; PG8_SCHED;
.LBB0_1191:
	ds_read_b128 v[128:131], v163
	ds_read_b128 v[132:135], v163 offset:1024
	ds_read_b128 v[136:139], v163 offset:2048
	ds_read_b128 v[168:171], v163 offset:3072
	s_add_u32 s16, s14, 0xfffe0080
	s_addc_u32 s17, s15, -1
	s_cmp_eq_u32 s41, 4
	s_cselect_b32 s19, s7, s17
	s_cselect_b32 s18, s37, s16
	s_cselect_b32 s17, s5, s40
	s_cselect_b32 s16, s38, s39
	v_lshl_add_u64 v[206:207], s[14:15], 0, v[148:149]
	s_add_i32 m0, s13, 0xc000
	ds_read_b128 v[172:175], v176
	ds_read_b128 v[178:181], v176 offset:1024
	ds_read_b128 v[182:185], v176 offset:2048
	ds_read_b128 v[186:189], v176 offset:3072
	ds_read_b128 v[190:193], v176 offset:4096
	ds_read_b128 v[194:197], v176 offset:5120
	ds_read_b128 v[198:201], v176 offset:6144
	ds_read_b128 v[202:205], v176 offset:7168
	global_load_lds_dwordx4 v[206:207], off
	s_add_i32 m0, s13, 0xe000
	v_lshl_add_u64 v[206:207], s[14:15], 0, v[150:151]
	global_load_lds_dwordx4 v[206:207], off
	s_waitcnt lgkmcnt(8)
	s_barrier
	s_waitcnt lgkmcnt(0)
	v_mfma_f32_16x16x32_bf16 v[124:127], v[128:131], v[172:175], v[124:127]
	v_mfma_f32_16x16x32_bf16 v[120:123], v[136:139], v[172:175], v[120:123]
	v_mfma_f32_16x16x32_bf16 v[108:111], v[128:131], v[182:185], v[108:111]
	v_mfma_f32_16x16x32_bf16 v[104:107], v[136:139], v[182:185], v[104:107]
	v_mfma_f32_16x16x32_bf16 v[92:95], v[128:131], v[190:193], v[92:95]
	v_mfma_f32_16x16x32_bf16 v[88:91], v[136:139], v[190:193], v[88:91]
	v_mfma_f32_16x16x32_bf16 v[76:79], v[128:131], v[198:201], v[76:79]
	v_mfma_f32_16x16x32_bf16 v[72:75], v[136:139], v[198:201], v[72:75]
	v_mfma_f32_16x16x32_bf16 v[124:127], v[132:135], v[178:181], v[124:127]
	v_mfma_f32_16x16x32_bf16 v[120:123], v[168:171], v[178:181], v[120:123]
	v_mfma_f32_16x16x32_bf16 v[108:111], v[132:135], v[186:189], v[108:111]
	v_mfma_f32_16x16x32_bf16 v[104:107], v[168:171], v[186:189], v[104:107]
	v_mfma_f32_16x16x32_bf16 v[92:95], v[132:135], v[194:197], v[92:95]
	v_mfma_f32_16x16x32_bf16 v[88:91], v[168:171], v[194:197], v[88:91]
	v_mfma_f32_16x16x32_bf16 v[76:79], v[132:135], v[202:205], v[76:79]
	v_mfma_f32_16x16x32_bf16 v[72:75], v[168:171], v[202:205], v[72:75]
	s_barrier
	s_add_i32 s30, s34, s22
	v_lshl_add_u64 v[222:223], s[16:17], 0, v[142:143]
	s_mov_b32 m0, s30
	ds_read_b128 v[206:209], v177
	ds_read_b128 v[210:213], v177 offset:1024
	ds_read_b128 v[214:217], v177 offset:2048
	ds_read_b128 v[218:221], v177 offset:3072
	global_load_lds_dwordx4 v[222:223], off
	s_add_i32 m0, s30, 0x2000
	v_lshl_add_u64 v[224:225], s[16:17], 0, v[146:147]
	global_load_lds_dwordx4 v[224:225], off
	s_barrier
	s_waitcnt lgkmcnt(0)
	v_mfma_f32_16x16x32_bf16 v[116:119], v[206:209], v[172:175], v[116:119]
	v_mfma_f32_16x16x32_bf16 v[112:115], v[214:217], v[172:175], v[112:115]
	v_mfma_f32_16x16x32_bf16 v[100:103], v[206:209], v[182:185], v[100:103]
	v_mfma_f32_16x16x32_bf16 v[96:99], v[214:217], v[182:185], v[96:99]
	v_mfma_f32_16x16x32_bf16 v[84:87], v[206:209], v[190:193], v[84:87]
	v_mfma_f32_16x16x32_bf16 v[80:83], v[214:217], v[190:193], v[80:83]
	v_mfma_f32_16x16x32_bf16 v[68:71], v[206:209], v[198:201], v[68:71]
	v_mfma_f32_16x16x32_bf16 v[64:67], v[214:217], v[198:201], v[64:67]
	v_mfma_f32_16x16x32_bf16 v[116:119], v[210:213], v[178:181], v[116:119]
	v_mfma_f32_16x16x32_bf16 v[112:115], v[218:221], v[178:181], v[112:115]
	v_mfma_f32_16x16x32_bf16 v[100:103], v[210:213], v[186:189], v[100:103]
	v_mfma_f32_16x16x32_bf16 v[96:99], v[218:221], v[186:189], v[96:99]
	v_mfma_f32_16x16x32_bf16 v[84:87], v[210:213], v[194:197], v[84:87]
	v_mfma_f32_16x16x32_bf16 v[80:83], v[218:221], v[194:197], v[80:83]
	v_mfma_f32_16x16x32_bf16 v[68:71], v[210:213], v[202:205], v[68:71]
	v_mfma_f32_16x16x32_bf16 v[64:67], v[218:221], v[202:205], v[64:67]
	s_mov_b32 m0, s13
	v_lshl_add_u64 v[226:227], s[18:19], 0, v[140:141]
	s_barrier
	ds_read_b128 v[172:175], v176 offset:16384
	ds_read_b128 v[178:181], v176 offset:17408
	ds_read_b128 v[182:185], v176 offset:18432
	ds_read_b128 v[186:189], v176 offset:19456
	ds_read_b128 v[190:193], v176 offset:20480
	ds_read_b128 v[194:197], v176 offset:21504
	ds_read_b128 v[198:201], v176 offset:22528
	ds_read_b128 v[202:205], v176 offset:23552
	global_load_lds_dwordx4 v[226:227], off
	s_mov_b32 m0, s23
	v_lshl_add_u64 v[228:229], s[18:19], 0, v[144:145]
	global_load_lds_dwordx4 v[228:229], off
	s_barrier
	s_waitcnt lgkmcnt(0)
	v_mfma_f32_16x16x32_bf16 v[60:63], v[128:131], v[172:175], v[60:63]
	v_mfma_f32_16x16x32_bf16 v[56:59], v[136:139], v[172:175], v[56:59]
	v_mfma_f32_16x16x32_bf16 v[44:47], v[128:131], v[182:185], v[44:47]
	v_mfma_f32_16x16x32_bf16 v[40:43], v[136:139], v[182:185], v[40:43]
	v_mfma_f32_16x16x32_bf16 v[28:31], v[128:131], v[190:193], v[28:31]
	v_mfma_f32_16x16x32_bf16 v[24:27], v[136:139], v[190:193], v[24:27]
	v_mfma_f32_16x16x32_bf16 v[12:15], v[128:131], v[198:201], v[12:15]
	v_mfma_f32_16x16x32_bf16 v[8:11], v[136:139], v[198:201], v[8:11]
	v_mfma_f32_16x16x32_bf16 v[60:63], v[132:135], v[178:181], v[60:63]
	v_mfma_f32_16x16x32_bf16 v[56:59], v[168:171], v[178:181], v[56:59]
	v_mfma_f32_16x16x32_bf16 v[44:47], v[132:135], v[186:189], v[44:47]
	v_mfma_f32_16x16x32_bf16 v[40:43], v[168:171], v[186:189], v[40:43]
	v_mfma_f32_16x16x32_bf16 v[28:31], v[132:135], v[194:197], v[28:31]
	v_mfma_f32_16x16x32_bf16 v[24:27], v[168:171], v[194:197], v[24:27]
	v_mfma_f32_16x16x32_bf16 v[12:15], v[132:135], v[202:205], v[12:15]
	v_mfma_f32_16x16x32_bf16 v[8:11], v[168:171], v[202:205], v[8:11]
	s_barrier
	s_add_u32 s42, s16, 0x20000
	s_addc_u32 s43, s17, 0
	s_add_i32 s30, s35, s22
	s_mov_b32 m0, s30
	v_lshl_add_u64 v[128:129], s[42:43], 0, v[142:143]
	global_load_lds_dwordx4 v[128:129], off
	s_add_i32 m0, s30, 0x2000
	v_lshl_add_u64 v[128:129], s[42:43], 0, v[146:147]
	global_load_lds_dwordx4 v[128:129], off
	s_waitcnt vmcnt(6)
	s_barrier
; #define PG8_STAGE(bufoff, gbase, voff) do { _Pragma("unroll") for (int _i = 0; _i < 2; ++_i) \
;         __builtin_amdgcn_global_load_lds((const unsigned*)((const char*)(gbase) + (voff)[_i]), (PG8_LAS unsigned*)(lds + (bufoff) + ldsw + _i * 8192), 16, 0, 0); } while (0)
; #define PG8_LDA(dst, b, h) do { _Pragma("unroll") for (int m = 0; m < 4; ++m) _Pragma("unroll") for (int k = 0; k < 2; ++k) dst[m][k] = *(const PG8_LAS bf16x8*)(lds + PG8_SA(b, h) + aoff + m * 2048 + k * 1024); } while (0)
; #define PG8_LDB(dst, b, h) do { _Pragma("unroll") for (int n = 0; n < 2; ++n) _Pragma("unroll") for (int k = 0; k < 2; ++k) dst[n][k] = *(const PG8_LAS bf16x8*)(lds + PG8_SB(b, h) + boff + n * 2048 + k * 1024); } while (0)
; #define PG8_MMA(ai, bj, At, Bt) do { __builtin_amdgcn_s_setprio(1); _Pragma("unroll") for (int m = 0; m < 4; ++m) _Pragma("unroll") for (int n = 0; n < 2; ++n) _Pragma("unroll") for (int k = 0; k < 2; ++k) \
;         acc[ai][bj][m][n] = __builtin_amdgcn_mfma_f32_16x16x32_bf16(Bt[n][k], At[m][k], acc[ai][bj][m][n], 0, 0, 0); __builtin_amdgcn_s_setprio(0); } while (0)
; #define PG8_WAIT_V(n) asm volatile("s_waitcnt vmcnt(" #n ")" ::: "memory")
; #define PG8_WAIT_L(n) asm volatile("s_waitcnt lgkmcnt(" #n ")" ::: "memory")
; #define PG8_BAR __builtin_amdgcn_s_barrier()
; #define PG8_SCHED __builtin_amdgcn_sched_barrier(0)
; template <class Epi, class Sched>
; __device__ __forceinline__ void gemm_phase(PG8_LAS unsigned char* lds, const Gemm g, const Sched& S, const Epi& E) {
;     ...
;             PG8_STAGE(PG8_SB(0, 1), b2 + hstep, voffB);
;             PG8_WAIT_V(6); PG8_BAR; PG8_MMA(1, 1, At, B1); PG8_BAR;
;             PG8_LDB(B0, 1, 0); PG8_SCHED; PG8_LDA(At, 1, 0); PG8_STAGE(PG8_SA(0, 1), a2 + hstep, voffA);
;             PG8_WAIT_L(8); PG8_BAR; PG8_WAIT_L(0); PG8_MMA(0, 0, At, B0); PG8_BAR; PG8_SCHED;
;             PG8_LDB(B1, 1, 1); PG8_STAGE(PG8_SB(1, 0), b3, voffB);
;             PG8_BAR; PG8_WAIT_L(0); PG8_MMA(0, 1, At, B1); PG8_BAR;
;             PG8_LDA(At, 1, 1); PG8_STAGE(PG8_SA(1, 0), a3, voffA);
	v_mfma_f32_16x16x32_bf16 v[52:55], v[206:209], v[172:175], v[52:55]
	v_mfma_f32_16x16x32_bf16 v[48:51], v[214:217], v[172:175], v[48:51]
	v_mfma_f32_16x16x32_bf16 v[36:39], v[206:209], v[182:185], v[36:39]
	v_mfma_f32_16x16x32_bf16 v[32:35], v[214:217], v[182:185], v[32:35]
	v_mfma_f32_16x16x32_bf16 v[20:23], v[206:209], v[190:193], v[20:23]
	v_mfma_f32_16x16x32_bf16 v[16:19], v[214:217], v[190:193], v[16:19]
	v_mfma_f32_16x16x32_bf16 v[4:7], v[206:209], v[198:201], v[4:7]
	v_mfma_f32_16x16x32_bf16 v[0:3], v[214:217], v[198:201], v[0:3]
	v_mfma_f32_16x16x32_bf16 v[52:55], v[210:213], v[178:181], v[52:55]
	v_mfma_f32_16x16x32_bf16 v[48:51], v[218:221], v[178:181], v[48:51]
	v_mfma_f32_16x16x32_bf16 v[36:39], v[210:213], v[186:189], v[36:39]
	v_mfma_f32_16x16x32_bf16 v[32:35], v[218:221], v[186:189], v[32:35]
	v_mfma_f32_16x16x32_bf16 v[20:23], v[210:213], v[194:197], v[20:23]
	v_mfma_f32_16x16x32_bf16 v[16:19], v[218:221], v[194:197], v[16:19]
	v_mfma_f32_16x16x32_bf16 v[4:7], v[210:213], v[202:205], v[4:7]
	v_mfma_f32_16x16x32_bf16 v[0:3], v[218:221], v[202:205], v[0:3]
	s_add_i32 s30, 0, 0x18000
	v_add_u32_e32 v168, s30, v159
	s_barrier
	ds_read_b128 v[128:131], v168
	ds_read_b128 v[132:135], v168 offset:1024
	ds_read_b128 v[136:139], v168 offset:2048
	ds_read_b128 v[168:171], v168 offset:3072
	s_add_u32 s18, s18, 0x20000
	s_addc_u32 s19, s19, 0
	s_mov_b32 m0, s24
	v_lshl_add_u64 v[206:207], s[18:19], 0, v[140:141]
	ds_read_b128 v[172:175], v176 offset:32768
	ds_read_b128 v[178:181], v176 offset:33792
	ds_read_b128 v[182:185], v176 offset:34816
	ds_read_b128 v[186:189], v176 offset:35840
	ds_read_b128 v[190:193], v176 offset:36864
	ds_read_b128 v[194:197], v176 offset:37888
	ds_read_b128 v[198:201], v176 offset:38912
	ds_read_b128 v[202:205], v176 offset:39936
	global_load_lds_dwordx4 v[206:207], off
	s_mov_b32 m0, s25
	v_lshl_add_u64 v[206:207], s[18:19], 0, v[144:145]
	global_load_lds_dwordx4 v[206:207], off
	s_waitcnt lgkmcnt(8)
	s_barrier
	s_waitcnt lgkmcnt(0)
	v_mfma_f32_16x16x32_bf16 v[124:127], v[128:131], v[172:175], v[124:127]
	v_mfma_f32_16x16x32_bf16 v[120:123], v[136:139], v[172:175], v[120:123]
	v_mfma_f32_16x16x32_bf16 v[108:111], v[128:131], v[182:185], v[108:111]
	v_mfma_f32_16x16x32_bf16 v[104:107], v[136:139], v[182:185], v[104:107]
	v_mfma_f32_16x16x32_bf16 v[92:95], v[128:131], v[190:193], v[92:95]
	v_mfma_f32_16x16x32_bf16 v[88:91], v[136:139], v[190:193], v[88:91]
	v_mfma_f32_16x16x32_bf16 v[76:79], v[128:131], v[198:201], v[76:79]
	v_mfma_f32_16x16x32_bf16 v[72:75], v[136:139], v[198:201], v[72:75]
	v_mfma_f32_16x16x32_bf16 v[124:127], v[132:135], v[178:181], v[124:127]
	v_mfma_f32_16x16x32_bf16 v[120:123], v[168:171], v[178:181], v[120:123]
	v_mfma_f32_16x16x32_bf16 v[108:111], v[132:135], v[186:189], v[108:111]
	v_mfma_f32_16x16x32_bf16 v[104:107], v[168:171], v[186:189], v[104:107]
	v_mfma_f32_16x16x32_bf16 v[92:95], v[132:135], v[194:197], v[92:95]
	v_mfma_f32_16x16x32_bf16 v[88:91], v[168:171], v[194:197], v[88:91]
	v_mfma_f32_16x16x32_bf16 v[76:79], v[132:135], v[202:205], v[76:79]
	v_mfma_f32_16x16x32_bf16 v[72:75], v[168:171], v[202:205], v[72:75]
	s_barrier
	s_add_i32 s18, 0, 0x1c000
	s_add_i32 s19, s30, s22
	v_add_u32_e32 v218, s18, v159
	v_lshl_add_u64 v[222:223], v[222:223], 0, s[2:3]
	s_mov_b32 m0, s19
	ds_read_b128 v[206:209], v218
	ds_read_b128 v[210:213], v218 offset:1024
	ds_read_b128 v[214:217], v218 offset:2048
	ds_read_b128 v[218:221], v218 offset:3072
	global_load_lds_dwordx4 v[222:223], off
	s_add_i32 m0, s19, 0x2000
	v_lshl_add_u64 v[222:223], v[224:225], 0, s[2:3]
	global_load_lds_dwordx4 v[222:223], off
	s_barrier
	s_waitcnt lgkmcnt(0)
	v_mfma_f32_16x16x32_bf16 v[116:119], v[206:209], v[172:175], v[116:119]
	v_mfma_f32_16x16x32_bf16 v[112:115], v[214:217], v[172:175], v[112:115]
	v_mfma_f32_16x16x32_bf16 v[100:103], v[206:209], v[182:185], v[100:103]
	v_mfma_f32_16x16x32_bf16 v[96:99], v[214:217], v[182:185], v[96:99]
	v_mfma_f32_16x16x32_bf16 v[84:87], v[206:209], v[190:193], v[84:87]
	v_mfma_f32_16x16x32_bf16 v[80:83], v[214:217], v[190:193], v[80:83]
	v_mfma_f32_16x16x32_bf16 v[68:71], v[206:209], v[198:201], v[68:71]
	v_mfma_f32_16x16x32_bf16 v[64:67], v[214:217], v[198:201], v[64:67]
	v_mfma_f32_16x16x32_bf16 v[116:119], v[210:213], v[178:181], v[116:119]
	v_mfma_f32_16x16x32_bf16 v[112:115], v[218:221], v[178:181], v[112:115]
	v_mfma_f32_16x16x32_bf16 v[100:103], v[210:213], v[186:189], v[100:103]
	v_mfma_f32_16x16x32_bf16 v[96:99], v[218:221], v[186:189], v[96:99]
	v_mfma_f32_16x16x32_bf16 v[84:87], v[210:213], v[194:197], v[84:87]
	v_mfma_f32_16x16x32_bf16 v[80:83], v[218:221], v[194:197], v[80:83]
	v_mfma_f32_16x16x32_bf16 v[68:71], v[210:213], v[202:205], v[68:71]
	v_mfma_f32_16x16x32_bf16 v[64:67], v[218:221], v[202:205], v[64:67]
	s_mov_b32 m0, s27
	v_lshl_add_u64 v[222:223], v[226:227], 0, s[2:3]
	s_barrier
	ds_read_b128 v[172:175], v176 offset:49152
	ds_read_b128 v[178:181], v176 offset:50176
	ds_read_b128 v[182:185], v176 offset:51200
	ds_read_b128 v[186:189], v176 offset:52224
	ds_read_b128 v[190:193], v176 offset:53248
	ds_read_b128 v[194:197], v176 offset:54272
	ds_read_b128 v[198:201], v176 offset:55296
	ds_read_b128 v[202:205], v176 offset:56320
	global_load_lds_dwordx4 v[222:223], off
	s_mov_b32 m0, s29
	v_lshl_add_u64 v[222:223], v[228:229], 0, s[2:3]
	global_load_lds_dwordx4 v[222:223], off
	s_barrier
; #define PG8_STAGE(bufoff, gbase, voff) do { _Pragma("unroll") for (int _i = 0; _i < 2; ++_i) \
;         __builtin_amdgcn_global_load_lds((const unsigned*)((const char*)(gbase) + (voff)[_i]), (PG8_LAS unsigned*)(lds + (bufoff) + ldsw + _i * 8192), 16, 0, 0); } while (0)
; #define PG8_MMA(ai, bj, At, Bt) do { __builtin_amdgcn_s_setprio(1); _Pragma("unroll") for (int m = 0; m < 4; ++m) _Pragma("unroll") for (int n = 0; n < 2; ++n) _Pragma("unroll") for (int k = 0; k < 2; ++k) \
;         acc[ai][bj][m][n] = __builtin_amdgcn_mfma_f32_16x16x32_bf16(Bt[n][k], At[m][k], acc[ai][bj][m][n], 0, 0, 0); __builtin_amdgcn_s_setprio(0); } while (0)
; #define PG8_WAIT_V(n) asm volatile("s_waitcnt vmcnt(" #n ")" ::: "memory")
; #define PG8_WAIT_L(n) asm volatile("s_waitcnt lgkmcnt(" #n ")" ::: "memory")
; #define PG8_BAR __builtin_amdgcn_s_barrier()
; template <class Epi, class Sched>
; __device__ __forceinline__ void gemm_phase(PG8_LAS unsigned char* lds, const Gemm g, const Sched& S, const Epi& E) {
;     ...
;             PG8_BAR; PG8_WAIT_L(0); PG8_MMA(1, 0, At, B0); PG8_BAR; PG8_SCHED;
;             PG8_STAGE(PG8_SB(1, 1), b3 + hstep, voffB);
;             PG8_WAIT_V(6); PG8_BAR; PG8_MMA(1, 1, At, B1); PG8_BAR;
;     DI void operator()(const f32x4 (&acc)[2][2][4][2], const Unit& u, int wr, int wc, int fr, int fq, const Pre& pre) const {
;         const int cb = u.pn * 256 + wc * 32 + 8 * fq, row0 = u.pm * 256 + wr * 64 + fr;
; #pragma unroll
;         for (int ai = 0; ai < 2; ++ai) {
;             u32x4v y[4][2];
; #pragma unroll
;             for (int m = 0; m < 4; ++m)
; #pragma unroll
;                 for (int bj = 0; bj < 2; ++bj) y[m][bj] = *(const u32x4v*)(YG + (size_t)(row0 + ai * 128 + m * 16) * 512 + cb + bj * 128);
; #pragma unroll
;             for (int m = 0; m < 4; ++m) { const int row = row0 + ai * 128 + m * 16;
; #pragma unroll
;                 for (int bj = 0; bj < 2; ++bj) { const f32x4 v0 = acc[ai][bj][m][0], v1 = acc[ai][bj][m][1]; const u32x4v yy = y[m][bj]; u32x4v o;
;                     o.x = pk2(bflo(yy.x) * sigm(v0[0]), bfhi(yy.x) * sigm(v0[1])); o.y = pk2(bflo(yy.y) * sigm(v0[2]), bfhi(yy.y) * sigm(v0[3]));
;                     o.z = pk2(bflo(yy.z) * sigm(v1[0]), bfhi(yy.z) * sigm(v1[1])); o.w = pk2(bflo(yy.w) * sigm(v1[2]), bfhi(yy.w) * sigm(v1[3]));
;                     *(u32x4v*)(CAT + (size_t)row * 1024 + 512 + cb + bj * 128) = o; } } }
	s_waitcnt lgkmcnt(0)
	v_mfma_f32_16x16x32_bf16 v[60:63], v[128:131], v[172:175], v[60:63]
	v_mfma_f32_16x16x32_bf16 v[56:59], v[136:139], v[172:175], v[56:59]
	v_mfma_f32_16x16x32_bf16 v[44:47], v[128:131], v[182:185], v[44:47]
	v_mfma_f32_16x16x32_bf16 v[40:43], v[136:139], v[182:185], v[40:43]
	v_mfma_f32_16x16x32_bf16 v[28:31], v[128:131], v[190:193], v[28:31]
	v_mfma_f32_16x16x32_bf16 v[24:27], v[136:139], v[190:193], v[24:27]
	v_mfma_f32_16x16x32_bf16 v[12:15], v[128:131], v[198:201], v[12:15]
	v_mfma_f32_16x16x32_bf16 v[8:11], v[136:139], v[198:201], v[8:11]
	v_mfma_f32_16x16x32_bf16 v[60:63], v[132:135], v[178:181], v[60:63]
	v_mfma_f32_16x16x32_bf16 v[56:59], v[168:171], v[178:181], v[56:59]
	v_mfma_f32_16x16x32_bf16 v[44:47], v[132:135], v[186:189], v[44:47]
	v_mfma_f32_16x16x32_bf16 v[40:43], v[168:171], v[186:189], v[40:43]
	v_mfma_f32_16x16x32_bf16 v[28:31], v[132:135], v[194:197], v[28:31]
	v_mfma_f32_16x16x32_bf16 v[24:27], v[168:171], v[194:197], v[24:27]
	v_mfma_f32_16x16x32_bf16 v[12:15], v[132:135], v[202:205], v[12:15]
	v_mfma_f32_16x16x32_bf16 v[8:11], v[168:171], v[202:205], v[8:11]
	s_barrier
	s_add_u32 s16, s16, 0x20080
	s_addc_u32 s17, s17, 0
	s_add_i32 s18, s18, s22
	s_mov_b32 m0, s18
	v_lshl_add_u64 v[128:129], s[16:17], 0, v[142:143]
	global_load_lds_dwordx4 v[128:129], off
	s_add_i32 m0, s18, 0x2000
	v_lshl_add_u64 v[128:129], s[16:17], 0, v[146:147]
	global_load_lds_dwordx4 v[128:129], off
	s_waitcnt vmcnt(6)
	s_barrier
	v_mfma_f32_16x16x32_bf16 v[52:55], v[206:209], v[172:175], v[52:55]
	v_mfma_f32_16x16x32_bf16 v[48:51], v[214:217], v[172:175], v[48:51]
	v_mfma_f32_16x16x32_bf16 v[36:39], v[206:209], v[182:185], v[36:39]
	v_mfma_f32_16x16x32_bf16 v[32:35], v[214:217], v[182:185], v[32:35]
	v_mfma_f32_16x16x32_bf16 v[20:23], v[206:209], v[190:193], v[20:23]
	v_mfma_f32_16x16x32_bf16 v[16:19], v[214:217], v[190:193], v[16:19]
	v_mfma_f32_16x16x32_bf16 v[4:7], v[206:209], v[198:201], v[4:7]
	v_mfma_f32_16x16x32_bf16 v[0:3], v[214:217], v[198:201], v[0:3]
	v_mfma_f32_16x16x32_bf16 v[52:55], v[210:213], v[178:181], v[52:55]
	v_mfma_f32_16x16x32_bf16 v[48:51], v[218:221], v[178:181], v[48:51]
	v_mfma_f32_16x16x32_bf16 v[36:39], v[210:213], v[186:189], v[36:39]
	v_mfma_f32_16x16x32_bf16 v[32:35], v[218:221], v[186:189], v[32:35]
	v_mfma_f32_16x16x32_bf16 v[20:23], v[210:213], v[194:197], v[20:23]
	v_mfma_f32_16x16x32_bf16 v[16:19], v[218:221], v[194:197], v[16:19]
	v_mfma_f32_16x16x32_bf16 v[4:7], v[210:213], v[202:205], v[4:7]
	v_mfma_f32_16x16x32_bf16 v[0:3], v[218:221], v[202:205], v[0:3]
	s_add_i32 s41, s41, 2
	s_add_u32 s14, s14, 0x100
	s_addc_u32 s15, s15, 0
	s_add_u32 s39, s39, 0x100
	s_addc_u32 s40, s40, 0
	s_cmp_lt_u32 s41, 6
	s_barrier
	s_cbranch_scc1 .LBB0_1191
	v_lshl_or_b32 v128, s36, 8, v161
	v_lshl_add_u32 v170, s12, 8, v157
	v_ashrrev_i32_e32 v129, 31, v128
	v_readlane_b32 s36, v255, 8
	v_lshlrev_b64 v[168:169], 1, v[128:129]
	v_readlane_b32 s44, v255, 16
	v_readlane_b32 s45, v255, 17
	v_ashrrev_i32_e32 v171, 31, v170
	v_lshlrev_b64 v[128:129], 10, v[170:171]
	v_lshl_add_u64 v[172:173], s[44:45], 0, v[168:169]
	v_lshl_add_u64 v[128:129], v[172:173], 0, v[128:129]
	global_load_dwordx4 v[178:181], v[128:129], off
	global_load_dwordx4 v[182:185], v[128:129], off offset:256
	v_or_b32_e32 v190, 16, v170
	v_or_b32_e32 v174, 32, v170
	v_mul_f32_e32 v124, 0xbfb8aa3b, v124
	v_mul_f32_e32 v125, 0xbfb8aa3b, v125
	v_mul_f32_e32 v120, 0xbfb8aa3b, v120
	v_mul_f32_e32 v121, 0xbfb8aa3b, v121
	v_mul_f32_e32 v122, 0xbfb8aa3b, v122
	v_mul_f32_e32 v123, 0xbfb8aa3b, v123
	v_mul_f32_e32 v128, 0xbfb8aa3b, v116
	v_mul_f32_e32 v117, 0xbfb8aa3b, v117
	v_or_b32_e32 v116, 48, v170
	v_ashrrev_i32_e32 v191, 31, v190
	v_ashrrev_i32_e32 v175, 31, v174
	v_readlane_b32 s46, v255, 18
	v_readlane_b32 s47, v255, 19
	v_mul_f32_e32 v126, 0xbfb8aa3b, v126
	v_mul_f32_e32 v127, 0xbfb8aa3b, v127
	v_exp_f32_e32 v196, v124
	v_exp_f32_e32 v197, v125
	v_exp_f32_e32 v200, v120
	v_exp_f32_e32 v201, v121
	v_exp_f32_e32 v202, v122
	v_exp_f32_e32 v203, v123
	v_exp_f32_e32 v205, v117
	v_ashrrev_i32_e32 v117, 31, v116
	v_lshlrev_b64 v[120:121], 11, v[170:171]
	v_lshlrev_b64 v[122:123], 10, v[190:191]
	v_lshlrev_b64 v[124:125], 10, v[174:175]
	v_exp_f32_e32 v198, v126
	v_exp_f32_e32 v199, v127
	v_lshlrev_b64 v[126:127], 10, v[116:117]
	v_lshl_add_u64 v[120:121], s[46:47], 0, v[120:121]
	v_lshl_add_u64 v[122:123], v[172:173], 0, v[122:123]
	v_lshl_add_u64 v[124:125], v[172:173], 0, v[124:125]
	v_exp_f32_e32 v204, v128
	v_lshl_add_u64 v[192:193], v[172:173], 0, v[126:127]
	v_lshl_add_u64 v[194:195], v[120:121], 0, v[168:169]
	global_load_dwordx4 v[186:189], v[122:123], off
	global_load_dwordx4 v[136:139], v[122:123], off offset:256
	global_load_dwordx4 v[132:135], v[124:125], off
	global_load_dwordx4 v[128:131], v[124:125], off offset:256
	s_nop 0
	global_load_dwordx4 v[124:127], v[192:193], off
	global_load_dwordx4 v[120:123], v[192:193], off offset:256
	v_add_f32_e32 v192, 1.0, v197
	v_add_f32_e32 v171, 1.0, v196
	v_add_f32_e32 v193, 1.0, v198
	v_add_f32_e32 v196, 1.0, v199
	v_add_f32_e32 v197, 1.0, v200
	v_add_f32_e32 v198, 1.0, v201
	v_add_f32_e32 v200, 1.0, v203
	v_rcp_f32_e32 v192, v192
	v_add_f32_e32 v199, 1.0, v202
	v_rcp_f32_e32 v171, v171
	v_rcp_f32_e32 v196, v196
	v_rcp_f32_e32 v198, v198
	v_rcp_f32_e32 v200, v200
	v_rcp_f32_e32 v193, v193
	v_rcp_f32_e32 v197, v197
	v_rcp_f32_e32 v199, v199
	v_mul_f32_e32 v118, 0xbfb8aa3b, v118
	v_add_f32_e32 v201, 1.0, v204
	v_exp_f32_e32 v118, v118
	v_mul_f32_e32 v119, 0xbfb8aa3b, v119
	v_exp_f32_e32 v119, v119
	v_mul_f32_e32 v112, 0xbfb8aa3b, v112
	v_exp_f32_e32 v112, v112
	v_mul_f32_e32 v113, 0xbfb8aa3b, v113
	v_exp_f32_e32 v113, v113
	v_add_f32_e32 v118, 1.0, v118
	v_rcp_f32_e32 v118, v118
	v_add_f32_e32 v119, 1.0, v119
	v_rcp_f32_e32 v119, v119
	v_add_f32_e32 v112, 1.0, v112
	v_rcp_f32_e32 v112, v112
	v_add_f32_e32 v113, 1.0, v113
	v_mul_f32_e32 v114, 0xbfb8aa3b, v114
	v_rcp_f32_e32 v113, v113
	v_exp_f32_e32 v114, v114
	v_mul_f32_e32 v115, 0xbfb8aa3b, v115
	v_exp_f32_e32 v115, v115
	v_mul_f32_e32 v108, 0xbfb8aa3b, v108
	v_exp_f32_e32 v108, v108
	v_mul_f32_e32 v109, 0xbfb8aa3b, v109
	s_waitcnt vmcnt(0)
; DI unsigned pk2(float lo, float hi) { unsigned r; asm volatile("v_cvt_pk_bf16_f32 %0, %1, %2" : "=v"(r) : "v"(lo), "v"(hi)); return r; }
; DI float bflo(unsigned u) { return __uint_as_float(u << 16); }
; DI float bfhi(unsigned u) { return __uint_as_float(u & 0xffff0000u); }
; DI float sigm(float x) { return __builtin_amdgcn_rcpf(1.f + __expf(-x)); }
;     DI void operator()(const f32x4 (&acc)[2][2][4][2], const Unit& u, int wr, int wc, int fr, int fq, const Pre& pre) const {
;     ...
;             for (int m = 0; m < 4; ++m) { const int row = row0 + ai * 128 + m * 16;
; #pragma unroll
;                 for (int bj = 0; bj < 2; ++bj) { const f32x4 v0 = acc[ai][bj][m][0], v1 = acc[ai][bj][m][1]; const u32x4v yy = y[m][bj]; u32x4v o;
;                     o.x = pk2(bflo(yy.x) * sigm(v0[0]), bfhi(yy.x) * sigm(v0[1])); o.y = pk2(bflo(yy.y) * sigm(v0[2]), bfhi(yy.y) * sigm(v0[3]));
;                     o.z = pk2(bflo(yy.z) * sigm(v1[0]), bfhi(yy.z) * sigm(v1[1])); o.w = pk2(bflo(yy.w) * sigm(v1[2]), bfhi(yy.w) * sigm(v1[3]));
;                     *(u32x4v*)(CAT + (size_t)row * 1024 + 512 + cb + bj * 128) = o; } } }
	v_lshlrev_b32_e32 v202, 16, v178
	v_and_b32_e32 v178, 0xffff0000, v178
	v_lshlrev_b32_e32 v203, 16, v179
	v_and_b32_e32 v179, 0xffff0000, v179
	v_lshlrev_b32_e32 v204, 16, v180
	v_and_b32_e32 v180, 0xffff0000, v180
	v_lshlrev_b32_e32 v206, 16, v181
	v_and_b32_e32 v181, 0xffff0000, v181
	v_mul_f32_e32 v178, v192, v178
	v_mul_f32_e32 v171, v171, v202
	v_mul_f32_e32 v179, v196, v179
	v_mul_f32_e32 v180, v198, v180
	v_mul_f32_e32 v181, v200, v181
	v_cvt_pk_bf16_f32 v178, v171, v178
	v_mul_f32_e32 v192, v193, v203
	v_mul_f32_e32 v193, v197, v204
	v_mul_f32_e32 v196, v199, v206
	v_cvt_pk_bf16_f32 v179, v192, v179
	v_cvt_pk_bf16_f32 v180, v193, v180
	v_cvt_pk_bf16_f32 v181, v196, v181
	global_store_dwordx4 v[194:195], v[178:181], off offset:1024
	v_rcp_f32_e32 v171, v201
	v_exp_f32_e32 v109, v109
	v_add_f32_e32 v178, 1.0, v205
	v_rcp_f32_e32 v178, v178
	v_lshlrev_b32_e32 v179, 16, v182
	v_mul_f32_e32 v171, v171, v179
	v_and_b32_e32 v179, 0xffff0000, v182
	v_mul_f32_e32 v178, v178, v179
	v_cvt_pk_bf16_f32 v178, v171, v178
	v_lshlrev_b32_e32 v171, 16, v183
	v_mul_f32_e32 v118, v118, v171
	v_and_b32_e32 v171, 0xffff0000, v183
	v_mul_f32_e32 v119, v119, v171
	v_cvt_pk_bf16_f32 v179, v118, v119
	v_lshlrev_b32_e32 v118, 16, v184
	v_mul_f32_e32 v112, v112, v118
	v_and_b32_e32 v118, 0xffff0000, v184
	v_mul_f32_e32 v113, v113, v118
	v_cvt_pk_bf16_f32 v180, v112, v113
	v_add_f32_e32 v112, 1.0, v114
	v_rcp_f32_e32 v112, v112
	v_add_f32_e32 v113, 1.0, v115
	v_rcp_f32_e32 v113, v113
	v_add_f32_e32 v108, 1.0, v108
	v_rcp_f32_e32 v108, v108
	v_add_f32_e32 v109, 1.0, v109
	v_lshlrev_b32_e32 v114, 16, v185
	v_rcp_f32_e32 v109, v109
	v_mul_f32_e32 v110, 0xbfb8aa3b, v110
	v_mul_f32_e32 v112, v112, v114
	v_and_b32_e32 v114, 0xffff0000, v185
	v_exp_f32_e32 v110, v110
	v_mul_f32_e32 v111, 0xbfb8aa3b, v111
	v_mul_f32_e32 v113, v113, v114
	v_lshlrev_b32_e32 v114, 16, v186
	v_exp_f32_e32 v111, v111
	v_mul_f32_e32 v108, v108, v114
	v_and_b32_e32 v114, 0xffff0000, v186
	v_mul_f32_e32 v104, 0xbfb8aa3b, v104
	v_mul_f32_e32 v109, v109, v114
	v_exp_f32_e32 v104, v104
	v_mul_f32_e32 v105, 0xbfb8aa3b, v105
	v_cvt_pk_bf16_f32 v181, v112, v113
	global_store_dwordx4 v[194:195], v[178:181], off offset:1280
	v_cvt_pk_bf16_f32 v108, v108, v109
	v_add_f32_e32 v109, 1.0, v110
	v_exp_f32_e32 v105, v105
	v_rcp_f32_e32 v109, v109
	v_add_f32_e32 v110, 1.0, v111
	v_rcp_f32_e32 v110, v110
	v_add_f32_e32 v104, 1.0, v104
	v_lshlrev_b32_e32 v111, 16, v187
	v_rcp_f32_e32 v104, v104
	v_add_f32_e32 v105, 1.0, v105
	v_mul_f32_e32 v106, 0xbfb8aa3b, v106
	v_mul_f32_e32 v109, v109, v111
	v_and_b32_e32 v111, 0xffff0000, v187
	v_rcp_f32_e32 v105, v105
	v_exp_f32_e32 v106, v106
	v_mul_f32_e32 v107, 0xbfb8aa3b, v107
	v_mul_f32_e32 v110, v110, v111
	v_exp_f32_e32 v107, v107
	v_mul_f32_e32 v100, 0xbfb8aa3b, v100
	v_cvt_pk_bf16_f32 v109, v109, v110
	v_lshlrev_b32_e32 v110, 16, v188
	v_exp_f32_e32 v100, v100
	v_mul_f32_e32 v101, 0xbfb8aa3b, v101
	v_mul_f32_e32 v104, v104, v110
	v_and_b32_e32 v110, 0xffff0000, v188
	v_exp_f32_e32 v101, v101
	v_mul_f32_e32 v105, v105, v110
	v_cvt_pk_bf16_f32 v110, v104, v105
	v_add_f32_e32 v104, 1.0, v106
	v_rcp_f32_e32 v104, v104
	v_add_f32_e32 v105, 1.0, v107
	v_rcp_f32_e32 v105, v105
	v_add_f32_e32 v100, 1.0, v100
	v_rcp_f32_e32 v100, v100
	v_add_f32_e32 v101, 1.0, v101
	v_lshlrev_b32_e32 v106, 16, v189
	v_rcp_f32_e32 v101, v101
	v_mul_f32_e32 v102, 0xbfb8aa3b, v102
	v_mul_f32_e32 v104, v104, v106
	v_and_b32_e32 v106, 0xffff0000, v189
	v_exp_f32_e32 v102, v102
	v_mul_f32_e32 v103, 0xbfb8aa3b, v103
	v_lshlrev_b64 v[112:113], 11, v[190:191]
	v_mul_f32_e32 v105, v105, v106
	v_lshlrev_b32_e32 v106, 16, v136
	v_exp_f32_e32 v103, v103
	v_cvt_pk_bf16_f32 v111, v104, v105
	v_lshl_add_u64 v[104:105], s[46:47], 0, v[112:113]
	v_mul_f32_e32 v100, v100, v106
	v_and_b32_e32 v106, 0xffff0000, v136
	v_mul_f32_e32 v96, 0xbfb8aa3b, v96
	v_lshl_add_u64 v[104:105], v[104:105], 0, v[168:169]
	v_mul_f32_e32 v101, v101, v106
	v_exp_f32_e32 v96, v96
	v_mul_f32_e32 v97, 0xbfb8aa3b, v97
	global_store_dwordx4 v[104:105], v[108:111], off offset:1024
	v_cvt_pk_bf16_f32 v100, v100, v101
	v_add_f32_e32 v101, 1.0, v102
	v_exp_f32_e32 v97, v97
	v_rcp_f32_e32 v101, v101
	v_add_f32_e32 v102, 1.0, v103
	v_rcp_f32_e32 v102, v102
	v_add_f32_e32 v96, 1.0, v96
	v_lshlrev_b32_e32 v103, 16, v137
	v_rcp_f32_e32 v96, v96
	v_add_f32_e32 v97, 1.0, v97
	v_mul_f32_e32 v98, 0xbfb8aa3b, v98
	v_mul_f32_e32 v101, v101, v103
	v_and_b32_e32 v103, 0xffff0000, v137
	v_rcp_f32_e32 v97, v97
	v_exp_f32_e32 v98, v98
	v_mul_f32_e32 v99, 0xbfb8aa3b, v99
	v_mul_f32_e32 v102, v102, v103
	v_exp_f32_e32 v99, v99
	v_mul_f32_e32 v92, 0xbfb8aa3b, v92
	v_cvt_pk_bf16_f32 v101, v101, v102
	v_lshlrev_b32_e32 v102, 16, v138
	v_exp_f32_e32 v92, v92
	v_mul_f32_e32 v93, 0xbfb8aa3b, v93
	v_mul_f32_e32 v96, v96, v102
	v_and_b32_e32 v102, 0xffff0000, v138
	v_exp_f32_e32 v93, v93
	v_mul_f32_e32 v97, v97, v102
	v_cvt_pk_bf16_f32 v102, v96, v97
	v_add_f32_e32 v96, 1.0, v98
	v_rcp_f32_e32 v96, v96
	v_add_f32_e32 v97, 1.0, v99
	v_rcp_f32_e32 v97, v97
	v_add_f32_e32 v92, 1.0, v92
	v_rcp_f32_e32 v92, v92
	v_add_f32_e32 v93, 1.0, v93
	v_lshlrev_b32_e32 v98, 16, v139
	v_rcp_f32_e32 v93, v93
	v_mul_f32_e32 v94, 0xbfb8aa3b, v94
	v_mul_f32_e32 v96, v96, v98
	v_and_b32_e32 v98, 0xffff0000, v139
	v_exp_f32_e32 v94, v94
	v_mul_f32_e32 v95, 0xbfb8aa3b, v95
	v_mul_f32_e32 v97, v97, v98
	v_lshlrev_b32_e32 v98, 16, v132
	v_exp_f32_e32 v95, v95
	v_mul_f32_e32 v92, v92, v98
	v_and_b32_e32 v98, 0xffff0000, v132
	v_mul_f32_e32 v88, 0xbfb8aa3b, v88
	v_mul_f32_e32 v93, v93, v98
	v_exp_f32_e32 v88, v88
	v_mul_f32_e32 v89, 0xbfb8aa3b, v89
	v_cvt_pk_bf16_f32 v103, v96, v97
; DI unsigned pk2(float lo, float hi) { unsigned r; asm volatile("v_cvt_pk_bf16_f32 %0, %1, %2" : "=v"(r) : "v"(lo), "v"(hi)); return r; }
; DI float bflo(unsigned u) { return __uint_as_float(u << 16); }
; DI float bfhi(unsigned u) { return __uint_as_float(u & 0xffff0000u); }
; DI float sigm(float x) { return __builtin_amdgcn_rcpf(1.f + __expf(-x)); }
;     DI void operator()(const f32x4 (&acc)[2][2][4][2], const Unit& u, int wr, int wc, int fr, int fq, const Pre& pre) const {
;     ...
;             for (int m = 0; m < 4; ++m) { const int row = row0 + ai * 128 + m * 16;
; #pragma unroll
;                 for (int bj = 0; bj < 2; ++bj) { const f32x4 v0 = acc[ai][bj][m][0], v1 = acc[ai][bj][m][1]; const u32x4v yy = y[m][bj]; u32x4v o;
;                     o.x = pk2(bflo(yy.x) * sigm(v0[0]), bfhi(yy.x) * sigm(v0[1])); o.y = pk2(bflo(yy.y) * sigm(v0[2]), bfhi(yy.y) * sigm(v0[3]));
;                     o.z = pk2(bflo(yy.z) * sigm(v1[0]), bfhi(yy.z) * sigm(v1[1])); o.w = pk2(bflo(yy.w) * sigm(v1[2]), bfhi(yy.w) * sigm(v1[3]));
;                     *(u32x4v*)(CAT + (size_t)row * 1024 + 512 + cb + bj * 128) = o; } } }
	global_store_dwordx4 v[104:105], v[100:103], off offset:1280
	v_cvt_pk_bf16_f32 v92, v92, v93
	v_add_f32_e32 v93, 1.0, v94
	v_exp_f32_e32 v89, v89
	v_rcp_f32_e32 v93, v93
	v_add_f32_e32 v94, 1.0, v95
	v_rcp_f32_e32 v94, v94
	v_add_f32_e32 v88, 1.0, v88
	v_lshlrev_b32_e32 v95, 16, v133
	v_rcp_f32_e32 v88, v88
	v_add_f32_e32 v89, 1.0, v89
	v_mul_f32_e32 v90, 0xbfb8aa3b, v90
	v_mul_f32_e32 v93, v93, v95
	v_and_b32_e32 v95, 0xffff0000, v133
	v_rcp_f32_e32 v89, v89
	v_exp_f32_e32 v90, v90
	v_mul_f32_e32 v91, 0xbfb8aa3b, v91
	v_mul_f32_e32 v94, v94, v95
	v_exp_f32_e32 v91, v91
	v_mul_f32_e32 v84, 0xbfb8aa3b, v84
	v_cvt_pk_bf16_f32 v93, v93, v94
	v_lshlrev_b32_e32 v94, 16, v134
	v_exp_f32_e32 v84, v84
	v_mul_f32_e32 v85, 0xbfb8aa3b, v85
	v_mul_f32_e32 v88, v88, v94
	v_and_b32_e32 v94, 0xffff0000, v134
	v_exp_f32_e32 v85, v85
	v_mul_f32_e32 v89, v89, v94
	v_cvt_pk_bf16_f32 v94, v88, v89
	v_add_f32_e32 v88, 1.0, v90
	v_rcp_f32_e32 v88, v88
	v_add_f32_e32 v89, 1.0, v91
	v_rcp_f32_e32 v89, v89
	v_add_f32_e32 v84, 1.0, v84
	v_rcp_f32_e32 v84, v84
	v_add_f32_e32 v85, 1.0, v85
	v_lshlrev_b32_e32 v90, 16, v135
	v_rcp_f32_e32 v85, v85
	v_mul_f32_e32 v86, 0xbfb8aa3b, v86
	v_mul_f32_e32 v88, v88, v90
	v_and_b32_e32 v90, 0xffff0000, v135
	v_exp_f32_e32 v86, v86
	v_mul_f32_e32 v87, 0xbfb8aa3b, v87
	v_lshlrev_b64 v[96:97], 11, v[174:175]
	v_mul_f32_e32 v89, v89, v90
	v_lshlrev_b32_e32 v90, 16, v128
	v_exp_f32_e32 v87, v87
	v_cvt_pk_bf16_f32 v95, v88, v89
	v_lshl_add_u64 v[88:89], s[46:47], 0, v[96:97]
	v_mul_f32_e32 v84, v84, v90
	v_and_b32_e32 v90, 0xffff0000, v128
	v_mul_f32_e32 v80, 0xbfb8aa3b, v80
	v_lshl_add_u64 v[88:89], v[88:89], 0, v[168:169]
	v_mul_f32_e32 v85, v85, v90
	v_exp_f32_e32 v80, v80
	v_mul_f32_e32 v81, 0xbfb8aa3b, v81
	global_store_dwordx4 v[88:89], v[92:95], off offset:1024
	v_cvt_pk_bf16_f32 v84, v84, v85
	v_add_f32_e32 v85, 1.0, v86
	v_exp_f32_e32 v81, v81
	v_rcp_f32_e32 v85, v85
	v_add_f32_e32 v86, 1.0, v87
	v_rcp_f32_e32 v86, v86
	v_add_f32_e32 v80, 1.0, v80
	v_lshlrev_b32_e32 v87, 16, v129
	v_rcp_f32_e32 v80, v80
	v_add_f32_e32 v81, 1.0, v81
	v_mul_f32_e32 v82, 0xbfb8aa3b, v82
	v_mul_f32_e32 v85, v85, v87
	v_and_b32_e32 v87, 0xffff0000, v129
	v_rcp_f32_e32 v81, v81
	v_exp_f32_e32 v82, v82
	v_mul_f32_e32 v83, 0xbfb8aa3b, v83
	v_mul_f32_e32 v86, v86, v87
	v_exp_f32_e32 v83, v83
	v_mul_f32_e32 v76, 0xbfb8aa3b, v76
	v_cvt_pk_bf16_f32 v85, v85, v86
	v_lshlrev_b32_e32 v86, 16, v130
	v_exp_f32_e32 v76, v76
	v_mul_f32_e32 v77, 0xbfb8aa3b, v77
	v_mul_f32_e32 v80, v80, v86
	v_and_b32_e32 v86, 0xffff0000, v130
	v_exp_f32_e32 v77, v77
	v_mul_f32_e32 v81, v81, v86
	v_cvt_pk_bf16_f32 v86, v80, v81
	v_add_f32_e32 v80, 1.0, v82
	v_rcp_f32_e32 v80, v80
	v_add_f32_e32 v81, 1.0, v83
	v_rcp_f32_e32 v81, v81
	v_add_f32_e32 v76, 1.0, v76
	v_rcp_f32_e32 v76, v76
	v_add_f32_e32 v77, 1.0, v77
	v_lshlrev_b32_e32 v82, 16, v131
	v_rcp_f32_e32 v77, v77
	v_mul_f32_e32 v78, 0xbfb8aa3b, v78
	v_mul_f32_e32 v80, v80, v82
	v_and_b32_e32 v82, 0xffff0000, v131
	v_exp_f32_e32 v78, v78
	v_mul_f32_e32 v79, 0xbfb8aa3b, v79
	v_mul_f32_e32 v81, v81, v82
	v_lshlrev_b32_e32 v82, 16, v124
	v_exp_f32_e32 v79, v79
	v_mul_f32_e32 v76, v76, v82
	v_and_b32_e32 v82, 0xffff0000, v124
	v_mul_f32_e32 v72, 0xbfb8aa3b, v72
	v_mul_f32_e32 v77, v77, v82
	v_exp_f32_e32 v72, v72
	v_mul_f32_e32 v73, 0xbfb8aa3b, v73
	v_cvt_pk_bf16_f32 v87, v80, v81
	global_store_dwordx4 v[88:89], v[84:87], off offset:1280
	v_cvt_pk_bf16_f32 v76, v76, v77
	v_add_f32_e32 v77, 1.0, v78
	v_exp_f32_e32 v73, v73
	v_rcp_f32_e32 v77, v77
	v_add_f32_e32 v78, 1.0, v79
	v_rcp_f32_e32 v78, v78
	v_add_f32_e32 v72, 1.0, v72
	v_lshlrev_b32_e32 v79, 16, v125
	v_rcp_f32_e32 v72, v72
	v_add_f32_e32 v73, 1.0, v73
	v_mul_f32_e32 v74, 0xbfb8aa3b, v74
	v_mul_f32_e32 v77, v77, v79
	v_and_b32_e32 v79, 0xffff0000, v125
	v_rcp_f32_e32 v73, v73
	v_exp_f32_e32 v74, v74
	v_mul_f32_e32 v75, 0xbfb8aa3b, v75
	v_mul_f32_e32 v78, v78, v79
	v_exp_f32_e32 v75, v75
	v_mul_f32_e32 v68, 0xbfb8aa3b, v68
	v_cvt_pk_bf16_f32 v77, v77, v78
	v_lshlrev_b32_e32 v78, 16, v126
	v_exp_f32_e32 v68, v68
	v_mul_f32_e32 v69, 0xbfb8aa3b, v69
	v_mul_f32_e32 v72, v72, v78
	v_and_b32_e32 v78, 0xffff0000, v126
	v_exp_f32_e32 v69, v69
	v_mul_f32_e32 v73, v73, v78
	v_cvt_pk_bf16_f32 v78, v72, v73
	v_add_f32_e32 v72, 1.0, v74
	v_rcp_f32_e32 v72, v72
	v_add_f32_e32 v73, 1.0, v75
	v_rcp_f32_e32 v73, v73
	v_add_f32_e32 v68, 1.0, v68
	v_rcp_f32_e32 v68, v68
	v_add_f32_e32 v69, 1.0, v69
	v_lshlrev_b32_e32 v74, 16, v127
	v_rcp_f32_e32 v69, v69
	v_mul_f32_e32 v70, 0xbfb8aa3b, v70
	v_mul_f32_e32 v72, v72, v74
	v_and_b32_e32 v74, 0xffff0000, v127
	v_exp_f32_e32 v70, v70
	v_mul_f32_e32 v71, 0xbfb8aa3b, v71
	v_lshlrev_b64 v[80:81], 11, v[116:117]
	v_mul_f32_e32 v73, v73, v74
	v_lshlrev_b32_e32 v74, 16, v120
	v_exp_f32_e32 v71, v71
	v_cvt_pk_bf16_f32 v79, v72, v73
	v_lshl_add_u64 v[72:73], s[46:47], 0, v[80:81]
	v_mul_f32_e32 v68, v68, v74
	v_and_b32_e32 v74, 0xffff0000, v120
	v_mul_f32_e32 v64, 0xbfb8aa3b, v64
	v_lshl_add_u64 v[72:73], v[72:73], 0, v[168:169]
	v_mul_f32_e32 v69, v69, v74
	v_exp_f32_e32 v64, v64
	v_mul_f32_e32 v65, 0xbfb8aa3b, v65
	global_store_dwordx4 v[72:73], v[76:79], off offset:1024
	v_cvt_pk_bf16_f32 v68, v68, v69
	v_add_f32_e32 v69, 1.0, v70
	v_exp_f32_e32 v65, v65
	v_rcp_f32_e32 v69, v69
	v_add_f32_e32 v70, 1.0, v71
	v_rcp_f32_e32 v70, v70
	v_add_f32_e32 v64, 1.0, v64
	v_lshlrev_b32_e32 v71, 16, v121
	v_rcp_f32_e32 v64, v64
	v_add_f32_e32 v65, 1.0, v65
	v_mul_f32_e32 v66, 0xbfb8aa3b, v66
	v_mul_f32_e32 v69, v69, v71
	v_and_b32_e32 v71, 0xffff0000, v121
	v_rcp_f32_e32 v65, v65
	v_exp_f32_e32 v66, v66
	v_mul_f32_e32 v67, 0xbfb8aa3b, v67
	v_mul_f32_e32 v70, v70, v71
; DI unsigned pk2(float lo, float hi) { unsigned r; asm volatile("v_cvt_pk_bf16_f32 %0, %1, %2" : "=v"(r) : "v"(lo), "v"(hi)); return r; }
; DI float bflo(unsigned u) { return __uint_as_float(u << 16); }
; DI float bfhi(unsigned u) { return __uint_as_float(u & 0xffff0000u); }
; DI float sigm(float x) { return __builtin_amdgcn_rcpf(1.f + __expf(-x)); }
;     DI void operator()(const f32x4 (&acc)[2][2][4][2], const Unit& u, int wr, int wc, int fr, int fq, const Pre& pre) const {
;     ...
;         for (int ai = 0; ai < 2; ++ai) {
;             u32x4v y[4][2];
; #pragma unroll
;             for (int m = 0; m < 4; ++m)
; #pragma unroll
;                 for (int bj = 0; bj < 2; ++bj) y[m][bj] = *(const u32x4v*)(YG + (size_t)(row0 + ai * 128 + m * 16) * 512 + cb + bj * 128);
; #pragma unroll
;             for (int m = 0; m < 4; ++m) { const int row = row0 + ai * 128 + m * 16;
; #pragma unroll
;                 for (int bj = 0; bj < 2; ++bj) { const f32x4 v0 = acc[ai][bj][m][0], v1 = acc[ai][bj][m][1]; const u32x4v yy = y[m][bj]; u32x4v o;
;                     o.x = pk2(bflo(yy.x) * sigm(v0[0]), bfhi(yy.x) * sigm(v0[1])); o.y = pk2(bflo(yy.y) * sigm(v0[2]), bfhi(yy.y) * sigm(v0[3]));
;                     o.z = pk2(bflo(yy.z) * sigm(v1[0]), bfhi(yy.z) * sigm(v1[1])); o.w = pk2(bflo(yy.w) * sigm(v1[2]), bfhi(yy.w) * sigm(v1[3]));
;                     *(u32x4v*)(CAT + (size_t)row * 1024 + 512 + cb + bj * 128) = o; } } }
	v_exp_f32_e32 v67, v67
	v_cvt_pk_bf16_f32 v69, v69, v70
	v_lshlrev_b32_e32 v70, 16, v122
	v_mul_f32_e32 v64, v64, v70
	v_and_b32_e32 v70, 0xffff0000, v122
	v_mul_f32_e32 v65, v65, v70
	v_cvt_pk_bf16_f32 v70, v64, v65
	v_add_f32_e32 v64, 1.0, v66
	v_rcp_f32_e32 v64, v64
	v_add_f32_e32 v65, 1.0, v67
	v_rcp_f32_e32 v65, v65
	v_lshlrev_b32_e32 v66, 16, v123
	v_mul_f32_e32 v64, v64, v66
	v_and_b32_e32 v66, 0xffff0000, v123
	v_add_u32_e32 v100, 0x80, v170
	v_mul_f32_e32 v65, v65, v66
	v_ashrrev_i32_e32 v101, 31, v100
	v_cvt_pk_bf16_f32 v71, v64, v65
	v_lshlrev_b64 v[64:65], 10, v[100:101]
	global_store_dwordx4 v[72:73], v[68:71], off offset:1280
	v_lshl_add_u64 v[64:65], v[172:173], 0, v[64:65]
	global_load_dwordx4 v[92:95], v[64:65], off
	global_load_dwordx4 v[96:99], v[64:65], off offset:256
	v_add_u32_e32 v102, 0x90, v170
	v_ashrrev_i32_e32 v103, 31, v102
	v_lshlrev_b64 v[64:65], 10, v[102:103]
	v_lshl_add_u64 v[64:65], v[172:173], 0, v[64:65]
	global_load_dwordx4 v[84:87], v[64:65], off
	global_load_dwordx4 v[80:83], v[64:65], off offset:256
	v_add_u32_e32 v90, 0xa0, v170
	v_ashrrev_i32_e32 v91, 31, v90
	v_lshlrev_b64 v[64:65], 10, v[90:91]
	v_lshl_add_u64 v[64:65], v[172:173], 0, v[64:65]
	v_mul_f32_e32 v60, 0xbfb8aa3b, v60
	v_mul_f32_e32 v61, 0xbfb8aa3b, v61
	global_load_dwordx4 v[76:79], v[64:65], off
	global_load_dwordx4 v[72:75], v[64:65], off offset:256
	v_exp_f32_e32 v60, v60
	v_exp_f32_e32 v61, v61
	v_mul_f32_e32 v62, 0xbfb8aa3b, v62
	v_add_u32_e32 v88, 0xb0, v170
	v_add_f32_e32 v60, 1.0, v60
	v_add_f32_e32 v61, 1.0, v61
	v_rcp_f32_e32 v60, v60
	v_rcp_f32_e32 v61, v61
	v_exp_f32_e32 v62, v62
	v_mul_f32_e32 v63, 0xbfb8aa3b, v63
	v_ashrrev_i32_e32 v89, 31, v88
	v_exp_f32_e32 v63, v63
	v_lshlrev_b64 v[64:65], 10, v[88:89]
	v_mul_f32_e32 v56, 0xbfb8aa3b, v56
	v_lshl_add_u64 v[64:65], v[172:173], 0, v[64:65]
	v_exp_f32_e32 v56, v56
	v_mul_f32_e32 v57, 0xbfb8aa3b, v57
	global_load_dwordx4 v[68:71], v[64:65], off
	s_nop 0
	global_load_dwordx4 v[64:67], v[64:65], off offset:256
	v_exp_f32_e32 v57, v57
	v_add_f32_e32 v56, 1.0, v56
	v_rcp_f32_e32 v56, v56
	v_mul_f32_e32 v58, 0xbfb8aa3b, v58
	v_add_f32_e32 v57, 1.0, v57
	v_rcp_f32_e32 v57, v57
	v_exp_f32_e32 v58, v58
	v_mul_f32_e32 v59, 0xbfb8aa3b, v59
	v_exp_f32_e32 v59, v59
	v_mul_f32_e32 v52, 0xbfb8aa3b, v52
	v_exp_f32_e32 v52, v52
	v_mul_f32_e32 v53, 0xbfb8aa3b, v53
	v_exp_f32_e32 v53, v53
	v_mul_f32_e32 v54, 0xbfb8aa3b, v54
	v_add_f32_e32 v52, 1.0, v52
	v_rcp_f32_e32 v52, v52
	v_add_f32_e32 v53, 1.0, v53
	v_rcp_f32_e32 v53, v53
	v_exp_f32_e32 v54, v54
	v_mul_f32_e32 v55, 0xbfb8aa3b, v55
	v_lshlrev_b64 v[100:101], 11, v[100:101]
	v_exp_f32_e32 v55, v55
	v_mul_f32_e32 v48, 0xbfb8aa3b, v48
	v_exp_f32_e32 v48, v48
	v_mul_f32_e32 v49, 0xbfb8aa3b, v49
	v_exp_f32_e32 v49, v49
	v_mul_f32_e32 v50, 0xbfb8aa3b, v50
	v_add_f32_e32 v48, 1.0, v48
	v_rcp_f32_e32 v48, v48
	v_add_f32_e32 v49, 1.0, v49
	v_rcp_f32_e32 v49, v49
	v_exp_f32_e32 v50, v50
	v_mul_f32_e32 v51, 0xbfb8aa3b, v51
	v_exp_f32_e32 v51, v51
	v_mul_f32_e32 v44, 0xbfb8aa3b, v44
	v_exp_f32_e32 v44, v44
	v_mul_f32_e32 v45, 0xbfb8aa3b, v45
	v_exp_f32_e32 v45, v45
	v_mul_f32_e32 v46, 0xbfb8aa3b, v46
	v_add_f32_e32 v44, 1.0, v44
	v_rcp_f32_e32 v44, v44
	v_add_f32_e32 v45, 1.0, v45
	v_rcp_f32_e32 v45, v45
	v_exp_f32_e32 v46, v46
	v_mul_f32_e32 v47, 0xbfb8aa3b, v47
	v_exp_f32_e32 v47, v47
	v_mul_f32_e32 v40, 0xbfb8aa3b, v40
	v_exp_f32_e32 v40, v40
	s_waitcnt vmcnt(0)
	v_lshlrev_b32_e32 v104, 16, v92
	v_and_b32_e32 v92, 0xffff0000, v92
	v_mul_f32_e32 v60, v60, v104
	v_mul_f32_e32 v61, v61, v92
	v_cvt_pk_bf16_f32 v60, v60, v61
	v_add_f32_e32 v61, 1.0, v62
	v_rcp_f32_e32 v61, v61
	v_add_f32_e32 v62, 1.0, v63
	v_rcp_f32_e32 v62, v62
	v_lshlrev_b32_e32 v63, 16, v93
	v_mul_f32_e32 v61, v61, v63
	v_and_b32_e32 v63, 0xffff0000, v93
	v_mul_f32_e32 v62, v62, v63
	v_cvt_pk_bf16_f32 v61, v61, v62
	v_lshlrev_b32_e32 v62, 16, v94
	v_mul_f32_e32 v56, v56, v62
	v_and_b32_e32 v62, 0xffff0000, v94
	v_mul_f32_e32 v57, v57, v62
	v_cvt_pk_bf16_f32 v62, v56, v57
	v_add_f32_e32 v56, 1.0, v58
	v_rcp_f32_e32 v56, v56
	v_add_f32_e32 v57, 1.0, v59
	v_rcp_f32_e32 v57, v57
	v_lshlrev_b32_e32 v58, 16, v95
	v_mul_f32_e32 v56, v56, v58
	v_and_b32_e32 v58, 0xffff0000, v95
	v_mul_f32_e32 v57, v57, v58
	v_lshlrev_b32_e32 v58, 16, v96
	v_cvt_pk_bf16_f32 v63, v56, v57
	v_lshl_add_u64 v[56:57], s[46:47], 0, v[100:101]
	v_mul_f32_e32 v52, v52, v58
	v_and_b32_e32 v58, 0xffff0000, v96
	v_lshl_add_u64 v[56:57], v[56:57], 0, v[168:169]
	v_mul_f32_e32 v53, v53, v58
	global_store_dwordx4 v[56:57], v[60:63], off offset:1024
	v_cvt_pk_bf16_f32 v52, v52, v53
	v_add_f32_e32 v53, 1.0, v54
	v_rcp_f32_e32 v53, v53
	v_add_f32_e32 v54, 1.0, v55
	v_rcp_f32_e32 v54, v54
	v_lshlrev_b32_e32 v55, 16, v97
	v_mul_f32_e32 v53, v53, v55
	v_and_b32_e32 v55, 0xffff0000, v97
	v_mul_f32_e32 v54, v54, v55
	v_cvt_pk_bf16_f32 v53, v53, v54
	v_lshlrev_b32_e32 v54, 16, v98
	v_mul_f32_e32 v48, v48, v54
	v_and_b32_e32 v54, 0xffff0000, v98
	v_mul_f32_e32 v49, v49, v54
	v_cvt_pk_bf16_f32 v54, v48, v49
	v_add_f32_e32 v48, 1.0, v50
	v_rcp_f32_e32 v48, v48
	v_add_f32_e32 v49, 1.0, v51
	v_rcp_f32_e32 v49, v49
	v_lshlrev_b32_e32 v50, 16, v99
	v_mul_f32_e32 v48, v48, v50
	v_and_b32_e32 v50, 0xffff0000, v99
	v_mul_f32_e32 v49, v49, v50
	v_lshlrev_b32_e32 v50, 16, v84
	v_mul_f32_e32 v44, v44, v50
	v_and_b32_e32 v50, 0xffff0000, v84
	v_mul_f32_e32 v45, v45, v50
	v_mul_f32_e32 v41, 0xbfb8aa3b, v41
	v_cvt_pk_bf16_f32 v55, v48, v49
	global_store_dwordx4 v[56:57], v[52:55], off offset:1280
	v_cvt_pk_bf16_f32 v44, v44, v45
	v_add_f32_e32 v45, 1.0, v46
	v_exp_f32_e32 v41, v41
	v_rcp_f32_e32 v45, v45
	v_add_f32_e32 v46, 1.0, v47
; DI unsigned pk2(float lo, float hi) { unsigned r; asm volatile("v_cvt_pk_bf16_f32 %0, %1, %2" : "=v"(r) : "v"(lo), "v"(hi)); return r; }
; DI float bflo(unsigned u) { return __uint_as_float(u << 16); }
; DI float bfhi(unsigned u) { return __uint_as_float(u & 0xffff0000u); }
; DI float sigm(float x) { return __builtin_amdgcn_rcpf(1.f + __expf(-x)); }
;     DI void operator()(const f32x4 (&acc)[2][2][4][2], const Unit& u, int wr, int wc, int fr, int fq, const Pre& pre) const {
;     ...
;             for (int m = 0; m < 4; ++m) { const int row = row0 + ai * 128 + m * 16;
; #pragma unroll
;                 for (int bj = 0; bj < 2; ++bj) { const f32x4 v0 = acc[ai][bj][m][0], v1 = acc[ai][bj][m][1]; const u32x4v yy = y[m][bj]; u32x4v o;
;                     o.x = pk2(bflo(yy.x) * sigm(v0[0]), bfhi(yy.x) * sigm(v0[1])); o.y = pk2(bflo(yy.y) * sigm(v0[2]), bfhi(yy.y) * sigm(v0[3]));
;                     o.z = pk2(bflo(yy.z) * sigm(v1[0]), bfhi(yy.z) * sigm(v1[1])); o.w = pk2(bflo(yy.w) * sigm(v1[2]), bfhi(yy.w) * sigm(v1[3]));
;                     *(u32x4v*)(CAT + (size_t)row * 1024 + 512 + cb + bj * 128) = o; } } }
	v_rcp_f32_e32 v46, v46
	v_add_f32_e32 v40, 1.0, v40
	v_lshlrev_b32_e32 v47, 16, v85
	v_rcp_f32_e32 v40, v40
	v_add_f32_e32 v41, 1.0, v41
	v_mul_f32_e32 v42, 0xbfb8aa3b, v42
	v_mul_f32_e32 v45, v45, v47
	v_and_b32_e32 v47, 0xffff0000, v85
	v_rcp_f32_e32 v41, v41
	v_exp_f32_e32 v42, v42
	v_mul_f32_e32 v43, 0xbfb8aa3b, v43
	v_mul_f32_e32 v46, v46, v47
	v_exp_f32_e32 v43, v43
	v_mul_f32_e32 v36, 0xbfb8aa3b, v36
	v_cvt_pk_bf16_f32 v45, v45, v46
	v_lshlrev_b32_e32 v46, 16, v86
	v_exp_f32_e32 v36, v36
	v_mul_f32_e32 v37, 0xbfb8aa3b, v37
	v_mul_f32_e32 v40, v40, v46
	v_and_b32_e32 v46, 0xffff0000, v86
	v_exp_f32_e32 v37, v37
	v_mul_f32_e32 v41, v41, v46
	v_cvt_pk_bf16_f32 v46, v40, v41
	v_add_f32_e32 v40, 1.0, v42
	v_rcp_f32_e32 v40, v40
	v_add_f32_e32 v41, 1.0, v43
	v_rcp_f32_e32 v41, v41
	v_add_f32_e32 v36, 1.0, v36
	v_rcp_f32_e32 v36, v36
	v_add_f32_e32 v37, 1.0, v37
	v_lshlrev_b32_e32 v42, 16, v87
	v_rcp_f32_e32 v37, v37
	v_mul_f32_e32 v38, 0xbfb8aa3b, v38
	v_mul_f32_e32 v40, v40, v42
	v_and_b32_e32 v42, 0xffff0000, v87
	v_exp_f32_e32 v38, v38
	v_mul_f32_e32 v39, 0xbfb8aa3b, v39
	v_lshlrev_b64 v[48:49], 11, v[102:103]
	v_mul_f32_e32 v41, v41, v42
	v_lshlrev_b32_e32 v42, 16, v80
	v_exp_f32_e32 v39, v39
	v_cvt_pk_bf16_f32 v47, v40, v41
	v_lshl_add_u64 v[40:41], s[46:47], 0, v[48:49]
	v_mul_f32_e32 v36, v36, v42
	v_and_b32_e32 v42, 0xffff0000, v80
	v_mul_f32_e32 v32, 0xbfb8aa3b, v32
	v_lshl_add_u64 v[40:41], v[40:41], 0, v[168:169]
	v_mul_f32_e32 v37, v37, v42
	v_exp_f32_e32 v32, v32
	v_mul_f32_e32 v33, 0xbfb8aa3b, v33
	global_store_dwordx4 v[40:41], v[44:47], off offset:1024
	v_cvt_pk_bf16_f32 v36, v36, v37
	v_add_f32_e32 v37, 1.0, v38
	v_exp_f32_e32 v33, v33
	v_rcp_f32_e32 v37, v37
	v_add_f32_e32 v38, 1.0, v39
	v_rcp_f32_e32 v38, v38
	v_add_f32_e32 v32, 1.0, v32
	v_lshlrev_b32_e32 v39, 16, v81
	v_rcp_f32_e32 v32, v32
	v_add_f32_e32 v33, 1.0, v33
	v_mul_f32_e32 v34, 0xbfb8aa3b, v34
	v_mul_f32_e32 v37, v37, v39
	v_and_b32_e32 v39, 0xffff0000, v81
	v_rcp_f32_e32 v33, v33
	v_exp_f32_e32 v34, v34
	v_mul_f32_e32 v35, 0xbfb8aa3b, v35
	v_mul_f32_e32 v38, v38, v39
	v_exp_f32_e32 v35, v35
	v_mul_f32_e32 v28, 0xbfb8aa3b, v28
	v_cvt_pk_bf16_f32 v37, v37, v38
	v_lshlrev_b32_e32 v38, 16, v82
	v_exp_f32_e32 v28, v28
	v_mul_f32_e32 v29, 0xbfb8aa3b, v29
	v_mul_f32_e32 v32, v32, v38
	v_and_b32_e32 v38, 0xffff0000, v82
	v_exp_f32_e32 v29, v29
	v_mul_f32_e32 v33, v33, v38
	v_cvt_pk_bf16_f32 v38, v32, v33
	v_add_f32_e32 v32, 1.0, v34
	v_rcp_f32_e32 v32, v32
	v_add_f32_e32 v33, 1.0, v35
	v_rcp_f32_e32 v33, v33
	v_add_f32_e32 v28, 1.0, v28
	v_rcp_f32_e32 v28, v28
	v_add_f32_e32 v29, 1.0, v29
	v_lshlrev_b32_e32 v34, 16, v83
	v_rcp_f32_e32 v29, v29
	v_mul_f32_e32 v30, 0xbfb8aa3b, v30
	v_mul_f32_e32 v32, v32, v34
	v_and_b32_e32 v34, 0xffff0000, v83
	v_exp_f32_e32 v30, v30
	v_mul_f32_e32 v31, 0xbfb8aa3b, v31
	v_mul_f32_e32 v33, v33, v34
	v_lshlrev_b32_e32 v34, 16, v76
	v_exp_f32_e32 v31, v31
	v_mul_f32_e32 v28, v28, v34
	v_and_b32_e32 v34, 0xffff0000, v76
	v_mul_f32_e32 v24, 0xbfb8aa3b, v24
	v_mul_f32_e32 v29, v29, v34
	v_exp_f32_e32 v24, v24
	v_mul_f32_e32 v25, 0xbfb8aa3b, v25
	v_cvt_pk_bf16_f32 v39, v32, v33
	global_store_dwordx4 v[40:41], v[36:39], off offset:1280
	v_cvt_pk_bf16_f32 v28, v28, v29
	v_add_f32_e32 v29, 1.0, v30
	v_exp_f32_e32 v25, v25
	v_rcp_f32_e32 v29, v29
	v_add_f32_e32 v30, 1.0, v31
	v_rcp_f32_e32 v30, v30
	v_add_f32_e32 v24, 1.0, v24
	v_lshlrev_b32_e32 v31, 16, v77
	v_rcp_f32_e32 v24, v24
	v_add_f32_e32 v25, 1.0, v25
	v_mul_f32_e32 v26, 0xbfb8aa3b, v26
	v_mul_f32_e32 v29, v29, v31
	v_and_b32_e32 v31, 0xffff0000, v77
	v_rcp_f32_e32 v25, v25
	v_exp_f32_e32 v26, v26
	v_mul_f32_e32 v27, 0xbfb8aa3b, v27
	v_mul_f32_e32 v30, v30, v31
	v_exp_f32_e32 v27, v27
	v_mul_f32_e32 v20, 0xbfb8aa3b, v20
	v_cvt_pk_bf16_f32 v29, v29, v30
	v_lshlrev_b32_e32 v30, 16, v78
	v_exp_f32_e32 v20, v20
	v_mul_f32_e32 v21, 0xbfb8aa3b, v21
	v_mul_f32_e32 v24, v24, v30
	v_and_b32_e32 v30, 0xffff0000, v78
	v_exp_f32_e32 v21, v21
	v_mul_f32_e32 v25, v25, v30
	v_cvt_pk_bf16_f32 v30, v24, v25
	v_add_f32_e32 v24, 1.0, v26
	v_rcp_f32_e32 v24, v24
	v_add_f32_e32 v25, 1.0, v27
	v_rcp_f32_e32 v25, v25
	v_add_f32_e32 v20, 1.0, v20
	v_rcp_f32_e32 v20, v20
	v_add_f32_e32 v21, 1.0, v21
	v_lshlrev_b32_e32 v26, 16, v79
	v_rcp_f32_e32 v21, v21
	v_mul_f32_e32 v22, 0xbfb8aa3b, v22
	v_mul_f32_e32 v24, v24, v26
	v_and_b32_e32 v26, 0xffff0000, v79
	v_exp_f32_e32 v22, v22
	v_mul_f32_e32 v23, 0xbfb8aa3b, v23
	v_lshlrev_b64 v[32:33], 11, v[90:91]
	v_mul_f32_e32 v25, v25, v26
	v_lshlrev_b32_e32 v26, 16, v72
	v_exp_f32_e32 v23, v23
	v_cvt_pk_bf16_f32 v31, v24, v25
	v_lshl_add_u64 v[24:25], s[46:47], 0, v[32:33]
	v_mul_f32_e32 v20, v20, v26
	v_and_b32_e32 v26, 0xffff0000, v72
	v_mul_f32_e32 v16, 0xbfb8aa3b, v16
	v_lshl_add_u64 v[24:25], v[24:25], 0, v[168:169]
	v_mul_f32_e32 v21, v21, v26
	v_exp_f32_e32 v16, v16
	v_mul_f32_e32 v17, 0xbfb8aa3b, v17
; #define PG8_WAIT_V(n) asm volatile("s_waitcnt vmcnt(" #n ")" ::: "memory")
; #define PG8_BAR __builtin_amdgcn_s_barrier()
; DI unsigned pk2(float lo, float hi) { unsigned r; asm volatile("v_cvt_pk_bf16_f32 %0, %1, %2" : "=v"(r) : "v"(lo), "v"(hi)); return r; }
; DI float bflo(unsigned u) { return __uint_as_float(u << 16); }
; DI float bfhi(unsigned u) { return __uint_as_float(u & 0xffff0000u); }
; DI float sigm(float x) { return __builtin_amdgcn_rcpf(1.f + __expf(-x)); }
; template <class Epi, class Sched>
; __device__ __forceinline__ void gemm_phase(PG8_LAS unsigned char* lds, const Gemm g, const Sched& S, const Epi& E) {
;     ...
;         cur = nxt; cA = nA; cB = nB; ++ui;
;     }
;     PG8_WAIT_V(0);
;     if (wr == 0) PG8_BAR;
;     PG8_BAR;
;     DI void operator()(const f32x4 (&acc)[2][2][4][2], const Unit& u, int wr, int wc, int fr, int fq, const Pre& pre) const {
;     ...
;             for (int m = 0; m < 4; ++m) { const int row = row0 + ai * 128 + m * 16;
; #pragma unroll
;                 for (int bj = 0; bj < 2; ++bj) { const f32x4 v0 = acc[ai][bj][m][0], v1 = acc[ai][bj][m][1]; const u32x4v yy = y[m][bj]; u32x4v o;
;                     o.x = pk2(bflo(yy.x) * sigm(v0[0]), bfhi(yy.x) * sigm(v0[1])); o.y = pk2(bflo(yy.y) * sigm(v0[2]), bfhi(yy.y) * sigm(v0[3]));
;                     o.z = pk2(bflo(yy.z) * sigm(v1[0]), bfhi(yy.z) * sigm(v1[1])); o.w = pk2(bflo(yy.w) * sigm(v1[2]), bfhi(yy.w) * sigm(v1[3]));
;                     *(u32x4v*)(CAT + (size_t)row * 1024 + 512 + cb + bj * 128) = o; } } }
	global_store_dwordx4 v[24:25], v[28:31], off offset:1024
	v_cvt_pk_bf16_f32 v20, v20, v21
	v_add_f32_e32 v21, 1.0, v22
	v_exp_f32_e32 v17, v17
	v_rcp_f32_e32 v21, v21
	v_add_f32_e32 v22, 1.0, v23
	v_rcp_f32_e32 v22, v22
	v_add_f32_e32 v16, 1.0, v16
	v_lshlrev_b32_e32 v23, 16, v73
	v_rcp_f32_e32 v16, v16
	v_add_f32_e32 v17, 1.0, v17
	v_mul_f32_e32 v18, 0xbfb8aa3b, v18
	v_mul_f32_e32 v21, v21, v23
	v_and_b32_e32 v23, 0xffff0000, v73
	v_rcp_f32_e32 v17, v17
	v_exp_f32_e32 v18, v18
	v_mul_f32_e32 v19, 0xbfb8aa3b, v19
	v_mul_f32_e32 v22, v22, v23
	v_exp_f32_e32 v19, v19
	v_mul_f32_e32 v12, 0xbfb8aa3b, v12
	v_cvt_pk_bf16_f32 v21, v21, v22
	v_lshlrev_b32_e32 v22, 16, v74
	v_exp_f32_e32 v12, v12
	v_mul_f32_e32 v13, 0xbfb8aa3b, v13
	v_mul_f32_e32 v16, v16, v22
	v_and_b32_e32 v22, 0xffff0000, v74
	v_exp_f32_e32 v13, v13
	v_mul_f32_e32 v17, v17, v22
	v_cvt_pk_bf16_f32 v22, v16, v17
	v_add_f32_e32 v16, 1.0, v18
	v_rcp_f32_e32 v16, v16
	v_add_f32_e32 v17, 1.0, v19
	v_rcp_f32_e32 v17, v17
	v_add_f32_e32 v12, 1.0, v12
	v_rcp_f32_e32 v12, v12
	v_add_f32_e32 v13, 1.0, v13
	v_lshlrev_b32_e32 v18, 16, v75
	v_rcp_f32_e32 v13, v13
	v_mul_f32_e32 v14, 0xbfb8aa3b, v14
	v_mul_f32_e32 v16, v16, v18
	v_and_b32_e32 v18, 0xffff0000, v75
	v_exp_f32_e32 v14, v14
	v_mul_f32_e32 v15, 0xbfb8aa3b, v15
	v_mul_f32_e32 v17, v17, v18
	v_lshlrev_b32_e32 v18, 16, v68
	v_exp_f32_e32 v15, v15
	v_mul_f32_e32 v12, v12, v18
	v_and_b32_e32 v18, 0xffff0000, v68
	v_mul_f32_e32 v8, 0xbfb8aa3b, v8
	v_mul_f32_e32 v13, v13, v18
	v_exp_f32_e32 v8, v8
	v_mul_f32_e32 v9, 0xbfb8aa3b, v9
	v_cvt_pk_bf16_f32 v23, v16, v17
	global_store_dwordx4 v[24:25], v[20:23], off offset:1280
	v_cvt_pk_bf16_f32 v12, v12, v13
	v_add_f32_e32 v13, 1.0, v14
	v_exp_f32_e32 v9, v9
	v_rcp_f32_e32 v13, v13
	v_add_f32_e32 v14, 1.0, v15
	v_rcp_f32_e32 v14, v14
	v_add_f32_e32 v8, 1.0, v8
	v_lshlrev_b32_e32 v15, 16, v69
	v_rcp_f32_e32 v8, v8
	v_add_f32_e32 v9, 1.0, v9
	v_mul_f32_e32 v10, 0xbfb8aa3b, v10
	v_mul_f32_e32 v13, v13, v15
	v_and_b32_e32 v15, 0xffff0000, v69
	v_rcp_f32_e32 v9, v9
	v_exp_f32_e32 v10, v10
	v_mul_f32_e32 v11, 0xbfb8aa3b, v11
	v_mul_f32_e32 v14, v14, v15
	v_exp_f32_e32 v11, v11
	v_mul_f32_e32 v4, 0xbfb8aa3b, v4
	v_cvt_pk_bf16_f32 v13, v13, v14
	v_lshlrev_b32_e32 v14, 16, v70
	v_exp_f32_e32 v4, v4
	v_mul_f32_e32 v5, 0xbfb8aa3b, v5
	v_mul_f32_e32 v8, v8, v14
	v_and_b32_e32 v14, 0xffff0000, v70
	v_exp_f32_e32 v5, v5
	v_mul_f32_e32 v9, v9, v14
	v_cvt_pk_bf16_f32 v14, v8, v9
	v_add_f32_e32 v8, 1.0, v10
	v_rcp_f32_e32 v8, v8
	v_add_f32_e32 v9, 1.0, v11
	v_rcp_f32_e32 v9, v9
	v_add_f32_e32 v4, 1.0, v4
	v_rcp_f32_e32 v4, v4
	v_add_f32_e32 v5, 1.0, v5
	v_lshlrev_b32_e32 v10, 16, v71
	v_rcp_f32_e32 v5, v5
	v_mul_f32_e32 v6, 0xbfb8aa3b, v6
	v_mul_f32_e32 v8, v8, v10
	v_and_b32_e32 v10, 0xffff0000, v71
	v_exp_f32_e32 v6, v6
	v_mul_f32_e32 v7, 0xbfb8aa3b, v7
	v_lshlrev_b64 v[16:17], 11, v[88:89]
	v_mul_f32_e32 v9, v9, v10
	v_lshlrev_b32_e32 v10, 16, v64
	v_exp_f32_e32 v7, v7
	v_cvt_pk_bf16_f32 v15, v8, v9
	v_lshl_add_u64 v[8:9], s[46:47], 0, v[16:17]
	v_mul_f32_e32 v4, v4, v10
	v_and_b32_e32 v10, 0xffff0000, v64
	v_mul_f32_e32 v0, 0xbfb8aa3b, v0
	v_lshl_add_u64 v[8:9], v[8:9], 0, v[168:169]
	v_mul_f32_e32 v5, v5, v10
	v_exp_f32_e32 v0, v0
	v_mul_f32_e32 v1, 0xbfb8aa3b, v1
	global_store_dwordx4 v[8:9], v[12:15], off offset:1024
	v_cvt_pk_bf16_f32 v4, v4, v5
	v_add_f32_e32 v5, 1.0, v6
	v_exp_f32_e32 v1, v1
	v_rcp_f32_e32 v5, v5
	v_add_f32_e32 v6, 1.0, v7
	v_rcp_f32_e32 v6, v6
	v_add_f32_e32 v0, 1.0, v0
	v_lshlrev_b32_e32 v7, 16, v65
	v_rcp_f32_e32 v0, v0
	v_add_f32_e32 v1, 1.0, v1
	v_mul_f32_e32 v2, 0xbfb8aa3b, v2
	v_mul_f32_e32 v5, v5, v7
	v_and_b32_e32 v7, 0xffff0000, v65
	v_rcp_f32_e32 v1, v1
	v_exp_f32_e32 v2, v2
	v_mul_f32_e32 v3, 0xbfb8aa3b, v3
	v_mul_f32_e32 v6, v6, v7
	v_exp_f32_e32 v3, v3
	v_cvt_pk_bf16_f32 v5, v5, v6
	v_lshlrev_b32_e32 v6, 16, v66
	v_mul_f32_e32 v0, v0, v6
	v_and_b32_e32 v6, 0xffff0000, v66
	v_mul_f32_e32 v1, v1, v6
	v_cvt_pk_bf16_f32 v6, v0, v1
	v_add_f32_e32 v0, 1.0, v2
	v_rcp_f32_e32 v0, v0
	v_add_f32_e32 v1, 1.0, v3
	v_rcp_f32_e32 v1, v1
	v_lshlrev_b32_e32 v2, 16, v67
	v_mul_f32_e32 v0, v0, v2
	v_and_b32_e32 v2, 0xffff0000, v67
	s_andn2_b64 vcc, exec, s[0:1]
	s_mov_b32 s12, s6
	s_mov_b32 s36, s4
	s_mov_b64 s[16:17], s[10:11]
	s_mov_b64 s[14:15], s[8:9]
	v_readlane_b32 s37, v255, 9
	v_readlane_b32 s38, v255, 10
	v_readlane_b32 s39, v255, 11
	v_readlane_b32 s40, v255, 12
	v_readlane_b32 s41, v255, 13
	v_readlane_b32 s42, v255, 14
	v_readlane_b32 s43, v255, 15
	v_readlane_b32 s48, v255, 20
	v_readlane_b32 s49, v255, 21
	v_readlane_b32 s50, v255, 22
	v_readlane_b32 s51, v255, 23
	v_mul_f32_e32 v1, v1, v2
	v_cvt_pk_bf16_f32 v7, v0, v1
	global_store_dwordx4 v[8:9], v[4:7], off offset:1280
	s_cbranch_vccnz .LBB0_1184
	s_waitcnt vmcnt(0)
	s_cmpk_gt_u32 s20, 0xff
	s_cbranch_scc1 .LBB0_1195
	s_barrier

; #define PG8_STAGE(bufoff, gbase, voff) do { _Pragma("unroll") for (int _i = 0; _i < 2; ++_i) \
;         __builtin_amdgcn_global_load_lds((const unsigned*)((const char*)(gbase) + (voff)[_i]), (PG8_LAS unsigned*)(lds + (bufoff) + ldsw + _i * 8192), 16, 0, 0); } while (0)
; #define PG8_LDA(dst, b, h) do { _Pragma("unroll") for (int m = 0; m < 4; ++m) _Pragma("unroll") for (int k = 0; k < 2; ++k) dst[m][k] = *(const PG8_LAS bf16x8*)(lds + PG8_SA(b, h) + aoff + m * 2048 + k * 1024); } while (0)
; #define PG8_LDB(dst, b, h) do { _Pragma("unroll") for (int n = 0; n < 2; ++n) _Pragma("unroll") for (int k = 0; k < 2; ++k) dst[n][k] = *(const PG8_LAS bf16x8*)(lds + PG8_SB(b, h) + boff + n * 2048 + k * 1024); } while (0)
; #define PG8_MMA(ai, bj, At, Bt) do { __builtin_amdgcn_s_setprio(1); _Pragma("unroll") for (int m = 0; m < 4; ++m) _Pragma("unroll") for (int n = 0; n < 2; ++n) _Pragma("unroll") for (int k = 0; k < 2; ++k) \
;         acc[ai][bj][m][n] = __builtin_amdgcn_mfma_f32_16x16x32_bf16(Bt[n][k], At[m][k], acc[ai][bj][m][n], 0, 0, 0); __builtin_amdgcn_s_setprio(0); } while (0)
; #define PG8_WAIT_L(n) asm volatile("s_waitcnt lgkmcnt(" #n ")" ::: "memory")
; #define PG8_BAR __builtin_amdgcn_s_barrier()
; #define PG8_SCHED __builtin_amdgcn_sched_barrier(0)
; template <class Epi, class Sched>
; __device__ __forceinline__ void gemm_phase(PG8_LAS unsigned char* lds, const Gemm g, const Sched& S, const Epi& E) {
;     ...
;             PG8_LDB(B0, 0, 0); PG8_SCHED; PG8_LDA(At, 0, 0); PG8_STAGE(PG8_SA(1, 1), a1 + hstep, voffA);
;             PG8_WAIT_L(8); PG8_BAR; PG8_WAIT_L(0); PG8_MMA(0, 0, At, B0); PG8_BAR; PG8_SCHED;
;             PG8_LDB(B1, 0, 1); PG8_STAGE(PG8_SB(0, 0), b2, voffB);
;             PG8_BAR; PG8_WAIT_L(0); PG8_MMA(0, 1, At, B1); PG8_BAR;
;             PG8_LDA(At, 0, 1); PG8_STAGE(PG8_SA(0, 0), a2, voffA);
;             PG8_BAR; PG8_WAIT_L(0); PG8_MMA(1, 0, At, B0); PG8_BAR; PG8_SCHED;
.LBB0_1313:
	ds_read_b128 v[128:131], v163
	ds_read_b128 v[132:135], v163 offset:1024
	ds_read_b128 v[136:139], v163 offset:2048
	ds_read_b128 v[140:143], v163 offset:3072
	s_add_i32 vcc_lo, s27, 2
	s_add_u32 s30, s40, 0xfffc0080
	s_addc_u32 s42, s41, -1
	s_cmp_eq_u32 s17, s27
	s_cselect_b32 s45, s37, s42
	s_cselect_b32 s44, s36, s30
	s_cselect_b32 s43, s39, s21
	s_cselect_b32 s42, s38, s19
	v_lshl_add_u64 v[196:197], s[40:41], 0, v[174:175]
	s_add_i32 m0, s31, 0xc000
	ds_read_b128 v[144:147], v198
	ds_read_b128 v[148:151], v198 offset:1024
	ds_read_b128 v[180:183], v198 offset:2048
	ds_read_b128 v[184:187], v198 offset:3072
	ds_read_b128 v[188:191], v198 offset:4096
	ds_read_b128 v[192:195], v198 offset:5120
	ds_read_b128 v[202:205], v198 offset:6144
	ds_read_b128 v[206:209], v198 offset:7168
	global_load_lds_dwordx4 v[196:197], off
	s_add_i32 m0, s31, 0xe000
	v_lshl_add_u64 v[196:197], s[40:41], 0, v[176:177]
	global_load_lds_dwordx4 v[196:197], off
	s_waitcnt lgkmcnt(8)
	s_barrier
	s_waitcnt lgkmcnt(0)
	v_mfma_f32_16x16x32_bf16 v[124:127], v[128:131], v[144:147], v[124:127]
	v_mfma_f32_16x16x32_bf16 v[120:123], v[136:139], v[144:147], v[120:123]
	v_mfma_f32_16x16x32_bf16 v[108:111], v[128:131], v[180:183], v[108:111]
	v_mfma_f32_16x16x32_bf16 v[104:107], v[136:139], v[180:183], v[104:107]
	v_mfma_f32_16x16x32_bf16 v[92:95], v[128:131], v[188:191], v[92:95]
	v_mfma_f32_16x16x32_bf16 v[88:91], v[136:139], v[188:191], v[88:91]
	v_mfma_f32_16x16x32_bf16 v[76:79], v[128:131], v[202:205], v[76:79]
	v_mfma_f32_16x16x32_bf16 v[72:75], v[136:139], v[202:205], v[72:75]
	v_mfma_f32_16x16x32_bf16 v[124:127], v[132:135], v[148:151], v[124:127]
	v_mfma_f32_16x16x32_bf16 v[120:123], v[140:143], v[148:151], v[120:123]
	v_mfma_f32_16x16x32_bf16 v[108:111], v[132:135], v[184:187], v[108:111]
	v_mfma_f32_16x16x32_bf16 v[104:107], v[140:143], v[184:187], v[104:107]
	v_mfma_f32_16x16x32_bf16 v[92:95], v[132:135], v[192:195], v[92:95]
	v_mfma_f32_16x16x32_bf16 v[88:91], v[140:143], v[192:195], v[88:91]
	v_mfma_f32_16x16x32_bf16 v[76:79], v[132:135], v[206:209], v[76:79]
	v_mfma_f32_16x16x32_bf16 v[72:75], v[140:143], v[206:209], v[72:75]
	s_barrier
	s_add_i32 s27, s88, s29
	v_lshl_add_u64 v[196:197], s[42:43], 0, v[166:167]
	s_mov_b32 m0, s27
	ds_read_b128 v[210:213], v199
	ds_read_b128 v[214:217], v199 offset:1024
	ds_read_b128 v[218:221], v199 offset:2048
	ds_read_b128 v[222:225], v199 offset:3072
	global_load_lds_dwordx4 v[196:197], off
	s_add_i32 m0, s27, 0x2000
	v_lshl_add_u64 v[226:227], s[42:43], 0, v[170:171]
	global_load_lds_dwordx4 v[226:227], off
	s_barrier
	s_waitcnt lgkmcnt(0)
	v_mfma_f32_16x16x32_bf16 v[116:119], v[210:213], v[144:147], v[116:119]
	v_mfma_f32_16x16x32_bf16 v[112:115], v[218:221], v[144:147], v[112:115]
	v_mfma_f32_16x16x32_bf16 v[100:103], v[210:213], v[180:183], v[100:103]
	v_mfma_f32_16x16x32_bf16 v[96:99], v[218:221], v[180:183], v[96:99]
	v_mfma_f32_16x16x32_bf16 v[84:87], v[210:213], v[188:191], v[84:87]
	v_mfma_f32_16x16x32_bf16 v[80:83], v[218:221], v[188:191], v[80:83]
	v_mfma_f32_16x16x32_bf16 v[68:71], v[210:213], v[202:205], v[68:71]
	v_mfma_f32_16x16x32_bf16 v[64:67], v[218:221], v[202:205], v[64:67]
	v_mfma_f32_16x16x32_bf16 v[116:119], v[214:217], v[148:151], v[116:119]
	v_mfma_f32_16x16x32_bf16 v[112:115], v[222:225], v[148:151], v[112:115]
	v_mfma_f32_16x16x32_bf16 v[100:103], v[214:217], v[184:187], v[100:103]
	v_mfma_f32_16x16x32_bf16 v[96:99], v[222:225], v[184:187], v[96:99]
	v_mfma_f32_16x16x32_bf16 v[84:87], v[214:217], v[192:195], v[84:87]
	v_mfma_f32_16x16x32_bf16 v[80:83], v[222:225], v[192:195], v[80:83]
	v_mfma_f32_16x16x32_bf16 v[68:71], v[214:217], v[206:209], v[68:71]
	v_mfma_f32_16x16x32_bf16 v[64:67], v[222:225], v[206:209], v[64:67]
	s_mov_b32 m0, s31
	v_lshl_add_u64 v[228:229], s[44:45], 0, v[164:165]
	s_barrier
	ds_read_b128 v[144:147], v198 offset:16384
	ds_read_b128 v[148:151], v198 offset:17408
	ds_read_b128 v[180:183], v198 offset:18432
	ds_read_b128 v[184:187], v198 offset:19456
	ds_read_b128 v[188:191], v198 offset:20480
	ds_read_b128 v[192:195], v198 offset:21504
	ds_read_b128 v[202:205], v198 offset:22528
	ds_read_b128 v[206:209], v198 offset:23552
	global_load_lds_dwordx4 v[228:229], off
	s_mov_b32 m0, s33
	v_lshl_add_u64 v[230:231], s[44:45], 0, v[168:169]
	global_load_lds_dwordx4 v[230:231], off
	s_barrier
	s_waitcnt lgkmcnt(0)
	v_mfma_f32_16x16x32_bf16 v[60:63], v[128:131], v[144:147], v[60:63]
	v_mfma_f32_16x16x32_bf16 v[56:59], v[136:139], v[144:147], v[56:59]
	v_mfma_f32_16x16x32_bf16 v[44:47], v[128:131], v[180:183], v[44:47]
	v_mfma_f32_16x16x32_bf16 v[40:43], v[136:139], v[180:183], v[40:43]
	v_mfma_f32_16x16x32_bf16 v[28:31], v[128:131], v[188:191], v[28:31]
	v_mfma_f32_16x16x32_bf16 v[24:27], v[136:139], v[188:191], v[24:27]
	v_mfma_f32_16x16x32_bf16 v[12:15], v[128:131], v[202:205], v[12:15]
	v_mfma_f32_16x16x32_bf16 v[8:11], v[136:139], v[202:205], v[8:11]
	v_mfma_f32_16x16x32_bf16 v[60:63], v[132:135], v[148:151], v[60:63]
	v_mfma_f32_16x16x32_bf16 v[56:59], v[140:143], v[148:151], v[56:59]
	v_mfma_f32_16x16x32_bf16 v[44:47], v[132:135], v[184:187], v[44:47]
	v_mfma_f32_16x16x32_bf16 v[40:43], v[140:143], v[184:187], v[40:43]
	v_mfma_f32_16x16x32_bf16 v[28:31], v[132:135], v[192:195], v[28:31]
	v_mfma_f32_16x16x32_bf16 v[24:27], v[140:143], v[192:195], v[24:27]
	v_mfma_f32_16x16x32_bf16 v[12:15], v[132:135], v[206:209], v[12:15]
	v_mfma_f32_16x16x32_bf16 v[8:11], v[140:143], v[206:209], v[8:11]
	s_barrier
; #define PG8_STAGE(bufoff, gbase, voff) do { _Pragma("unroll") for (int _i = 0; _i < 2; ++_i) \
;         __builtin_amdgcn_global_load_lds((const unsigned*)((const char*)(gbase) + (voff)[_i]), (PG8_LAS unsigned*)(lds + (bufoff) + ldsw + _i * 8192), 16, 0, 0); } while (0)
; #define PG8_LDA(dst, b, h) do { _Pragma("unroll") for (int m = 0; m < 4; ++m) _Pragma("unroll") for (int k = 0; k < 2; ++k) dst[m][k] = *(const PG8_LAS bf16x8*)(lds + PG8_SA(b, h) + aoff + m * 2048 + k * 1024); } while (0)
; #define PG8_LDB(dst, b, h) do { _Pragma("unroll") for (int n = 0; n < 2; ++n) _Pragma("unroll") for (int k = 0; k < 2; ++k) dst[n][k] = *(const PG8_LAS bf16x8*)(lds + PG8_SB(b, h) + boff + n * 2048 + k * 1024); } while (0)
; #define PG8_MMA(ai, bj, At, Bt) do { __builtin_amdgcn_s_setprio(1); _Pragma("unroll") for (int m = 0; m < 4; ++m) _Pragma("unroll") for (int n = 0; n < 2; ++n) _Pragma("unroll") for (int k = 0; k < 2; ++k) \
;         acc[ai][bj][m][n] = __builtin_amdgcn_mfma_f32_16x16x32_bf16(Bt[n][k], At[m][k], acc[ai][bj][m][n], 0, 0, 0); __builtin_amdgcn_s_setprio(0); } while (0)
; #define PG8_WAIT_V(n) asm volatile("s_waitcnt vmcnt(" #n ")" ::: "memory")
; #define PG8_WAIT_L(n) asm volatile("s_waitcnt lgkmcnt(" #n ")" ::: "memory")
; #define PG8_BAR __builtin_amdgcn_s_barrier()
; #define PG8_SCHED __builtin_amdgcn_sched_barrier(0)
; template <class Epi, class Sched>
; __device__ __forceinline__ void gemm_phase(PG8_LAS unsigned char* lds, const Gemm g, const Sched& S, const Epi& E) {
;     ...
;             PG8_STAGE(PG8_SB(0, 1), b2 + hstep, voffB);
;             PG8_WAIT_V(6); PG8_BAR; PG8_MMA(1, 1, At, B1); PG8_BAR;
;             PG8_LDB(B0, 1, 0); PG8_SCHED; PG8_LDA(At, 1, 0); PG8_STAGE(PG8_SA(0, 1), a2 + hstep, voffA);
;             PG8_WAIT_L(8); PG8_BAR; PG8_WAIT_L(0); PG8_MMA(0, 0, At, B0); PG8_BAR; PG8_SCHED;
;             PG8_LDB(B1, 1, 1); PG8_STAGE(PG8_SB(1, 0), b3, voffB);
	s_add_u32 s96, s42, 0x40000
	s_addc_u32 s97, s43, 0
	s_add_i32 s27, s89, s29
	s_mov_b32 m0, s27
	v_lshl_add_u64 v[128:129], s[96:97], 0, v[166:167]
	global_load_lds_dwordx4 v[128:129], off
	s_add_i32 m0, s27, 0x2000
	v_lshl_add_u64 v[128:129], s[96:97], 0, v[170:171]
	global_load_lds_dwordx4 v[128:129], off
	s_waitcnt vmcnt(6)
	s_barrier
	v_mfma_f32_16x16x32_bf16 v[52:55], v[210:213], v[144:147], v[52:55]
	v_mfma_f32_16x16x32_bf16 v[48:51], v[218:221], v[144:147], v[48:51]
	v_mfma_f32_16x16x32_bf16 v[36:39], v[210:213], v[180:183], v[36:39]
	v_mfma_f32_16x16x32_bf16 v[32:35], v[218:221], v[180:183], v[32:35]
	v_mfma_f32_16x16x32_bf16 v[20:23], v[210:213], v[188:191], v[20:23]
	v_mfma_f32_16x16x32_bf16 v[16:19], v[218:221], v[188:191], v[16:19]
	v_mfma_f32_16x16x32_bf16 v[4:7], v[210:213], v[202:205], v[4:7]
	v_mfma_f32_16x16x32_bf16 v[0:3], v[218:221], v[202:205], v[0:3]
	v_mfma_f32_16x16x32_bf16 v[52:55], v[214:217], v[148:151], v[52:55]
	v_mfma_f32_16x16x32_bf16 v[48:51], v[222:225], v[148:151], v[48:51]
	v_mfma_f32_16x16x32_bf16 v[36:39], v[214:217], v[184:187], v[36:39]
	v_mfma_f32_16x16x32_bf16 v[32:35], v[222:225], v[184:187], v[32:35]
	v_mfma_f32_16x16x32_bf16 v[20:23], v[214:217], v[192:195], v[20:23]
	v_mfma_f32_16x16x32_bf16 v[16:19], v[222:225], v[192:195], v[16:19]
	v_mfma_f32_16x16x32_bf16 v[4:7], v[214:217], v[206:209], v[4:7]
	v_mfma_f32_16x16x32_bf16 v[0:3], v[222:225], v[206:209], v[0:3]
	s_add_i32 s27, 0, 0x18000
	v_add_u32_e32 v140, s27, v159
	s_barrier
	ds_read_b128 v[128:131], v140
	ds_read_b128 v[132:135], v140 offset:1024
	ds_read_b128 v[136:139], v140 offset:2048
	ds_read_b128 v[140:143], v140 offset:3072
	s_add_u32 s44, s44, 0x40000
	s_addc_u32 s45, s45, 0
	s_mov_b32 m0, s34
	v_lshl_add_u64 v[210:211], s[44:45], 0, v[164:165]
	ds_read_b128 v[144:147], v198 offset:32768
	ds_read_b128 v[148:151], v198 offset:33792
	ds_read_b128 v[180:183], v198 offset:34816
	ds_read_b128 v[184:187], v198 offset:35840
	ds_read_b128 v[188:191], v198 offset:36864
	ds_read_b128 v[192:195], v198 offset:37888
	ds_read_b128 v[202:205], v198 offset:38912
	ds_read_b128 v[206:209], v198 offset:39936
	global_load_lds_dwordx4 v[210:211], off
	s_mov_b32 m0, s35
	v_lshl_add_u64 v[210:211], s[44:45], 0, v[168:169]
	global_load_lds_dwordx4 v[210:211], off
	s_waitcnt lgkmcnt(8)
	s_barrier
	s_waitcnt lgkmcnt(0)
	v_mfma_f32_16x16x32_bf16 v[124:127], v[128:131], v[144:147], v[124:127]
	v_mfma_f32_16x16x32_bf16 v[120:123], v[136:139], v[144:147], v[120:123]
	v_mfma_f32_16x16x32_bf16 v[108:111], v[128:131], v[180:183], v[108:111]
	v_mfma_f32_16x16x32_bf16 v[104:107], v[136:139], v[180:183], v[104:107]
	v_mfma_f32_16x16x32_bf16 v[92:95], v[128:131], v[188:191], v[92:95]
	v_mfma_f32_16x16x32_bf16 v[88:91], v[136:139], v[188:191], v[88:91]
	v_mfma_f32_16x16x32_bf16 v[76:79], v[128:131], v[202:205], v[76:79]
	v_mfma_f32_16x16x32_bf16 v[72:75], v[136:139], v[202:205], v[72:75]
	v_mfma_f32_16x16x32_bf16 v[124:127], v[132:135], v[148:151], v[124:127]
	v_mfma_f32_16x16x32_bf16 v[120:123], v[140:143], v[148:151], v[120:123]
	v_mfma_f32_16x16x32_bf16 v[108:111], v[132:135], v[184:187], v[108:111]
	v_mfma_f32_16x16x32_bf16 v[104:107], v[140:143], v[184:187], v[104:107]
	v_mfma_f32_16x16x32_bf16 v[92:95], v[132:135], v[192:195], v[92:95]
	v_mfma_f32_16x16x32_bf16 v[88:91], v[140:143], v[192:195], v[88:91]
	v_mfma_f32_16x16x32_bf16 v[76:79], v[132:135], v[206:209], v[76:79]
	v_mfma_f32_16x16x32_bf16 v[72:75], v[140:143], v[206:209], v[72:75]
	s_barrier
	s_add_i32 s30, 0, 0x1c000
	s_add_i32 s27, s27, s29
	v_add_u32_e32 v201, s30, v159
	v_lshl_add_u64 v[196:197], v[196:197], 0, s[10:11]
	s_mov_b32 m0, s27
	ds_read_b128 v[210:213], v201
	ds_read_b128 v[214:217], v201 offset:1024
	ds_read_b128 v[218:221], v201 offset:2048
	ds_read_b128 v[222:225], v201 offset:3072
	global_load_lds_dwordx4 v[196:197], off
	s_add_i32 m0, s27, 0x2000
	v_lshl_add_u64 v[196:197], v[226:227], 0, s[10:11]
	global_load_lds_dwordx4 v[196:197], off
	s_barrier
; #define PG8_STAGE(bufoff, gbase, voff) do { _Pragma("unroll") for (int _i = 0; _i < 2; ++_i) \
;         __builtin_amdgcn_global_load_lds((const unsigned*)((const char*)(gbase) + (voff)[_i]), (PG8_LAS unsigned*)(lds + (bufoff) + ldsw + _i * 8192), 16, 0, 0); } while (0)
; #define PG8_LDA(dst, b, h) do { _Pragma("unroll") for (int m = 0; m < 4; ++m) _Pragma("unroll") for (int k = 0; k < 2; ++k) dst[m][k] = *(const PG8_LAS bf16x8*)(lds + PG8_SA(b, h) + aoff + m * 2048 + k * 1024); } while (0)
; #define PG8_MMA(ai, bj, At, Bt) do { __builtin_amdgcn_s_setprio(1); _Pragma("unroll") for (int m = 0; m < 4; ++m) _Pragma("unroll") for (int n = 0; n < 2; ++n) _Pragma("unroll") for (int k = 0; k < 2; ++k) \
;         acc[ai][bj][m][n] = __builtin_amdgcn_mfma_f32_16x16x32_bf16(Bt[n][k], At[m][k], acc[ai][bj][m][n], 0, 0, 0); __builtin_amdgcn_s_setprio(0); } while (0)
; #define PG8_WAIT_V(n) asm volatile("s_waitcnt vmcnt(" #n ")" ::: "memory")
; #define PG8_WAIT_L(n) asm volatile("s_waitcnt lgkmcnt(" #n ")" ::: "memory")
; #define PG8_BAR __builtin_amdgcn_s_barrier()
; #define PG8_SCHED __builtin_amdgcn_sched_barrier(0)
; template <class Epi, class Sched>
; __device__ __forceinline__ void gemm_phase(PG8_LAS unsigned char* lds, const Gemm g, const Sched& S, const Epi& E) {
;     ...
;             PG8_BAR; PG8_WAIT_L(0); PG8_MMA(0, 1, At, B1); PG8_BAR;
;             PG8_LDA(At, 1, 1); PG8_STAGE(PG8_SA(1, 0), a3, voffA);
;             PG8_BAR; PG8_WAIT_L(0); PG8_MMA(1, 0, At, B0); PG8_BAR; PG8_SCHED;
;             PG8_STAGE(PG8_SB(1, 1), b3 + hstep, voffB);
;             PG8_WAIT_V(6); PG8_BAR; PG8_MMA(1, 1, At, B1); PG8_BAR;
;         }
;         if constexpr (!Epi::AFTER_DRAIN) {
;             if (cur.part < 0) E(acc, cur, wr, wc, fr, fq, pre);
	s_waitcnt lgkmcnt(0)
	v_mfma_f32_16x16x32_bf16 v[116:119], v[210:213], v[144:147], v[116:119]
	v_mfma_f32_16x16x32_bf16 v[112:115], v[218:221], v[144:147], v[112:115]
	v_mfma_f32_16x16x32_bf16 v[100:103], v[210:213], v[180:183], v[100:103]
	v_mfma_f32_16x16x32_bf16 v[96:99], v[218:221], v[180:183], v[96:99]
	v_mfma_f32_16x16x32_bf16 v[84:87], v[210:213], v[188:191], v[84:87]
	v_mfma_f32_16x16x32_bf16 v[80:83], v[218:221], v[188:191], v[80:83]
	v_mfma_f32_16x16x32_bf16 v[68:71], v[210:213], v[202:205], v[68:71]
	v_mfma_f32_16x16x32_bf16 v[64:67], v[218:221], v[202:205], v[64:67]
	v_mfma_f32_16x16x32_bf16 v[116:119], v[214:217], v[148:151], v[116:119]
	v_mfma_f32_16x16x32_bf16 v[112:115], v[222:225], v[148:151], v[112:115]
	v_mfma_f32_16x16x32_bf16 v[100:103], v[214:217], v[184:187], v[100:103]
	v_mfma_f32_16x16x32_bf16 v[96:99], v[222:225], v[184:187], v[96:99]
	v_mfma_f32_16x16x32_bf16 v[84:87], v[214:217], v[192:195], v[84:87]
	v_mfma_f32_16x16x32_bf16 v[80:83], v[222:225], v[192:195], v[80:83]
	v_mfma_f32_16x16x32_bf16 v[68:71], v[214:217], v[206:209], v[68:71]
	v_mfma_f32_16x16x32_bf16 v[64:67], v[222:225], v[206:209], v[64:67]
	s_mov_b32 m0, s47
	v_lshl_add_u64 v[196:197], v[228:229], 0, s[10:11]
	s_barrier
	ds_read_b128 v[144:147], v198 offset:49152
	ds_read_b128 v[148:151], v198 offset:50176
	ds_read_b128 v[180:183], v198 offset:51200
	ds_read_b128 v[184:187], v198 offset:52224
	ds_read_b128 v[188:191], v198 offset:53248
	ds_read_b128 v[192:195], v198 offset:54272
	ds_read_b128 v[202:205], v198 offset:55296
	ds_read_b128 v[206:209], v198 offset:56320
	global_load_lds_dwordx4 v[196:197], off
	s_mov_b32 m0, s48
	v_lshl_add_u64 v[196:197], v[230:231], 0, s[10:11]
	global_load_lds_dwordx4 v[196:197], off
	s_barrier
	s_waitcnt lgkmcnt(0)
	v_mfma_f32_16x16x32_bf16 v[60:63], v[128:131], v[144:147], v[60:63]
	v_mfma_f32_16x16x32_bf16 v[56:59], v[136:139], v[144:147], v[56:59]
	v_mfma_f32_16x16x32_bf16 v[44:47], v[128:131], v[180:183], v[44:47]
	v_mfma_f32_16x16x32_bf16 v[40:43], v[136:139], v[180:183], v[40:43]
	v_mfma_f32_16x16x32_bf16 v[28:31], v[128:131], v[188:191], v[28:31]
	v_mfma_f32_16x16x32_bf16 v[24:27], v[136:139], v[188:191], v[24:27]
	v_mfma_f32_16x16x32_bf16 v[12:15], v[128:131], v[202:205], v[12:15]
	v_mfma_f32_16x16x32_bf16 v[8:11], v[136:139], v[202:205], v[8:11]
	v_mfma_f32_16x16x32_bf16 v[60:63], v[132:135], v[148:151], v[60:63]
	v_mfma_f32_16x16x32_bf16 v[56:59], v[140:143], v[148:151], v[56:59]
	v_mfma_f32_16x16x32_bf16 v[44:47], v[132:135], v[184:187], v[44:47]
	v_mfma_f32_16x16x32_bf16 v[40:43], v[140:143], v[184:187], v[40:43]
	v_mfma_f32_16x16x32_bf16 v[28:31], v[132:135], v[192:195], v[28:31]
	v_mfma_f32_16x16x32_bf16 v[24:27], v[140:143], v[192:195], v[24:27]
	v_mfma_f32_16x16x32_bf16 v[12:15], v[132:135], v[206:209], v[12:15]
	v_mfma_f32_16x16x32_bf16 v[8:11], v[140:143], v[206:209], v[8:11]
	s_barrier
	s_add_u32 s42, s42, 0x40080
	s_addc_u32 s43, s43, 0
	s_add_i32 s27, s30, s29
	s_mov_b32 m0, s27
	v_lshl_add_u64 v[128:129], s[42:43], 0, v[166:167]
	global_load_lds_dwordx4 v[128:129], off
	s_add_i32 m0, s27, 0x2000
	v_lshl_add_u64 v[128:129], s[42:43], 0, v[170:171]
	global_load_lds_dwordx4 v[128:129], off
	s_waitcnt vmcnt(6)
	s_barrier
	v_mfma_f32_16x16x32_bf16 v[52:55], v[210:213], v[144:147], v[52:55]
	v_mfma_f32_16x16x32_bf16 v[48:51], v[218:221], v[144:147], v[48:51]
	v_mfma_f32_16x16x32_bf16 v[36:39], v[210:213], v[180:183], v[36:39]
	v_mfma_f32_16x16x32_bf16 v[32:35], v[218:221], v[180:183], v[32:35]
	v_mfma_f32_16x16x32_bf16 v[20:23], v[210:213], v[188:191], v[20:23]
	v_mfma_f32_16x16x32_bf16 v[16:19], v[218:221], v[188:191], v[16:19]
	v_mfma_f32_16x16x32_bf16 v[4:7], v[210:213], v[202:205], v[4:7]
	v_mfma_f32_16x16x32_bf16 v[0:3], v[218:221], v[202:205], v[0:3]
	v_mfma_f32_16x16x32_bf16 v[52:55], v[214:217], v[148:151], v[52:55]
	v_mfma_f32_16x16x32_bf16 v[48:51], v[222:225], v[148:151], v[48:51]
	v_mfma_f32_16x16x32_bf16 v[36:39], v[214:217], v[184:187], v[36:39]
	v_mfma_f32_16x16x32_bf16 v[32:35], v[222:225], v[184:187], v[32:35]
	v_mfma_f32_16x16x32_bf16 v[20:23], v[214:217], v[192:195], v[20:23]
	v_mfma_f32_16x16x32_bf16 v[16:19], v[222:225], v[192:195], v[16:19]
	v_mfma_f32_16x16x32_bf16 v[4:7], v[214:217], v[206:209], v[4:7]
	v_mfma_f32_16x16x32_bf16 v[0:3], v[222:225], v[206:209], v[0:3]
	s_add_u32 s40, s40, 0x100
	s_addc_u32 s41, s41, 0
	s_add_u32 s19, s19, 0x100
	s_addc_u32 s21, s21, 0
	s_cmp_ge_i32 vcc_lo, s15
	s_mov_b32 s27, vcc_lo
	s_barrier
	s_cbranch_scc0 .LBB0_1313
	s_cmp_gt_i32 s8, -1
	s_mov_b64 s[40:41], -1
	s_cbranch_scc0 .LBB0_1316

; #define PG8_STAGE(bufoff, gbase, voff) do { _Pragma("unroll") for (int _i = 0; _i < 2; ++_i) \
;         __builtin_amdgcn_global_load_lds((const unsigned*)((const char*)(gbase) + (voff)[_i]), (PG8_LAS unsigned*)(lds + (bufoff) + ldsw + _i * 8192), 16, 0, 0); } while (0)
; #define PG8_LDA(dst, b, h) do { _Pragma("unroll") for (int m = 0; m < 4; ++m) _Pragma("unroll") for (int k = 0; k < 2; ++k) dst[m][k] = *(const PG8_LAS bf16x8*)(lds + PG8_SA(b, h) + aoff + m * 2048 + k * 1024); } while (0)
; #define PG8_LDB(dst, b, h) do { _Pragma("unroll") for (int n = 0; n < 2; ++n) _Pragma("unroll") for (int k = 0; k < 2; ++k) dst[n][k] = *(const PG8_LAS bf16x8*)(lds + PG8_SB(b, h) + boff + n * 2048 + k * 1024); } while (0)
; #define PG8_MMA(ai, bj, At, Bt) do { __builtin_amdgcn_s_setprio(1); _Pragma("unroll") for (int m = 0; m < 4; ++m) _Pragma("unroll") for (int n = 0; n < 2; ++n) _Pragma("unroll") for (int k = 0; k < 2; ++k) \
;         acc[ai][bj][m][n] = __builtin_amdgcn_mfma_f32_16x16x32_bf16(Bt[n][k], At[m][k], acc[ai][bj][m][n], 0, 0, 0); __builtin_amdgcn_s_setprio(0); } while (0)
; #define PG8_WAIT_L(n) asm volatile("s_waitcnt lgkmcnt(" #n ")" ::: "memory")
; #define PG8_BAR __builtin_amdgcn_s_barrier()
; #define PG8_SCHED __builtin_amdgcn_sched_barrier(0)
; template <class Epi, class Sched>
; __device__ __forceinline__ void gemm_phase(PG8_LAS unsigned char* lds, const Gemm g, const Sched& S, const Epi& E) {
;     ...
;             const bool last = (t == cnk - 2);
;             const char* a1 = cA + (size_t)(t + 1) * kstep;
;             const char* a2 = last ? nA : cA + (size_t)(t + 2) * kstep; const char* b2 = last ? nB : cB + (size_t)(t + 2) * kstep;
;             const char* a3 = a2 + kstep; const char* b3 = b2 + kstep;
;             if (last && has_next) S.a_ready(nxt);
;             if (last) E.prefetch(pre, cur, wr, fr);
;             PG8_LDB(B0, 0, 0); PG8_SCHED; PG8_LDA(At, 0, 0); PG8_STAGE(PG8_SA(1, 1), a1 + hstep, voffA);
;             PG8_WAIT_L(8); PG8_BAR; PG8_WAIT_L(0); PG8_MMA(0, 0, At, B0); PG8_BAR; PG8_SCHED;
;             PG8_LDB(B1, 0, 1); PG8_STAGE(PG8_SB(0, 0), b2, voffB);
;             PG8_BAR; PG8_WAIT_L(0); PG8_MMA(0, 1, At, B1); PG8_BAR;
;             PG8_LDA(At, 0, 1); PG8_STAGE(PG8_SA(0, 0), a2, voffA);
;             PG8_BAR; PG8_WAIT_L(0); PG8_MMA(1, 0, At, B0); PG8_BAR; PG8_SCHED;
.LBB0_1509:
	v_add_u32_e32 v142, s33, v159
	ds_read_b128 v[130:133], v142
	ds_read_b128 v[134:137], v142 offset:1024
	ds_read_b128 v[138:141], v142 offset:2048
	ds_read_b128 v[142:145], v142 offset:3072
	s_add_u32 s30, s4, 0xfffc0080
	s_addc_u32 s40, s5, -1
	s_and_b64 s[38:39], s[38:39], exec
	s_cselect_b32 s41, s23, s40
	s_cselect_b32 s40, s43, s30
	s_cselect_b32 s39, s21, s46
	s_cselect_b32 s38, s44, s45
	v_lshl_add_u64 v[150:151], s[4:5], 0, v[174:175]
	s_add_i32 m0, s16, 0xc000
	ds_read_b128 v[146:149], v163
	ds_read_b128 v[192:195], v163 offset:1024
	ds_read_b128 v[196:199], v163 offset:2048
	ds_read_b128 v[200:203], v163 offset:3072
	ds_read_b128 v[206:209], v163 offset:4096
	ds_read_b128 v[210:213], v163 offset:5120
	ds_read_b128 v[214:217], v163 offset:6144
	ds_read_b128 v[218:221], v163 offset:7168
	global_load_lds_dwordx4 v[150:151], off
	s_add_i32 m0, s16, 0xe000
	v_lshl_add_u64 v[150:151], s[4:5], 0, v[176:177]
	global_load_lds_dwordx4 v[150:151], off
	s_waitcnt lgkmcnt(8)
	s_barrier
	s_waitcnt lgkmcnt(0)
	v_mfma_f32_16x16x32_bf16 v[124:127], v[130:133], v[146:149], v[124:127]
	v_mfma_f32_16x16x32_bf16 v[120:123], v[138:141], v[146:149], v[120:123]
	v_mfma_f32_16x16x32_bf16 v[108:111], v[130:133], v[196:199], v[108:111]
	v_mfma_f32_16x16x32_bf16 v[104:107], v[138:141], v[196:199], v[104:107]
	v_mfma_f32_16x16x32_bf16 v[92:95], v[130:133], v[206:209], v[92:95]
	v_mfma_f32_16x16x32_bf16 v[88:91], v[138:141], v[206:209], v[88:91]
	v_mfma_f32_16x16x32_bf16 v[76:79], v[130:133], v[214:217], v[76:79]
	v_mfma_f32_16x16x32_bf16 v[72:75], v[138:141], v[214:217], v[72:75]
	v_mfma_f32_16x16x32_bf16 v[124:127], v[134:137], v[192:195], v[124:127]
	v_mfma_f32_16x16x32_bf16 v[120:123], v[142:145], v[192:195], v[120:123]
	v_mfma_f32_16x16x32_bf16 v[108:111], v[134:137], v[200:203], v[108:111]
	v_mfma_f32_16x16x32_bf16 v[104:107], v[142:145], v[200:203], v[104:107]
	v_mfma_f32_16x16x32_bf16 v[92:95], v[134:137], v[210:213], v[92:95]
	v_mfma_f32_16x16x32_bf16 v[88:91], v[142:145], v[210:213], v[88:91]
	v_mfma_f32_16x16x32_bf16 v[76:79], v[134:137], v[218:221], v[76:79]
	v_mfma_f32_16x16x32_bf16 v[72:75], v[142:145], v[218:221], v[72:75]
	s_barrier
	v_add_u32_e32 v150, s34, v159
	s_add_i32 s30, s33, s3
	ds_read_b128 v[222:225], v150
	ds_read_b128 v[226:229], v150 offset:1024
	ds_read_b128 v[230:233], v150 offset:2048
	ds_read_b128 v[234:237], v150 offset:3072
	v_lshl_add_u64 v[150:151], s[38:39], 0, v[168:169]
	s_mov_b32 m0, s30
	v_lshl_add_u64 v[238:239], s[38:39], 0, v[164:165]
	global_load_lds_dwordx4 v[150:151], off
	s_add_i32 m0, s30, 0x2000
	s_nop 0
	global_load_lds_dwordx4 v[238:239], off
	s_barrier
	s_waitcnt lgkmcnt(0)
	v_mfma_f32_16x16x32_bf16 v[116:119], v[222:225], v[146:149], v[116:119]
	v_mfma_f32_16x16x32_bf16 v[112:115], v[230:233], v[146:149], v[112:115]
	v_mfma_f32_16x16x32_bf16 v[100:103], v[222:225], v[196:199], v[100:103]
	v_mfma_f32_16x16x32_bf16 v[96:99], v[230:233], v[196:199], v[96:99]
	v_mfma_f32_16x16x32_bf16 v[84:87], v[222:225], v[206:209], v[84:87]
	v_mfma_f32_16x16x32_bf16 v[80:83], v[230:233], v[206:209], v[80:83]
	v_mfma_f32_16x16x32_bf16 v[68:71], v[222:225], v[214:217], v[68:71]
	v_mfma_f32_16x16x32_bf16 v[64:67], v[230:233], v[214:217], v[64:67]
	v_mfma_f32_16x16x32_bf16 v[116:119], v[226:229], v[192:195], v[116:119]
	v_mfma_f32_16x16x32_bf16 v[112:115], v[234:237], v[192:195], v[112:115]
	v_mfma_f32_16x16x32_bf16 v[100:103], v[226:229], v[200:203], v[100:103]
	v_mfma_f32_16x16x32_bf16 v[96:99], v[234:237], v[200:203], v[96:99]
	v_mfma_f32_16x16x32_bf16 v[84:87], v[226:229], v[210:213], v[84:87]
	v_mfma_f32_16x16x32_bf16 v[80:83], v[234:237], v[210:213], v[80:83]
	v_mfma_f32_16x16x32_bf16 v[68:71], v[226:229], v[218:221], v[68:71]
	v_mfma_f32_16x16x32_bf16 v[64:67], v[234:237], v[218:221], v[64:67]
	s_mov_b32 m0, s16
	v_lshl_add_u64 v[240:241], s[40:41], 0, v[170:171]
	s_barrier
	ds_read_b128 v[146:149], v163 offset:16384
	ds_read_b128 v[192:195], v163 offset:17408
	ds_read_b128 v[196:199], v163 offset:18432
	ds_read_b128 v[200:203], v163 offset:19456
	ds_read_b128 v[206:209], v163 offset:20480
	ds_read_b128 v[210:213], v163 offset:21504
	ds_read_b128 v[214:217], v163 offset:22528
	ds_read_b128 v[218:221], v163 offset:23552
	global_load_lds_dwordx4 v[240:241], off
	s_mov_b32 m0, s17
	v_lshl_add_u64 v[242:243], s[40:41], 0, v[166:167]
	global_load_lds_dwordx4 v[242:243], off
	s_barrier
	s_waitcnt lgkmcnt(0)
	v_mfma_f32_16x16x32_bf16 v[60:63], v[130:133], v[146:149], v[60:63]
	v_mfma_f32_16x16x32_bf16 v[56:59], v[138:141], v[146:149], v[56:59]
	v_mfma_f32_16x16x32_bf16 v[44:47], v[130:133], v[196:199], v[44:47]
	v_mfma_f32_16x16x32_bf16 v[40:43], v[138:141], v[196:199], v[40:43]
	v_mfma_f32_16x16x32_bf16 v[28:31], v[130:133], v[206:209], v[28:31]
	v_mfma_f32_16x16x32_bf16 v[24:27], v[138:141], v[206:209], v[24:27]
	v_mfma_f32_16x16x32_bf16 v[12:15], v[130:133], v[214:217], v[12:15]
	v_mfma_f32_16x16x32_bf16 v[8:11], v[138:141], v[214:217], v[8:11]
	v_mfma_f32_16x16x32_bf16 v[60:63], v[134:137], v[192:195], v[60:63]
	v_mfma_f32_16x16x32_bf16 v[56:59], v[142:145], v[192:195], v[56:59]
	v_mfma_f32_16x16x32_bf16 v[44:47], v[134:137], v[200:203], v[44:47]
	v_mfma_f32_16x16x32_bf16 v[40:43], v[142:145], v[200:203], v[40:43]
	v_mfma_f32_16x16x32_bf16 v[28:31], v[134:137], v[210:213], v[28:31]
	v_mfma_f32_16x16x32_bf16 v[24:27], v[142:145], v[210:213], v[24:27]
	v_mfma_f32_16x16x32_bf16 v[12:15], v[134:137], v[218:221], v[12:15]
	v_mfma_f32_16x16x32_bf16 v[8:11], v[142:145], v[218:221], v[8:11]
	s_barrier
; #define PG8_STAGE(bufoff, gbase, voff) do { _Pragma("unroll") for (int _i = 0; _i < 2; ++_i) \
;         __builtin_amdgcn_global_load_lds((const unsigned*)((const char*)(gbase) + (voff)[_i]), (PG8_LAS unsigned*)(lds + (bufoff) + ldsw + _i * 8192), 16, 0, 0); } while (0)
; #define PG8_LDA(dst, b, h) do { _Pragma("unroll") for (int m = 0; m < 4; ++m) _Pragma("unroll") for (int k = 0; k < 2; ++k) dst[m][k] = *(const PG8_LAS bf16x8*)(lds + PG8_SA(b, h) + aoff + m * 2048 + k * 1024); } while (0)
; #define PG8_LDB(dst, b, h) do { _Pragma("unroll") for (int n = 0; n < 2; ++n) _Pragma("unroll") for (int k = 0; k < 2; ++k) dst[n][k] = *(const PG8_LAS bf16x8*)(lds + PG8_SB(b, h) + boff + n * 2048 + k * 1024); } while (0)
; #define PG8_MMA(ai, bj, At, Bt) do { __builtin_amdgcn_s_setprio(1); _Pragma("unroll") for (int m = 0; m < 4; ++m) _Pragma("unroll") for (int n = 0; n < 2; ++n) _Pragma("unroll") for (int k = 0; k < 2; ++k) \
;         acc[ai][bj][m][n] = __builtin_amdgcn_mfma_f32_16x16x32_bf16(Bt[n][k], At[m][k], acc[ai][bj][m][n], 0, 0, 0); __builtin_amdgcn_s_setprio(0); } while (0)
; #define PG8_WAIT_V(n) asm volatile("s_waitcnt vmcnt(" #n ")" ::: "memory")
; #define PG8_WAIT_L(n) asm volatile("s_waitcnt lgkmcnt(" #n ")" ::: "memory")
; #define PG8_BAR __builtin_amdgcn_s_barrier()
; #define PG8_SCHED __builtin_amdgcn_sched_barrier(0)
; template <class Epi, class Sched>
; __device__ __forceinline__ void gemm_phase(PG8_LAS unsigned char* lds, const Gemm g, const Sched& S, const Epi& E) {
;     ...
;             PG8_STAGE(PG8_SB(0, 1), b2 + hstep, voffB);
;             PG8_WAIT_V(6); PG8_BAR; PG8_MMA(1, 1, At, B1); PG8_BAR;
;             PG8_LDB(B0, 1, 0); PG8_SCHED; PG8_LDA(At, 1, 0); PG8_STAGE(PG8_SA(0, 1), a2 + hstep, voffA);
;             PG8_WAIT_L(8); PG8_BAR; PG8_WAIT_L(0); PG8_MMA(0, 0, At, B0); PG8_BAR; PG8_SCHED;
;             PG8_LDB(B1, 1, 1); PG8_STAGE(PG8_SB(1, 0), b3, voffB);
	s_add_u32 s48, s38, 0x40000
	s_addc_u32 s49, s39, 0
	s_add_i32 s30, s34, s3
	s_mov_b32 m0, s30
	v_lshl_add_u64 v[130:131], s[48:49], 0, v[168:169]
	global_load_lds_dwordx4 v[130:131], off
	s_add_i32 m0, s30, 0x2000
	v_lshl_add_u64 v[130:131], s[48:49], 0, v[164:165]
	global_load_lds_dwordx4 v[130:131], off
	s_waitcnt vmcnt(6)
	s_barrier
	v_mfma_f32_16x16x32_bf16 v[52:55], v[222:225], v[146:149], v[52:55]
	v_mfma_f32_16x16x32_bf16 v[48:51], v[230:233], v[146:149], v[48:51]
	v_mfma_f32_16x16x32_bf16 v[36:39], v[222:225], v[196:199], v[36:39]
	v_mfma_f32_16x16x32_bf16 v[32:35], v[230:233], v[196:199], v[32:35]
	v_mfma_f32_16x16x32_bf16 v[20:23], v[222:225], v[206:209], v[20:23]
	v_mfma_f32_16x16x32_bf16 v[16:19], v[230:233], v[206:209], v[16:19]
	v_mfma_f32_16x16x32_bf16 v[4:7], v[222:225], v[214:217], v[4:7]
	v_mfma_f32_16x16x32_bf16 v[0:3], v[230:233], v[214:217], v[0:3]
	v_mfma_f32_16x16x32_bf16 v[52:55], v[226:229], v[192:195], v[52:55]
	v_mfma_f32_16x16x32_bf16 v[48:51], v[234:237], v[192:195], v[48:51]
	v_mfma_f32_16x16x32_bf16 v[36:39], v[226:229], v[200:203], v[36:39]
	v_mfma_f32_16x16x32_bf16 v[32:35], v[234:237], v[200:203], v[32:35]
	v_mfma_f32_16x16x32_bf16 v[20:23], v[226:229], v[210:213], v[20:23]
	v_mfma_f32_16x16x32_bf16 v[16:19], v[234:237], v[210:213], v[16:19]
	v_mfma_f32_16x16x32_bf16 v[4:7], v[226:229], v[218:221], v[4:7]
	v_mfma_f32_16x16x32_bf16 v[0:3], v[234:237], v[218:221], v[0:3]
	s_add_i32 s30, 0, 0x18000
	v_add_u32_e32 v142, s30, v159
	s_barrier
	ds_read_b128 v[130:133], v142
	ds_read_b128 v[134:137], v142 offset:1024
	ds_read_b128 v[138:141], v142 offset:2048
	ds_read_b128 v[142:145], v142 offset:3072
	s_add_u32 s40, s40, 0x40000
	s_addc_u32 s41, s41, 0
	s_mov_b32 m0, s18
	v_lshl_add_u64 v[222:223], s[40:41], 0, v[170:171]
	ds_read_b128 v[146:149], v163 offset:32768
	ds_read_b128 v[192:195], v163 offset:33792
	ds_read_b128 v[196:199], v163 offset:34816
	ds_read_b128 v[200:203], v163 offset:35840
	ds_read_b128 v[206:209], v163 offset:36864
	ds_read_b128 v[210:213], v163 offset:37888
	ds_read_b128 v[214:217], v163 offset:38912
	ds_read_b128 v[218:221], v163 offset:39936
	global_load_lds_dwordx4 v[222:223], off
	s_mov_b32 m0, s19
	v_lshl_add_u64 v[222:223], s[40:41], 0, v[166:167]
	global_load_lds_dwordx4 v[222:223], off
	s_waitcnt lgkmcnt(8)
	s_barrier
	s_waitcnt lgkmcnt(0)
	v_mfma_f32_16x16x32_bf16 v[124:127], v[130:133], v[146:149], v[124:127]
	v_mfma_f32_16x16x32_bf16 v[120:123], v[138:141], v[146:149], v[120:123]
	v_mfma_f32_16x16x32_bf16 v[108:111], v[130:133], v[196:199], v[108:111]
	v_mfma_f32_16x16x32_bf16 v[104:107], v[138:141], v[196:199], v[104:107]
	v_mfma_f32_16x16x32_bf16 v[92:95], v[130:133], v[206:209], v[92:95]
	v_mfma_f32_16x16x32_bf16 v[88:91], v[138:141], v[206:209], v[88:91]
	v_mfma_f32_16x16x32_bf16 v[76:79], v[130:133], v[214:217], v[76:79]
	v_mfma_f32_16x16x32_bf16 v[72:75], v[138:141], v[214:217], v[72:75]
	v_mfma_f32_16x16x32_bf16 v[124:127], v[134:137], v[192:195], v[124:127]
	v_mfma_f32_16x16x32_bf16 v[120:123], v[142:145], v[192:195], v[120:123]
	v_mfma_f32_16x16x32_bf16 v[108:111], v[134:137], v[200:203], v[108:111]
	v_mfma_f32_16x16x32_bf16 v[104:107], v[142:145], v[200:203], v[104:107]
	v_mfma_f32_16x16x32_bf16 v[92:95], v[134:137], v[210:213], v[92:95]
	v_mfma_f32_16x16x32_bf16 v[88:91], v[142:145], v[210:213], v[88:91]
	v_mfma_f32_16x16x32_bf16 v[76:79], v[134:137], v[218:221], v[76:79]
	v_mfma_f32_16x16x32_bf16 v[72:75], v[142:145], v[218:221], v[72:75]
	s_barrier
	s_add_i32 s40, 0, 0x1c000
	s_add_i32 s30, s30, s3
	v_add_u32_e32 v205, s40, v159
	v_lshl_add_u64 v[150:151], v[150:151], 0, s[8:9]
	s_mov_b32 m0, s30
	ds_read_b128 v[222:225], v205
	ds_read_b128 v[226:229], v205 offset:1024
	ds_read_b128 v[230:233], v205 offset:2048
	ds_read_b128 v[234:237], v205 offset:3072
	global_load_lds_dwordx4 v[150:151], off
	s_add_i32 m0, s30, 0x2000
	v_lshl_add_u64 v[150:151], v[238:239], 0, s[8:9]
	global_load_lds_dwordx4 v[150:151], off
	s_barrier
; #define PG8_STAGE(bufoff, gbase, voff) do { _Pragma("unroll") for (int _i = 0; _i < 2; ++_i) \
;         __builtin_amdgcn_global_load_lds((const unsigned*)((const char*)(gbase) + (voff)[_i]), (PG8_LAS unsigned*)(lds + (bufoff) + ldsw + _i * 8192), 16, 0, 0); } while (0)
; #define PG8_LDA(dst, b, h) do { _Pragma("unroll") for (int m = 0; m < 4; ++m) _Pragma("unroll") for (int k = 0; k < 2; ++k) dst[m][k] = *(const PG8_LAS bf16x8*)(lds + PG8_SA(b, h) + aoff + m * 2048 + k * 1024); } while (0)
; #define PG8_MMA(ai, bj, At, Bt) do { __builtin_amdgcn_s_setprio(1); _Pragma("unroll") for (int m = 0; m < 4; ++m) _Pragma("unroll") for (int n = 0; n < 2; ++n) _Pragma("unroll") for (int k = 0; k < 2; ++k) \
;         acc[ai][bj][m][n] = __builtin_amdgcn_mfma_f32_16x16x32_bf16(Bt[n][k], At[m][k], acc[ai][bj][m][n], 0, 0, 0); __builtin_amdgcn_s_setprio(0); } while (0)
; #define PG8_WAIT_V(n) asm volatile("s_waitcnt vmcnt(" #n ")" ::: "memory")
; #define PG8_WAIT_L(n) asm volatile("s_waitcnt lgkmcnt(" #n ")" ::: "memory")
; #define PG8_BAR __builtin_amdgcn_s_barrier()
; #define PG8_SCHED __builtin_amdgcn_sched_barrier(0)
; template <class Epi, class Sched>
; __device__ __forceinline__ void gemm_phase(PG8_LAS unsigned char* lds, const Gemm g, const Sched& S, const Epi& E) {
;     ...
;             PG8_BAR; PG8_WAIT_L(0); PG8_MMA(0, 1, At, B1); PG8_BAR;
;             PG8_LDA(At, 1, 1); PG8_STAGE(PG8_SA(1, 0), a3, voffA);
;             PG8_BAR; PG8_WAIT_L(0); PG8_MMA(1, 0, At, B0); PG8_BAR; PG8_SCHED;
;             PG8_STAGE(PG8_SB(1, 1), b3 + hstep, voffB);
;             PG8_WAIT_V(6); PG8_BAR; PG8_MMA(1, 1, At, B1); PG8_BAR;
;         }
	s_waitcnt lgkmcnt(0)
	v_mfma_f32_16x16x32_bf16 v[116:119], v[222:225], v[146:149], v[116:119]
	v_mfma_f32_16x16x32_bf16 v[112:115], v[230:233], v[146:149], v[112:115]
	v_mfma_f32_16x16x32_bf16 v[100:103], v[222:225], v[196:199], v[100:103]
	v_mfma_f32_16x16x32_bf16 v[96:99], v[230:233], v[196:199], v[96:99]
	v_mfma_f32_16x16x32_bf16 v[84:87], v[222:225], v[206:209], v[84:87]
	v_mfma_f32_16x16x32_bf16 v[80:83], v[230:233], v[206:209], v[80:83]
	v_mfma_f32_16x16x32_bf16 v[68:71], v[222:225], v[214:217], v[68:71]
	v_mfma_f32_16x16x32_bf16 v[64:67], v[230:233], v[214:217], v[64:67]
	v_mfma_f32_16x16x32_bf16 v[116:119], v[226:229], v[192:195], v[116:119]
	v_mfma_f32_16x16x32_bf16 v[112:115], v[234:237], v[192:195], v[112:115]
	v_mfma_f32_16x16x32_bf16 v[100:103], v[226:229], v[200:203], v[100:103]
	v_mfma_f32_16x16x32_bf16 v[96:99], v[234:237], v[200:203], v[96:99]
	v_mfma_f32_16x16x32_bf16 v[84:87], v[226:229], v[210:213], v[84:87]
	v_mfma_f32_16x16x32_bf16 v[80:83], v[234:237], v[210:213], v[80:83]
	v_mfma_f32_16x16x32_bf16 v[68:71], v[226:229], v[218:221], v[68:71]
	v_mfma_f32_16x16x32_bf16 v[64:67], v[234:237], v[218:221], v[64:67]
	s_mov_b32 m0, s25
	v_lshl_add_u64 v[150:151], v[240:241], 0, s[8:9]
	s_barrier
	ds_read_b128 v[146:149], v163 offset:49152
	ds_read_b128 v[192:195], v163 offset:50176
	ds_read_b128 v[196:199], v163 offset:51200
	ds_read_b128 v[200:203], v163 offset:52224
	ds_read_b128 v[206:209], v163 offset:53248
	ds_read_b128 v[210:213], v163 offset:54272
	ds_read_b128 v[214:217], v163 offset:55296
	ds_read_b128 v[218:221], v163 offset:56320
	global_load_lds_dwordx4 v[150:151], off
	s_mov_b32 m0, s29
	v_lshl_add_u64 v[150:151], v[242:243], 0, s[8:9]
	global_load_lds_dwordx4 v[150:151], off
	s_barrier
	s_waitcnt lgkmcnt(0)
	v_mfma_f32_16x16x32_bf16 v[60:63], v[130:133], v[146:149], v[60:63]
	v_mfma_f32_16x16x32_bf16 v[56:59], v[138:141], v[146:149], v[56:59]
	v_mfma_f32_16x16x32_bf16 v[44:47], v[130:133], v[196:199], v[44:47]
	v_mfma_f32_16x16x32_bf16 v[40:43], v[138:141], v[196:199], v[40:43]
	v_mfma_f32_16x16x32_bf16 v[28:31], v[130:133], v[206:209], v[28:31]
	v_mfma_f32_16x16x32_bf16 v[24:27], v[138:141], v[206:209], v[24:27]
	v_mfma_f32_16x16x32_bf16 v[12:15], v[130:133], v[214:217], v[12:15]
	v_mfma_f32_16x16x32_bf16 v[8:11], v[138:141], v[214:217], v[8:11]
	v_mfma_f32_16x16x32_bf16 v[60:63], v[134:137], v[192:195], v[60:63]
	v_mfma_f32_16x16x32_bf16 v[56:59], v[142:145], v[192:195], v[56:59]
	v_mfma_f32_16x16x32_bf16 v[44:47], v[134:137], v[200:203], v[44:47]
	v_mfma_f32_16x16x32_bf16 v[40:43], v[142:145], v[200:203], v[40:43]
	v_mfma_f32_16x16x32_bf16 v[28:31], v[134:137], v[210:213], v[28:31]
	v_mfma_f32_16x16x32_bf16 v[24:27], v[142:145], v[210:213], v[24:27]
	v_mfma_f32_16x16x32_bf16 v[12:15], v[134:137], v[218:221], v[12:15]
	v_mfma_f32_16x16x32_bf16 v[8:11], v[142:145], v[218:221], v[8:11]
	s_barrier
	s_add_u32 s38, s38, 0x40080
	s_addc_u32 s39, s39, 0
	s_add_i32 s30, s40, s3
	s_mov_b32 m0, s30
	v_lshl_add_u64 v[130:131], s[38:39], 0, v[168:169]
	global_load_lds_dwordx4 v[130:131], off
	s_add_i32 m0, s30, 0x2000
	v_lshl_add_u64 v[130:131], s[38:39], 0, v[164:165]
	global_load_lds_dwordx4 v[130:131], off
	s_waitcnt vmcnt(6)
	s_barrier
	v_mfma_f32_16x16x32_bf16 v[52:55], v[222:225], v[146:149], v[52:55]
	v_mfma_f32_16x16x32_bf16 v[48:51], v[230:233], v[146:149], v[48:51]
	v_mfma_f32_16x16x32_bf16 v[36:39], v[222:225], v[196:199], v[36:39]
	v_mfma_f32_16x16x32_bf16 v[32:35], v[230:233], v[196:199], v[32:35]
	v_mfma_f32_16x16x32_bf16 v[20:23], v[222:225], v[206:209], v[20:23]
	v_mfma_f32_16x16x32_bf16 v[16:19], v[230:233], v[206:209], v[16:19]
	v_mfma_f32_16x16x32_bf16 v[4:7], v[222:225], v[214:217], v[4:7]
	v_mfma_f32_16x16x32_bf16 v[0:3], v[230:233], v[214:217], v[0:3]
	v_mfma_f32_16x16x32_bf16 v[52:55], v[226:229], v[192:195], v[52:55]
	v_mfma_f32_16x16x32_bf16 v[48:51], v[234:237], v[192:195], v[48:51]
	v_mfma_f32_16x16x32_bf16 v[36:39], v[226:229], v[200:203], v[36:39]
	v_mfma_f32_16x16x32_bf16 v[32:35], v[234:237], v[200:203], v[32:35]
	v_mfma_f32_16x16x32_bf16 v[20:23], v[226:229], v[210:213], v[20:23]
	v_mfma_f32_16x16x32_bf16 v[16:19], v[234:237], v[210:213], v[16:19]
	v_mfma_f32_16x16x32_bf16 v[4:7], v[226:229], v[218:221], v[4:7]
	v_mfma_f32_16x16x32_bf16 v[0:3], v[234:237], v[218:221], v[0:3]
	s_add_i32 s47, s47, 2
	s_add_u32 s4, s4, 0x100
	s_addc_u32 s5, s5, 0
	s_add_u32 s45, s45, 0x100
	s_addc_u32 s46, s46, 0
	s_cmp_lt_u32 s47, 14
	s_barrier
	s_cbranch_scc0 .LBB0_1512

; #define PG8_STAGE(bufoff, gbase, voff) do { _Pragma("unroll") for (int _i = 0; _i < 2; ++_i) \
;         __builtin_amdgcn_global_load_lds((const unsigned*)((const char*)(gbase) + (voff)[_i]), (PG8_LAS unsigned*)(lds + (bufoff) + ldsw + _i * 8192), 16, 0, 0); } while (0)
; #define PG8_LDA(dst, b, h) do { _Pragma("unroll") for (int m = 0; m < 4; ++m) _Pragma("unroll") for (int k = 0; k < 2; ++k) dst[m][k] = *(const PG8_LAS bf16x8*)(lds + PG8_SA(b, h) + aoff + m * 2048 + k * 1024); } while (0)
; #define PG8_LDB(dst, b, h) do { _Pragma("unroll") for (int n = 0; n < 2; ++n) _Pragma("unroll") for (int k = 0; k < 2; ++k) dst[n][k] = *(const PG8_LAS bf16x8*)(lds + PG8_SB(b, h) + boff + n * 2048 + k * 1024); } while (0)
; #define PG8_MMA(ai, bj, At, Bt) do { __builtin_amdgcn_s_setprio(1); _Pragma("unroll") for (int m = 0; m < 4; ++m) _Pragma("unroll") for (int n = 0; n < 2; ++n) _Pragma("unroll") for (int k = 0; k < 2; ++k) \
;         acc[ai][bj][m][n] = __builtin_amdgcn_mfma_f32_16x16x32_bf16(Bt[n][k], At[m][k], acc[ai][bj][m][n], 0, 0, 0); __builtin_amdgcn_s_setprio(0); } while (0)
; #define PG8_WAIT_L(n) asm volatile("s_waitcnt lgkmcnt(" #n ")" ::: "memory")
; #define PG8_BAR __builtin_amdgcn_s_barrier()
; #define PG8_SCHED __builtin_amdgcn_sched_barrier(0)
; template <class Epi, class Sched>
; __device__ __forceinline__ void gemm_phase(PG8_LAS unsigned char* lds, const Gemm g, const Sched& S, const Epi& E) {
;     ...
;             const bool last = (t == cnk - 2);
;             const char* a1 = cA + (size_t)(t + 1) * kstep;
;             const char* a2 = last ? nA : cA + (size_t)(t + 2) * kstep; const char* b2 = last ? nB : cB + (size_t)(t + 2) * kstep;
;             const char* a3 = a2 + kstep; const char* b3 = b2 + kstep;
;             if (last && has_next) S.a_ready(nxt);
;             if (last) E.prefetch(pre, cur, wr, fr);
;             PG8_LDB(B0, 0, 0); PG8_SCHED; PG8_LDA(At, 0, 0); PG8_STAGE(PG8_SA(1, 1), a1 + hstep, voffA);
;             PG8_WAIT_L(8); PG8_BAR; PG8_WAIT_L(0); PG8_MMA(0, 0, At, B0); PG8_BAR; PG8_SCHED;
;             PG8_LDB(B1, 0, 1); PG8_STAGE(PG8_SB(0, 0), b2, voffB);
;             PG8_BAR; PG8_WAIT_L(0); PG8_MMA(0, 1, At, B1); PG8_BAR;
;             PG8_LDA(At, 0, 1); PG8_STAGE(PG8_SA(0, 0), a2, voffA);
;             PG8_BAR; PG8_WAIT_L(0); PG8_MMA(1, 0, At, B0); PG8_BAR; PG8_SCHED;
.LBB0_1636:
	ds_read_b128 v[128:131], v163
	ds_read_b128 v[132:135], v163 offset:1024
	ds_read_b128 v[136:139], v163 offset:2048
	ds_read_b128 v[140:143], v163 offset:3072
	s_add_i32 s76, s45, 2
	s_add_u32 s30, s48, 0xfff00080
	s_addc_u32 s50, s49, -1
	s_cmp_eq_u32 s27, s45
	s_cselect_b32 s53, s43, s50
	s_cselect_b32 s52, s42, s30
	s_cselect_b32 s51, s47, s39
	s_cselect_b32 s50, s46, s37
	v_lshl_add_u64 v[196:197], s[48:49], 0, v[174:175]
	s_add_i32 m0, s5, 0xc000
	ds_read_b128 v[144:147], v198
	ds_read_b128 v[148:151], v198 offset:1024
	ds_read_b128 v[180:183], v198 offset:2048
	ds_read_b128 v[184:187], v198 offset:3072
	ds_read_b128 v[188:191], v198 offset:4096
	ds_read_b128 v[192:195], v198 offset:5120
	ds_read_b128 v[202:205], v198 offset:6144
	ds_read_b128 v[206:209], v198 offset:7168
	global_load_lds_dwordx4 v[196:197], off
	s_add_i32 m0, s5, 0xe000
	v_lshl_add_u64 v[196:197], s[48:49], 0, v[176:177]
	global_load_lds_dwordx4 v[196:197], off
	s_waitcnt lgkmcnt(8)
	s_barrier
	s_waitcnt lgkmcnt(0)
	v_mfma_f32_16x16x32_bf16 v[124:127], v[128:131], v[144:147], v[124:127]
	v_mfma_f32_16x16x32_bf16 v[120:123], v[136:139], v[144:147], v[120:123]
	v_mfma_f32_16x16x32_bf16 v[108:111], v[128:131], v[180:183], v[108:111]
	v_mfma_f32_16x16x32_bf16 v[104:107], v[136:139], v[180:183], v[104:107]
	v_mfma_f32_16x16x32_bf16 v[92:95], v[128:131], v[188:191], v[92:95]
	v_mfma_f32_16x16x32_bf16 v[88:91], v[136:139], v[188:191], v[88:91]
	v_mfma_f32_16x16x32_bf16 v[76:79], v[128:131], v[202:205], v[76:79]
	v_mfma_f32_16x16x32_bf16 v[72:75], v[136:139], v[202:205], v[72:75]
	v_mfma_f32_16x16x32_bf16 v[124:127], v[132:135], v[148:151], v[124:127]
	v_mfma_f32_16x16x32_bf16 v[120:123], v[140:143], v[148:151], v[120:123]
	v_mfma_f32_16x16x32_bf16 v[108:111], v[132:135], v[184:187], v[108:111]
	v_mfma_f32_16x16x32_bf16 v[104:107], v[140:143], v[184:187], v[104:107]
	v_mfma_f32_16x16x32_bf16 v[92:95], v[132:135], v[192:195], v[92:95]
	v_mfma_f32_16x16x32_bf16 v[88:91], v[140:143], v[192:195], v[88:91]
	v_mfma_f32_16x16x32_bf16 v[76:79], v[132:135], v[206:209], v[76:79]
	v_mfma_f32_16x16x32_bf16 v[72:75], v[140:143], v[206:209], v[72:75]
	s_barrier
	s_add_i32 s30, s71, s4
	v_lshl_add_u64 v[196:197], s[50:51], 0, v[166:167]
	s_mov_b32 m0, s30
	ds_read_b128 v[210:213], v199
	ds_read_b128 v[214:217], v199 offset:1024
	ds_read_b128 v[218:221], v199 offset:2048
	ds_read_b128 v[222:225], v199 offset:3072
	global_load_lds_dwordx4 v[196:197], off
	s_add_i32 m0, s30, 0x2000
	v_lshl_add_u64 v[226:227], s[50:51], 0, v[170:171]
	global_load_lds_dwordx4 v[226:227], off
	s_barrier
	s_waitcnt lgkmcnt(0)
	v_mfma_f32_16x16x32_bf16 v[116:119], v[210:213], v[144:147], v[116:119]
	v_mfma_f32_16x16x32_bf16 v[112:115], v[218:221], v[144:147], v[112:115]
	v_mfma_f32_16x16x32_bf16 v[100:103], v[210:213], v[180:183], v[100:103]
	v_mfma_f32_16x16x32_bf16 v[96:99], v[218:221], v[180:183], v[96:99]
	v_mfma_f32_16x16x32_bf16 v[84:87], v[210:213], v[188:191], v[84:87]
	v_mfma_f32_16x16x32_bf16 v[80:83], v[218:221], v[188:191], v[80:83]
	v_mfma_f32_16x16x32_bf16 v[68:71], v[210:213], v[202:205], v[68:71]
	v_mfma_f32_16x16x32_bf16 v[64:67], v[218:221], v[202:205], v[64:67]
	v_mfma_f32_16x16x32_bf16 v[116:119], v[214:217], v[148:151], v[116:119]
	v_mfma_f32_16x16x32_bf16 v[112:115], v[222:225], v[148:151], v[112:115]
	v_mfma_f32_16x16x32_bf16 v[100:103], v[214:217], v[184:187], v[100:103]
	v_mfma_f32_16x16x32_bf16 v[96:99], v[222:225], v[184:187], v[96:99]
	v_mfma_f32_16x16x32_bf16 v[84:87], v[214:217], v[192:195], v[84:87]
	v_mfma_f32_16x16x32_bf16 v[80:83], v[222:225], v[192:195], v[80:83]
	v_mfma_f32_16x16x32_bf16 v[68:71], v[214:217], v[206:209], v[68:71]
	v_mfma_f32_16x16x32_bf16 v[64:67], v[222:225], v[206:209], v[64:67]
	s_mov_b32 m0, s5
	v_lshl_add_u64 v[228:229], s[52:53], 0, v[164:165]
	s_barrier
	ds_read_b128 v[144:147], v198 offset:16384
	ds_read_b128 v[148:151], v198 offset:17408
	ds_read_b128 v[180:183], v198 offset:18432
	ds_read_b128 v[184:187], v198 offset:19456
	ds_read_b128 v[188:191], v198 offset:20480
	ds_read_b128 v[192:195], v198 offset:21504
	ds_read_b128 v[202:205], v198 offset:22528
	ds_read_b128 v[206:209], v198 offset:23552
	global_load_lds_dwordx4 v[228:229], off
	s_mov_b32 m0, s16
	v_lshl_add_u64 v[230:231], s[52:53], 0, v[168:169]
	global_load_lds_dwordx4 v[230:231], off
	s_barrier
	s_waitcnt lgkmcnt(0)
	v_mfma_f32_16x16x32_bf16 v[60:63], v[128:131], v[144:147], v[60:63]
	v_mfma_f32_16x16x32_bf16 v[56:59], v[136:139], v[144:147], v[56:59]
	v_mfma_f32_16x16x32_bf16 v[44:47], v[128:131], v[180:183], v[44:47]
	v_mfma_f32_16x16x32_bf16 v[40:43], v[136:139], v[180:183], v[40:43]
	v_mfma_f32_16x16x32_bf16 v[28:31], v[128:131], v[188:191], v[28:31]
	v_mfma_f32_16x16x32_bf16 v[24:27], v[136:139], v[188:191], v[24:27]
	v_mfma_f32_16x16x32_bf16 v[12:15], v[128:131], v[202:205], v[12:15]
	v_mfma_f32_16x16x32_bf16 v[8:11], v[136:139], v[202:205], v[8:11]
	v_mfma_f32_16x16x32_bf16 v[60:63], v[132:135], v[148:151], v[60:63]
	v_mfma_f32_16x16x32_bf16 v[56:59], v[140:143], v[148:151], v[56:59]
	v_mfma_f32_16x16x32_bf16 v[44:47], v[132:135], v[184:187], v[44:47]
	v_mfma_f32_16x16x32_bf16 v[40:43], v[140:143], v[184:187], v[40:43]
	v_mfma_f32_16x16x32_bf16 v[28:31], v[132:135], v[192:195], v[28:31]
	v_mfma_f32_16x16x32_bf16 v[24:27], v[140:143], v[192:195], v[24:27]
	v_mfma_f32_16x16x32_bf16 v[12:15], v[132:135], v[206:209], v[12:15]
	v_mfma_f32_16x16x32_bf16 v[8:11], v[140:143], v[206:209], v[8:11]
	s_barrier
; #define PG8_STAGE(bufoff, gbase, voff) do { _Pragma("unroll") for (int _i = 0; _i < 2; ++_i) \
;         __builtin_amdgcn_global_load_lds((const unsigned*)((const char*)(gbase) + (voff)[_i]), (PG8_LAS unsigned*)(lds + (bufoff) + ldsw + _i * 8192), 16, 0, 0); } while (0)
; #define PG8_LDA(dst, b, h) do { _Pragma("unroll") for (int m = 0; m < 4; ++m) _Pragma("unroll") for (int k = 0; k < 2; ++k) dst[m][k] = *(const PG8_LAS bf16x8*)(lds + PG8_SA(b, h) + aoff + m * 2048 + k * 1024); } while (0)
; #define PG8_LDB(dst, b, h) do { _Pragma("unroll") for (int n = 0; n < 2; ++n) _Pragma("unroll") for (int k = 0; k < 2; ++k) dst[n][k] = *(const PG8_LAS bf16x8*)(lds + PG8_SB(b, h) + boff + n * 2048 + k * 1024); } while (0)
; #define PG8_MMA(ai, bj, At, Bt) do { __builtin_amdgcn_s_setprio(1); _Pragma("unroll") for (int m = 0; m < 4; ++m) _Pragma("unroll") for (int n = 0; n < 2; ++n) _Pragma("unroll") for (int k = 0; k < 2; ++k) \
;         acc[ai][bj][m][n] = __builtin_amdgcn_mfma_f32_16x16x32_bf16(Bt[n][k], At[m][k], acc[ai][bj][m][n], 0, 0, 0); __builtin_amdgcn_s_setprio(0); } while (0)
; #define PG8_WAIT_V(n) asm volatile("s_waitcnt vmcnt(" #n ")" ::: "memory")
; #define PG8_WAIT_L(n) asm volatile("s_waitcnt lgkmcnt(" #n ")" ::: "memory")
; #define PG8_BAR __builtin_amdgcn_s_barrier()
; #define PG8_SCHED __builtin_amdgcn_sched_barrier(0)
; template <class Epi, class Sched>
; __device__ __forceinline__ void gemm_phase(PG8_LAS unsigned char* lds, const Gemm g, const Sched& S, const Epi& E) {
;     ...
;             PG8_STAGE(PG8_SB(0, 1), b2 + hstep, voffB);
;             PG8_WAIT_V(6); PG8_BAR; PG8_MMA(1, 1, At, B1); PG8_BAR;
;             PG8_LDB(B0, 1, 0); PG8_SCHED; PG8_LDA(At, 1, 0); PG8_STAGE(PG8_SA(0, 1), a2 + hstep, voffA);
;             PG8_WAIT_L(8); PG8_BAR; PG8_WAIT_L(0); PG8_MMA(0, 0, At, B0); PG8_BAR; PG8_SCHED;
;             PG8_LDB(B1, 1, 1); PG8_STAGE(PG8_SB(1, 0), b3, voffB);
	s_add_u32 s96, s50, 0x100000
	s_addc_u32 s97, s51, 0
	s_add_i32 s30, s72, s4
	s_mov_b32 m0, s30
	v_lshl_add_u64 v[128:129], s[96:97], 0, v[166:167]
	global_load_lds_dwordx4 v[128:129], off
	s_add_i32 m0, s30, 0x2000
	v_lshl_add_u64 v[128:129], s[96:97], 0, v[170:171]
	global_load_lds_dwordx4 v[128:129], off
	s_waitcnt vmcnt(6)
	s_barrier
	v_mfma_f32_16x16x32_bf16 v[52:55], v[210:213], v[144:147], v[52:55]
	v_mfma_f32_16x16x32_bf16 v[48:51], v[218:221], v[144:147], v[48:51]
	v_mfma_f32_16x16x32_bf16 v[36:39], v[210:213], v[180:183], v[36:39]
	v_mfma_f32_16x16x32_bf16 v[32:35], v[218:221], v[180:183], v[32:35]
	v_mfma_f32_16x16x32_bf16 v[20:23], v[210:213], v[188:191], v[20:23]
	v_mfma_f32_16x16x32_bf16 v[16:19], v[218:221], v[188:191], v[16:19]
	v_mfma_f32_16x16x32_bf16 v[4:7], v[210:213], v[202:205], v[4:7]
	v_mfma_f32_16x16x32_bf16 v[0:3], v[218:221], v[202:205], v[0:3]
	v_mfma_f32_16x16x32_bf16 v[52:55], v[214:217], v[148:151], v[52:55]
	v_mfma_f32_16x16x32_bf16 v[48:51], v[222:225], v[148:151], v[48:51]
	v_mfma_f32_16x16x32_bf16 v[36:39], v[214:217], v[184:187], v[36:39]
	v_mfma_f32_16x16x32_bf16 v[32:35], v[222:225], v[184:187], v[32:35]
	v_mfma_f32_16x16x32_bf16 v[20:23], v[214:217], v[192:195], v[20:23]
	v_mfma_f32_16x16x32_bf16 v[16:19], v[222:225], v[192:195], v[16:19]
	v_mfma_f32_16x16x32_bf16 v[4:7], v[214:217], v[206:209], v[4:7]
	v_mfma_f32_16x16x32_bf16 v[0:3], v[222:225], v[206:209], v[0:3]
	s_add_i32 s30, 0, 0x18000
	v_add_u32_e32 v140, s30, v159
	s_barrier
	ds_read_b128 v[128:131], v140
	ds_read_b128 v[132:135], v140 offset:1024
	ds_read_b128 v[136:139], v140 offset:2048
	ds_read_b128 v[140:143], v140 offset:3072
	s_add_u32 s52, s52, 0x100000
	s_addc_u32 s53, s53, 0
	s_mov_b32 m0, s17
	v_lshl_add_u64 v[210:211], s[52:53], 0, v[164:165]
	ds_read_b128 v[144:147], v198 offset:32768
	ds_read_b128 v[148:151], v198 offset:33792
	ds_read_b128 v[180:183], v198 offset:34816
	ds_read_b128 v[184:187], v198 offset:35840
	ds_read_b128 v[188:191], v198 offset:36864
	ds_read_b128 v[192:195], v198 offset:37888
	ds_read_b128 v[202:205], v198 offset:38912
	ds_read_b128 v[206:209], v198 offset:39936
	global_load_lds_dwordx4 v[210:211], off
	s_mov_b32 m0, s18
	v_lshl_add_u64 v[210:211], s[52:53], 0, v[168:169]
	global_load_lds_dwordx4 v[210:211], off
	s_waitcnt lgkmcnt(8)
	s_barrier
	s_waitcnt lgkmcnt(0)
	v_mfma_f32_16x16x32_bf16 v[124:127], v[128:131], v[144:147], v[124:127]
	v_mfma_f32_16x16x32_bf16 v[120:123], v[136:139], v[144:147], v[120:123]
	v_mfma_f32_16x16x32_bf16 v[108:111], v[128:131], v[180:183], v[108:111]
	v_mfma_f32_16x16x32_bf16 v[104:107], v[136:139], v[180:183], v[104:107]
	v_mfma_f32_16x16x32_bf16 v[92:95], v[128:131], v[188:191], v[92:95]
	v_mfma_f32_16x16x32_bf16 v[88:91], v[136:139], v[188:191], v[88:91]
	v_mfma_f32_16x16x32_bf16 v[76:79], v[128:131], v[202:205], v[76:79]
	v_mfma_f32_16x16x32_bf16 v[72:75], v[136:139], v[202:205], v[72:75]
	v_mfma_f32_16x16x32_bf16 v[124:127], v[132:135], v[148:151], v[124:127]
	v_mfma_f32_16x16x32_bf16 v[120:123], v[140:143], v[148:151], v[120:123]
	v_mfma_f32_16x16x32_bf16 v[108:111], v[132:135], v[184:187], v[108:111]
	v_mfma_f32_16x16x32_bf16 v[104:107], v[140:143], v[184:187], v[104:107]
	v_mfma_f32_16x16x32_bf16 v[92:95], v[132:135], v[192:195], v[92:95]
	v_mfma_f32_16x16x32_bf16 v[88:91], v[140:143], v[192:195], v[88:91]
	v_mfma_f32_16x16x32_bf16 v[76:79], v[132:135], v[206:209], v[76:79]
	v_mfma_f32_16x16x32_bf16 v[72:75], v[140:143], v[206:209], v[72:75]
	s_barrier
	s_add_i32 s45, 0, 0x1c000
	s_add_i32 s30, s30, s4
	v_add_u32_e32 v201, s45, v159
	v_lshl_add_u64 v[196:197], v[196:197], 0, s[14:15]
	s_mov_b32 m0, s30
	ds_read_b128 v[210:213], v201
	ds_read_b128 v[214:217], v201 offset:1024
	ds_read_b128 v[218:221], v201 offset:2048
	ds_read_b128 v[222:225], v201 offset:3072
	global_load_lds_dwordx4 v[196:197], off
	s_add_i32 m0, s30, 0x2000
	v_lshl_add_u64 v[196:197], v[226:227], 0, s[14:15]
	global_load_lds_dwordx4 v[196:197], off
	s_barrier
; #define PG8_STAGE(bufoff, gbase, voff) do { _Pragma("unroll") for (int _i = 0; _i < 2; ++_i) \
;         __builtin_amdgcn_global_load_lds((const unsigned*)((const char*)(gbase) + (voff)[_i]), (PG8_LAS unsigned*)(lds + (bufoff) + ldsw + _i * 8192), 16, 0, 0); } while (0)
; #define PG8_LDA(dst, b, h) do { _Pragma("unroll") for (int m = 0; m < 4; ++m) _Pragma("unroll") for (int k = 0; k < 2; ++k) dst[m][k] = *(const PG8_LAS bf16x8*)(lds + PG8_SA(b, h) + aoff + m * 2048 + k * 1024); } while (0)
; #define PG8_MMA(ai, bj, At, Bt) do { __builtin_amdgcn_s_setprio(1); _Pragma("unroll") for (int m = 0; m < 4; ++m) _Pragma("unroll") for (int n = 0; n < 2; ++n) _Pragma("unroll") for (int k = 0; k < 2; ++k) \
;         acc[ai][bj][m][n] = __builtin_amdgcn_mfma_f32_16x16x32_bf16(Bt[n][k], At[m][k], acc[ai][bj][m][n], 0, 0, 0); __builtin_amdgcn_s_setprio(0); } while (0)
; #define PG8_WAIT_V(n) asm volatile("s_waitcnt vmcnt(" #n ")" ::: "memory")
; #define PG8_WAIT_L(n) asm volatile("s_waitcnt lgkmcnt(" #n ")" ::: "memory")
; #define PG8_BAR __builtin_amdgcn_s_barrier()
; #define PG8_SCHED __builtin_amdgcn_sched_barrier(0)
; template <class Epi, class Sched>
; __device__ __forceinline__ void gemm_phase(PG8_LAS unsigned char* lds, const Gemm g, const Sched& S, const Epi& E) {
;     ...
;             PG8_BAR; PG8_WAIT_L(0); PG8_MMA(0, 1, At, B1); PG8_BAR;
;             PG8_LDA(At, 1, 1); PG8_STAGE(PG8_SA(1, 0), a3, voffA);
;             PG8_BAR; PG8_WAIT_L(0); PG8_MMA(1, 0, At, B0); PG8_BAR; PG8_SCHED;
;             PG8_STAGE(PG8_SB(1, 1), b3 + hstep, voffB);
;             PG8_WAIT_V(6); PG8_BAR; PG8_MMA(1, 1, At, B1); PG8_BAR;
;         }
;         if constexpr (!Epi::AFTER_DRAIN) {
;             if (cur.part < 0) E(acc, cur, wr, wc, fr, fq, pre);
	s_waitcnt lgkmcnt(0)
	v_mfma_f32_16x16x32_bf16 v[116:119], v[210:213], v[144:147], v[116:119]
	v_mfma_f32_16x16x32_bf16 v[112:115], v[218:221], v[144:147], v[112:115]
	v_mfma_f32_16x16x32_bf16 v[100:103], v[210:213], v[180:183], v[100:103]
	v_mfma_f32_16x16x32_bf16 v[96:99], v[218:221], v[180:183], v[96:99]
	v_mfma_f32_16x16x32_bf16 v[84:87], v[210:213], v[188:191], v[84:87]
	v_mfma_f32_16x16x32_bf16 v[80:83], v[218:221], v[188:191], v[80:83]
	v_mfma_f32_16x16x32_bf16 v[68:71], v[210:213], v[202:205], v[68:71]
	v_mfma_f32_16x16x32_bf16 v[64:67], v[218:221], v[202:205], v[64:67]
	v_mfma_f32_16x16x32_bf16 v[116:119], v[214:217], v[148:151], v[116:119]
	v_mfma_f32_16x16x32_bf16 v[112:115], v[222:225], v[148:151], v[112:115]
	v_mfma_f32_16x16x32_bf16 v[100:103], v[214:217], v[184:187], v[100:103]
	v_mfma_f32_16x16x32_bf16 v[96:99], v[222:225], v[184:187], v[96:99]
	v_mfma_f32_16x16x32_bf16 v[84:87], v[214:217], v[192:195], v[84:87]
	v_mfma_f32_16x16x32_bf16 v[80:83], v[222:225], v[192:195], v[80:83]
	v_mfma_f32_16x16x32_bf16 v[68:71], v[214:217], v[206:209], v[68:71]
	v_mfma_f32_16x16x32_bf16 v[64:67], v[222:225], v[206:209], v[64:67]
	s_mov_b32 m0, s24
	v_lshl_add_u64 v[196:197], v[228:229], 0, s[14:15]
	s_barrier
	ds_read_b128 v[144:147], v198 offset:49152
	ds_read_b128 v[148:151], v198 offset:50176
	ds_read_b128 v[180:183], v198 offset:51200
	ds_read_b128 v[184:187], v198 offset:52224
	ds_read_b128 v[188:191], v198 offset:53248
	ds_read_b128 v[192:195], v198 offset:54272
	ds_read_b128 v[202:205], v198 offset:55296
	ds_read_b128 v[206:209], v198 offset:56320
	global_load_lds_dwordx4 v[196:197], off
	s_mov_b32 m0, s25
	v_lshl_add_u64 v[196:197], v[230:231], 0, s[14:15]
	global_load_lds_dwordx4 v[196:197], off
	s_barrier
	s_waitcnt lgkmcnt(0)
	v_mfma_f32_16x16x32_bf16 v[60:63], v[128:131], v[144:147], v[60:63]
	v_mfma_f32_16x16x32_bf16 v[56:59], v[136:139], v[144:147], v[56:59]
	v_mfma_f32_16x16x32_bf16 v[44:47], v[128:131], v[180:183], v[44:47]
	v_mfma_f32_16x16x32_bf16 v[40:43], v[136:139], v[180:183], v[40:43]
	v_mfma_f32_16x16x32_bf16 v[28:31], v[128:131], v[188:191], v[28:31]
	v_mfma_f32_16x16x32_bf16 v[24:27], v[136:139], v[188:191], v[24:27]
	v_mfma_f32_16x16x32_bf16 v[12:15], v[128:131], v[202:205], v[12:15]
	v_mfma_f32_16x16x32_bf16 v[8:11], v[136:139], v[202:205], v[8:11]
	v_mfma_f32_16x16x32_bf16 v[60:63], v[132:135], v[148:151], v[60:63]
	v_mfma_f32_16x16x32_bf16 v[56:59], v[140:143], v[148:151], v[56:59]
	v_mfma_f32_16x16x32_bf16 v[44:47], v[132:135], v[184:187], v[44:47]
	v_mfma_f32_16x16x32_bf16 v[40:43], v[140:143], v[184:187], v[40:43]
	v_mfma_f32_16x16x32_bf16 v[28:31], v[132:135], v[192:195], v[28:31]
	v_mfma_f32_16x16x32_bf16 v[24:27], v[140:143], v[192:195], v[24:27]
	v_mfma_f32_16x16x32_bf16 v[12:15], v[132:135], v[206:209], v[12:15]
	v_mfma_f32_16x16x32_bf16 v[8:11], v[140:143], v[206:209], v[8:11]
	s_barrier
	s_add_u32 s50, s50, 0x100080
	s_addc_u32 s51, s51, 0
	s_add_i32 s30, s45, s4
	s_mov_b32 m0, s30
	v_lshl_add_u64 v[128:129], s[50:51], 0, v[166:167]
	global_load_lds_dwordx4 v[128:129], off
	s_add_i32 m0, s30, 0x2000
	v_lshl_add_u64 v[128:129], s[50:51], 0, v[170:171]
	global_load_lds_dwordx4 v[128:129], off
	s_waitcnt vmcnt(6)
	s_barrier
	v_mfma_f32_16x16x32_bf16 v[52:55], v[210:213], v[144:147], v[52:55]
	v_mfma_f32_16x16x32_bf16 v[48:51], v[218:221], v[144:147], v[48:51]
	v_mfma_f32_16x16x32_bf16 v[36:39], v[210:213], v[180:183], v[36:39]
	v_mfma_f32_16x16x32_bf16 v[32:35], v[218:221], v[180:183], v[32:35]
	v_mfma_f32_16x16x32_bf16 v[20:23], v[210:213], v[188:191], v[20:23]
	v_mfma_f32_16x16x32_bf16 v[16:19], v[218:221], v[188:191], v[16:19]
	v_mfma_f32_16x16x32_bf16 v[4:7], v[210:213], v[202:205], v[4:7]
	v_mfma_f32_16x16x32_bf16 v[0:3], v[218:221], v[202:205], v[0:3]
	v_mfma_f32_16x16x32_bf16 v[52:55], v[214:217], v[148:151], v[52:55]
	v_mfma_f32_16x16x32_bf16 v[48:51], v[222:225], v[148:151], v[48:51]
	v_mfma_f32_16x16x32_bf16 v[36:39], v[214:217], v[184:187], v[36:39]
	v_mfma_f32_16x16x32_bf16 v[32:35], v[222:225], v[184:187], v[32:35]
	v_mfma_f32_16x16x32_bf16 v[20:23], v[214:217], v[192:195], v[20:23]
	v_mfma_f32_16x16x32_bf16 v[16:19], v[222:225], v[192:195], v[16:19]
	v_mfma_f32_16x16x32_bf16 v[4:7], v[214:217], v[206:209], v[4:7]
	v_mfma_f32_16x16x32_bf16 v[0:3], v[222:225], v[206:209], v[0:3]
	s_add_u32 s48, s48, 0x100
	s_addc_u32 s49, s49, 0
	s_add_u32 s37, s37, 0x100
	s_addc_u32 s39, s39, 0
	s_cmp_ge_i32 s76, s23
	s_mov_b32 s45, s76
	s_barrier
	s_cbranch_scc0 .LBB0_1636
	s_cmp_gt_i32 s10, -1
	s_mov_b64 s[48:49], -1
	s_cbranch_scc0 .LBB0_1639

; #define PG8_STAGE(bufoff, gbase, voff) do { _Pragma("unroll") for (int _i = 0; _i < 2; ++_i) \
;         __builtin_amdgcn_global_load_lds((const unsigned*)((const char*)(gbase) + (voff)[_i]), (PG8_LAS unsigned*)(lds + (bufoff) + ldsw + _i * 8192), 16, 0, 0); } while (0)
; #define PG8_LDA(dst, b, h) do { _Pragma("unroll") for (int m = 0; m < 4; ++m) _Pragma("unroll") for (int k = 0; k < 2; ++k) dst[m][k] = *(const PG8_LAS bf16x8*)(lds + PG8_SA(b, h) + aoff + m * 2048 + k * 1024); } while (0)
; #define PG8_LDB(dst, b, h) do { _Pragma("unroll") for (int n = 0; n < 2; ++n) _Pragma("unroll") for (int k = 0; k < 2; ++k) dst[n][k] = *(const PG8_LAS bf16x8*)(lds + PG8_SB(b, h) + boff + n * 2048 + k * 1024); } while (0)
; #define PG8_MMA(ai, bj, At, Bt) do { __builtin_amdgcn_s_setprio(1); _Pragma("unroll") for (int m = 0; m < 4; ++m) _Pragma("unroll") for (int n = 0; n < 2; ++n) _Pragma("unroll") for (int k = 0; k < 2; ++k) \
;         acc[ai][bj][m][n] = __builtin_amdgcn_mfma_f32_16x16x32_bf16(Bt[n][k], At[m][k], acc[ai][bj][m][n], 0, 0, 0); __builtin_amdgcn_s_setprio(0); } while (0)
; #define PG8_WAIT_L(n) asm volatile("s_waitcnt lgkmcnt(" #n ")" ::: "memory")
; #define PG8_BAR __builtin_amdgcn_s_barrier()
; #define PG8_SCHED __builtin_amdgcn_sched_barrier(0)
; template <class Epi, class Sched>
; __device__ __forceinline__ void gemm_phase(PG8_LAS unsigned char* lds, const Gemm g, const Sched& S, const Epi& E) {
;     ...
;             const bool last = (t == cnk - 2);
;             const char* a1 = cA + (size_t)(t + 1) * kstep;
;             const char* a2 = last ? nA : cA + (size_t)(t + 2) * kstep; const char* b2 = last ? nB : cB + (size_t)(t + 2) * kstep;
;             const char* a3 = a2 + kstep; const char* b3 = b2 + kstep;
;             if (last && has_next) S.a_ready(nxt);
;             if (last) E.prefetch(pre, cur, wr, fr);
;             PG8_LDB(B0, 0, 0); PG8_SCHED; PG8_LDA(At, 0, 0); PG8_STAGE(PG8_SA(1, 1), a1 + hstep, voffA);
;             PG8_WAIT_L(8); PG8_BAR; PG8_WAIT_L(0); PG8_MMA(0, 0, At, B0); PG8_BAR; PG8_SCHED;
;             PG8_LDB(B1, 0, 1); PG8_STAGE(PG8_SB(0, 0), b2, voffB);
;             PG8_BAR; PG8_WAIT_L(0); PG8_MMA(0, 1, At, B1); PG8_BAR;
;             PG8_LDA(At, 0, 1); PG8_STAGE(PG8_SA(0, 0), a2, voffA);
;             PG8_BAR; PG8_WAIT_L(0); PG8_MMA(1, 0, At, B0); PG8_BAR; PG8_SCHED;
.LBB0_1847:
	v_add_u32_e32 v138, s73, v159
	ds_read_b128 v[130:133], v138
	ds_read_b128 v[134:137], v138 offset:1024
	ds_read_b128 v[182:185], v138 offset:2048
	ds_read_b128 v[186:189], v138 offset:3072
	s_add_u32 s14, s0, 0xfffc0080
	s_addc_u32 s15, s1, -1
	s_and_b64 s[12:13], s[12:13], exec
	s_cselect_b32 s15, s11, s15
	s_cselect_b32 s14, s47, s14
	s_cselect_b32 s13, s45, s55
	s_cselect_b32 s12, vcc_lo, vcc_hi
	v_lshl_add_u64 v[138:139], s[0:1], 0, v[166:167]
	s_add_i32 m0, s25, 0xc000
	ds_read_b128 v[190:193], v213
	ds_read_b128 v[194:197], v213 offset:1024
	ds_read_b128 v[198:201], v213 offset:2048
	ds_read_b128 v[202:205], v213 offset:3072
	ds_read_b128 v[218:221], v213 offset:4096
	ds_read_b128 v[222:225], v213 offset:5120
	ds_read_b128 v[226:229], v213 offset:6144
	ds_read_b128 v[230:233], v213 offset:7168
	global_load_lds_dwordx4 v[138:139], off
	s_add_i32 m0, s25, 0xe000
	v_lshl_add_u64 v[138:139], s[0:1], 0, v[168:169]
	global_load_lds_dwordx4 v[138:139], off
	s_waitcnt lgkmcnt(8)
	s_barrier
	s_waitcnt lgkmcnt(0)
	v_mfma_f32_16x16x32_bf16 v[124:127], v[130:133], v[190:193], v[124:127]
	v_mfma_f32_16x16x32_bf16 v[120:123], v[182:185], v[190:193], v[120:123]
	v_mfma_f32_16x16x32_bf16 v[108:111], v[130:133], v[198:201], v[108:111]
	v_mfma_f32_16x16x32_bf16 v[104:107], v[182:185], v[198:201], v[104:107]
	v_mfma_f32_16x16x32_bf16 v[92:95], v[130:133], v[218:221], v[92:95]
	v_mfma_f32_16x16x32_bf16 v[88:91], v[182:185], v[218:221], v[88:91]
	v_mfma_f32_16x16x32_bf16 v[76:79], v[130:133], v[226:229], v[76:79]
	v_mfma_f32_16x16x32_bf16 v[72:75], v[182:185], v[226:229], v[72:75]
	v_mfma_f32_16x16x32_bf16 v[124:127], v[134:137], v[194:197], v[124:127]
	v_mfma_f32_16x16x32_bf16 v[120:123], v[186:189], v[194:197], v[120:123]
	v_mfma_f32_16x16x32_bf16 v[108:111], v[134:137], v[202:205], v[108:111]
	v_mfma_f32_16x16x32_bf16 v[104:107], v[186:189], v[202:205], v[104:107]
	v_mfma_f32_16x16x32_bf16 v[92:95], v[134:137], v[222:225], v[92:95]
	v_mfma_f32_16x16x32_bf16 v[88:91], v[186:189], v[222:225], v[88:91]
	v_mfma_f32_16x16x32_bf16 v[76:79], v[134:137], v[230:233], v[76:79]
	v_mfma_f32_16x16x32_bf16 v[72:75], v[186:189], v[230:233], v[72:75]
	s_barrier
	v_add_u32_e32 v138, s74, v159
	s_add_i32 s30, s73, s24
	ds_read_b128 v[234:237], v138
	ds_read_b128 v[238:241], v138 offset:1024
	ds_read_b128 v[242:245], v138 offset:2048
	ds_read_b128 v[246:249], v138 offset:3072
	v_lshl_add_u64 v[138:139], s[12:13], 0, v[142:143]
	s_mov_b32 m0, s30
	v_lshl_add_u64 v[206:207], s[12:13], 0, v[146:147]
	global_load_lds_dwordx4 v[138:139], off
	s_add_i32 m0, s30, 0x2000
	s_nop 0
	global_load_lds_dwordx4 v[206:207], off
	s_barrier
	s_waitcnt lgkmcnt(0)
	v_mfma_f32_16x16x32_bf16 v[116:119], v[234:237], v[190:193], v[116:119]
	v_mfma_f32_16x16x32_bf16 v[112:115], v[242:245], v[190:193], v[112:115]
	v_mfma_f32_16x16x32_bf16 v[100:103], v[234:237], v[198:201], v[100:103]
	v_mfma_f32_16x16x32_bf16 v[96:99], v[242:245], v[198:201], v[96:99]
	v_mfma_f32_16x16x32_bf16 v[84:87], v[234:237], v[218:221], v[84:87]
	v_mfma_f32_16x16x32_bf16 v[80:83], v[242:245], v[218:221], v[80:83]
	v_mfma_f32_16x16x32_bf16 v[68:71], v[234:237], v[226:229], v[68:71]
	v_mfma_f32_16x16x32_bf16 v[64:67], v[242:245], v[226:229], v[64:67]
	v_mfma_f32_16x16x32_bf16 v[116:119], v[238:241], v[194:197], v[116:119]
	v_mfma_f32_16x16x32_bf16 v[112:115], v[246:249], v[194:197], v[112:115]
	v_mfma_f32_16x16x32_bf16 v[100:103], v[238:241], v[202:205], v[100:103]
	v_mfma_f32_16x16x32_bf16 v[96:99], v[246:249], v[202:205], v[96:99]
	v_mfma_f32_16x16x32_bf16 v[84:87], v[238:241], v[222:225], v[84:87]
	v_mfma_f32_16x16x32_bf16 v[80:83], v[246:249], v[222:225], v[80:83]
	v_mfma_f32_16x16x32_bf16 v[68:71], v[238:241], v[230:233], v[68:71]
	v_mfma_f32_16x16x32_bf16 v[64:67], v[246:249], v[230:233], v[64:67]
	s_mov_b32 m0, s25
	v_lshl_add_u64 v[250:251], s[14:15], 0, v[140:141]
	s_barrier
	ds_read_b128 v[190:193], v213 offset:16384
	ds_read_b128 v[194:197], v213 offset:17408
	ds_read_b128 v[198:201], v213 offset:18432
	ds_read_b128 v[202:205], v213 offset:19456
	ds_read_b128 v[218:221], v213 offset:20480
	ds_read_b128 v[222:225], v213 offset:21504
	ds_read_b128 v[226:229], v213 offset:22528
	ds_read_b128 v[230:233], v213 offset:23552
	global_load_lds_dwordx4 v[250:251], off
	s_mov_b32 m0, s27
	v_lshl_add_u64 v[252:253], s[14:15], 0, v[144:145]
	global_load_lds_dwordx4 v[252:253], off
	s_barrier
	s_waitcnt lgkmcnt(0)
	v_mfma_f32_16x16x32_bf16 v[60:63], v[130:133], v[190:193], v[60:63]
	v_mfma_f32_16x16x32_bf16 v[56:59], v[182:185], v[190:193], v[56:59]
	v_mfma_f32_16x16x32_bf16 v[44:47], v[130:133], v[198:201], v[44:47]
	v_mfma_f32_16x16x32_bf16 v[40:43], v[182:185], v[198:201], v[40:43]
	v_mfma_f32_16x16x32_bf16 v[28:31], v[130:133], v[218:221], v[28:31]
	v_mfma_f32_16x16x32_bf16 v[24:27], v[182:185], v[218:221], v[24:27]
	v_mfma_f32_16x16x32_bf16 v[12:15], v[130:133], v[226:229], v[12:15]
	v_mfma_f32_16x16x32_bf16 v[8:11], v[182:185], v[226:229], v[8:11]
	v_mfma_f32_16x16x32_bf16 v[60:63], v[134:137], v[194:197], v[60:63]
	v_mfma_f32_16x16x32_bf16 v[56:59], v[186:189], v[194:197], v[56:59]
	v_mfma_f32_16x16x32_bf16 v[44:47], v[134:137], v[202:205], v[44:47]
	v_mfma_f32_16x16x32_bf16 v[40:43], v[186:189], v[202:205], v[40:43]
	v_mfma_f32_16x16x32_bf16 v[28:31], v[134:137], v[222:225], v[28:31]
	v_mfma_f32_16x16x32_bf16 v[24:27], v[186:189], v[222:225], v[24:27]
	v_mfma_f32_16x16x32_bf16 v[12:15], v[134:137], v[230:233], v[12:15]
	v_mfma_f32_16x16x32_bf16 v[8:11], v[186:189], v[230:233], v[8:11]
	s_barrier
; #define PG8_STAGE(bufoff, gbase, voff) do { _Pragma("unroll") for (int _i = 0; _i < 2; ++_i) \
;         __builtin_amdgcn_global_load_lds((const unsigned*)((const char*)(gbase) + (voff)[_i]), (PG8_LAS unsigned*)(lds + (bufoff) + ldsw + _i * 8192), 16, 0, 0); } while (0)
; #define PG8_LDA(dst, b, h) do { _Pragma("unroll") for (int m = 0; m < 4; ++m) _Pragma("unroll") for (int k = 0; k < 2; ++k) dst[m][k] = *(const PG8_LAS bf16x8*)(lds + PG8_SA(b, h) + aoff + m * 2048 + k * 1024); } while (0)
; #define PG8_LDB(dst, b, h) do { _Pragma("unroll") for (int n = 0; n < 2; ++n) _Pragma("unroll") for (int k = 0; k < 2; ++k) dst[n][k] = *(const PG8_LAS bf16x8*)(lds + PG8_SB(b, h) + boff + n * 2048 + k * 1024); } while (0)
; #define PG8_MMA(ai, bj, At, Bt) do { __builtin_amdgcn_s_setprio(1); _Pragma("unroll") for (int m = 0; m < 4; ++m) _Pragma("unroll") for (int n = 0; n < 2; ++n) _Pragma("unroll") for (int k = 0; k < 2; ++k) \
;         acc[ai][bj][m][n] = __builtin_amdgcn_mfma_f32_16x16x32_bf16(Bt[n][k], At[m][k], acc[ai][bj][m][n], 0, 0, 0); __builtin_amdgcn_s_setprio(0); } while (0)
; #define PG8_WAIT_V(n) asm volatile("s_waitcnt vmcnt(" #n ")" ::: "memory")
; #define PG8_WAIT_L(n) asm volatile("s_waitcnt lgkmcnt(" #n ")" ::: "memory")
; #define PG8_BAR __builtin_amdgcn_s_barrier()
; #define PG8_SCHED __builtin_amdgcn_sched_barrier(0)
; template <class Epi, class Sched>
; __device__ __forceinline__ void gemm_phase(PG8_LAS unsigned char* lds, const Gemm g, const Sched& S, const Epi& E) {
;     ...
;             PG8_STAGE(PG8_SB(0, 1), b2 + hstep, voffB);
;             PG8_WAIT_V(6); PG8_BAR; PG8_MMA(1, 1, At, B1); PG8_BAR;
;             PG8_LDB(B0, 1, 0); PG8_SCHED; PG8_LDA(At, 1, 0); PG8_STAGE(PG8_SA(0, 1), a2 + hstep, voffA);
;             PG8_WAIT_L(8); PG8_BAR; PG8_WAIT_L(0); PG8_MMA(0, 0, At, B0); PG8_BAR; PG8_SCHED;
;             PG8_LDB(B1, 1, 1); PG8_STAGE(PG8_SB(1, 0), b3, voffB);
	s_add_u32 s96, s12, 0x40000
	s_addc_u32 s97, s13, 0
	s_add_i32 s30, s74, s24
	s_mov_b32 m0, s30
	v_lshl_add_u64 v[130:131], s[96:97], 0, v[142:143]
	global_load_lds_dwordx4 v[130:131], off
	s_add_i32 m0, s30, 0x2000
	v_lshl_add_u64 v[130:131], s[96:97], 0, v[146:147]
	global_load_lds_dwordx4 v[130:131], off
	s_waitcnt vmcnt(6)
	s_barrier
	v_mfma_f32_16x16x32_bf16 v[52:55], v[234:237], v[190:193], v[52:55]
	v_mfma_f32_16x16x32_bf16 v[48:51], v[242:245], v[190:193], v[48:51]
	v_mfma_f32_16x16x32_bf16 v[36:39], v[234:237], v[198:201], v[36:39]
	v_mfma_f32_16x16x32_bf16 v[32:35], v[242:245], v[198:201], v[32:35]
	v_mfma_f32_16x16x32_bf16 v[20:23], v[234:237], v[218:221], v[20:23]
	v_mfma_f32_16x16x32_bf16 v[16:19], v[242:245], v[218:221], v[16:19]
	v_mfma_f32_16x16x32_bf16 v[4:7], v[234:237], v[226:229], v[4:7]
	v_mfma_f32_16x16x32_bf16 v[0:3], v[242:245], v[226:229], v[0:3]
	v_mfma_f32_16x16x32_bf16 v[52:55], v[238:241], v[194:197], v[52:55]
	v_mfma_f32_16x16x32_bf16 v[48:51], v[246:249], v[194:197], v[48:51]
	v_mfma_f32_16x16x32_bf16 v[36:39], v[238:241], v[202:205], v[36:39]
	v_mfma_f32_16x16x32_bf16 v[32:35], v[246:249], v[202:205], v[32:35]
	v_mfma_f32_16x16x32_bf16 v[20:23], v[238:241], v[222:225], v[20:23]
	v_mfma_f32_16x16x32_bf16 v[16:19], v[246:249], v[222:225], v[16:19]
	v_mfma_f32_16x16x32_bf16 v[4:7], v[238:241], v[230:233], v[4:7]
	v_mfma_f32_16x16x32_bf16 v[0:3], v[246:249], v[230:233], v[0:3]
	s_add_i32 s30, 0, 0x18000
	v_add_u32_e32 v148, s30, v159
	s_barrier
	ds_read_b128 v[130:133], v148
	ds_read_b128 v[134:137], v148 offset:1024
	ds_read_b128 v[182:185], v148 offset:2048
	ds_read_b128 v[186:189], v148 offset:3072
	s_add_u32 s14, s14, 0x40000
	s_addc_u32 s15, s15, 0
	s_mov_b32 m0, s29
	v_lshl_add_u64 v[234:235], s[14:15], 0, v[140:141]
	ds_read_b128 v[190:193], v213 offset:32768
	ds_read_b128 v[194:197], v213 offset:33792
	ds_read_b128 v[198:201], v213 offset:34816
	ds_read_b128 v[202:205], v213 offset:35840
	ds_read_b128 v[218:221], v213 offset:36864
	ds_read_b128 v[222:225], v213 offset:37888
	ds_read_b128 v[226:229], v213 offset:38912
	ds_read_b128 v[230:233], v213 offset:39936
	global_load_lds_dwordx4 v[234:235], off
	s_mov_b32 m0, s33
	v_lshl_add_u64 v[234:235], s[14:15], 0, v[144:145]
	global_load_lds_dwordx4 v[234:235], off
	s_waitcnt lgkmcnt(8)
	s_barrier
	s_waitcnt lgkmcnt(0)
	v_mfma_f32_16x16x32_bf16 v[124:127], v[130:133], v[190:193], v[124:127]
	v_mfma_f32_16x16x32_bf16 v[120:123], v[182:185], v[190:193], v[120:123]
	v_mfma_f32_16x16x32_bf16 v[108:111], v[130:133], v[198:201], v[108:111]
	v_mfma_f32_16x16x32_bf16 v[104:107], v[182:185], v[198:201], v[104:107]
	v_mfma_f32_16x16x32_bf16 v[92:95], v[130:133], v[218:221], v[92:95]
	v_mfma_f32_16x16x32_bf16 v[88:91], v[182:185], v[218:221], v[88:91]
	v_mfma_f32_16x16x32_bf16 v[76:79], v[130:133], v[226:229], v[76:79]
	v_mfma_f32_16x16x32_bf16 v[72:75], v[182:185], v[226:229], v[72:75]
	v_mfma_f32_16x16x32_bf16 v[124:127], v[134:137], v[194:197], v[124:127]
	v_mfma_f32_16x16x32_bf16 v[120:123], v[186:189], v[194:197], v[120:123]
	v_mfma_f32_16x16x32_bf16 v[108:111], v[134:137], v[202:205], v[108:111]
	v_mfma_f32_16x16x32_bf16 v[104:107], v[186:189], v[202:205], v[104:107]
	v_mfma_f32_16x16x32_bf16 v[92:95], v[134:137], v[222:225], v[92:95]
	v_mfma_f32_16x16x32_bf16 v[88:91], v[186:189], v[222:225], v[88:91]
	v_mfma_f32_16x16x32_bf16 v[76:79], v[134:137], v[230:233], v[76:79]
	v_mfma_f32_16x16x32_bf16 v[72:75], v[186:189], v[230:233], v[72:75]
	s_barrier
	s_add_i32 s14, 0, 0x1c000
	s_add_i32 s15, s30, s24
	v_add_u32_e32 v148, s14, v159
	v_lshl_add_u64 v[138:139], v[138:139], 0, s[20:21]
	s_mov_b32 m0, s15
	ds_read_b128 v[234:237], v148
	ds_read_b128 v[238:241], v148 offset:1024
	ds_read_b128 v[242:245], v148 offset:2048
	ds_read_b128 v[246:249], v148 offset:3072
	global_load_lds_dwordx4 v[138:139], off
	s_add_i32 m0, s15, 0x2000
	v_lshl_add_u64 v[138:139], v[206:207], 0, s[20:21]
	global_load_lds_dwordx4 v[138:139], off
	s_barrier
; #define PG8_STAGE(bufoff, gbase, voff) do { _Pragma("unroll") for (int _i = 0; _i < 2; ++_i) \
;         __builtin_amdgcn_global_load_lds((const unsigned*)((const char*)(gbase) + (voff)[_i]), (PG8_LAS unsigned*)(lds + (bufoff) + ldsw + _i * 8192), 16, 0, 0); } while (0)
; #define PG8_LDA(dst, b, h) do { _Pragma("unroll") for (int m = 0; m < 4; ++m) _Pragma("unroll") for (int k = 0; k < 2; ++k) dst[m][k] = *(const PG8_LAS bf16x8*)(lds + PG8_SA(b, h) + aoff + m * 2048 + k * 1024); } while (0)
; #define PG8_MMA(ai, bj, At, Bt) do { __builtin_amdgcn_s_setprio(1); _Pragma("unroll") for (int m = 0; m < 4; ++m) _Pragma("unroll") for (int n = 0; n < 2; ++n) _Pragma("unroll") for (int k = 0; k < 2; ++k) \
;         acc[ai][bj][m][n] = __builtin_amdgcn_mfma_f32_16x16x32_bf16(Bt[n][k], At[m][k], acc[ai][bj][m][n], 0, 0, 0); __builtin_amdgcn_s_setprio(0); } while (0)
; #define PG8_WAIT_V(n) asm volatile("s_waitcnt vmcnt(" #n ")" ::: "memory")
; #define PG8_WAIT_L(n) asm volatile("s_waitcnt lgkmcnt(" #n ")" ::: "memory")
; #define PG8_BAR __builtin_amdgcn_s_barrier()
; #define PG8_SCHED __builtin_amdgcn_sched_barrier(0)
; template <class Epi, class Sched>
; __device__ __forceinline__ void gemm_phase(PG8_LAS unsigned char* lds, const Gemm g, const Sched& S, const Epi& E) {
;     ...
;             PG8_BAR; PG8_WAIT_L(0); PG8_MMA(0, 1, At, B1); PG8_BAR;
;             PG8_LDA(At, 1, 1); PG8_STAGE(PG8_SA(1, 0), a3, voffA);
;             PG8_BAR; PG8_WAIT_L(0); PG8_MMA(1, 0, At, B0); PG8_BAR; PG8_SCHED;
;             PG8_STAGE(PG8_SB(1, 1), b3 + hstep, voffB);
;             PG8_WAIT_V(6); PG8_BAR; PG8_MMA(1, 1, At, B1); PG8_BAR;
;         }
	s_waitcnt lgkmcnt(0)
	v_mfma_f32_16x16x32_bf16 v[116:119], v[234:237], v[190:193], v[116:119]
	v_mfma_f32_16x16x32_bf16 v[112:115], v[242:245], v[190:193], v[112:115]
	v_mfma_f32_16x16x32_bf16 v[100:103], v[234:237], v[198:201], v[100:103]
	v_mfma_f32_16x16x32_bf16 v[96:99], v[242:245], v[198:201], v[96:99]
	v_mfma_f32_16x16x32_bf16 v[84:87], v[234:237], v[218:221], v[84:87]
	v_mfma_f32_16x16x32_bf16 v[80:83], v[242:245], v[218:221], v[80:83]
	v_mfma_f32_16x16x32_bf16 v[68:71], v[234:237], v[226:229], v[68:71]
	v_mfma_f32_16x16x32_bf16 v[64:67], v[242:245], v[226:229], v[64:67]
	v_mfma_f32_16x16x32_bf16 v[116:119], v[238:241], v[194:197], v[116:119]
	v_mfma_f32_16x16x32_bf16 v[112:115], v[246:249], v[194:197], v[112:115]
	v_mfma_f32_16x16x32_bf16 v[100:103], v[238:241], v[202:205], v[100:103]
	v_mfma_f32_16x16x32_bf16 v[96:99], v[246:249], v[202:205], v[96:99]
	v_mfma_f32_16x16x32_bf16 v[84:87], v[238:241], v[222:225], v[84:87]
	v_mfma_f32_16x16x32_bf16 v[80:83], v[246:249], v[222:225], v[80:83]
	v_mfma_f32_16x16x32_bf16 v[68:71], v[238:241], v[230:233], v[68:71]
	v_mfma_f32_16x16x32_bf16 v[64:67], v[246:249], v[230:233], v[64:67]
	s_mov_b32 m0, s16
	v_lshl_add_u64 v[138:139], v[250:251], 0, s[20:21]
	s_barrier
	ds_read_b128 v[190:193], v213 offset:49152
	ds_read_b128 v[194:197], v213 offset:50176
	ds_read_b128 v[198:201], v213 offset:51200
	ds_read_b128 v[202:205], v213 offset:52224
	ds_read_b128 v[218:221], v213 offset:53248
	ds_read_b128 v[222:225], v213 offset:54272
	ds_read_b128 v[226:229], v213 offset:55296
	ds_read_b128 v[230:233], v213 offset:56320
	global_load_lds_dwordx4 v[138:139], off
	s_mov_b32 m0, s17
	v_lshl_add_u64 v[138:139], v[252:253], 0, s[20:21]
	global_load_lds_dwordx4 v[138:139], off
	s_barrier
	s_waitcnt lgkmcnt(0)
	v_mfma_f32_16x16x32_bf16 v[60:63], v[130:133], v[190:193], v[60:63]
	v_mfma_f32_16x16x32_bf16 v[56:59], v[182:185], v[190:193], v[56:59]
	v_mfma_f32_16x16x32_bf16 v[44:47], v[130:133], v[198:201], v[44:47]
	v_mfma_f32_16x16x32_bf16 v[40:43], v[182:185], v[198:201], v[40:43]
	v_mfma_f32_16x16x32_bf16 v[28:31], v[130:133], v[218:221], v[28:31]
	v_mfma_f32_16x16x32_bf16 v[24:27], v[182:185], v[218:221], v[24:27]
	v_mfma_f32_16x16x32_bf16 v[12:15], v[130:133], v[226:229], v[12:15]
	v_mfma_f32_16x16x32_bf16 v[8:11], v[182:185], v[226:229], v[8:11]
	v_mfma_f32_16x16x32_bf16 v[60:63], v[134:137], v[194:197], v[60:63]
	v_mfma_f32_16x16x32_bf16 v[56:59], v[186:189], v[194:197], v[56:59]
	v_mfma_f32_16x16x32_bf16 v[44:47], v[134:137], v[202:205], v[44:47]
	v_mfma_f32_16x16x32_bf16 v[40:43], v[186:189], v[202:205], v[40:43]
	v_mfma_f32_16x16x32_bf16 v[28:31], v[134:137], v[222:225], v[28:31]
	v_mfma_f32_16x16x32_bf16 v[24:27], v[186:189], v[222:225], v[24:27]
	v_mfma_f32_16x16x32_bf16 v[12:15], v[134:137], v[230:233], v[12:15]
	v_mfma_f32_16x16x32_bf16 v[8:11], v[186:189], v[230:233], v[8:11]
	s_barrier
	s_add_u32 s12, s12, 0x40080
	s_addc_u32 s13, s13, 0
	s_add_i32 s14, s14, s24
	s_mov_b32 m0, s14
	v_lshl_add_u64 v[130:131], s[12:13], 0, v[142:143]
	global_load_lds_dwordx4 v[130:131], off
	s_add_i32 m0, s14, 0x2000
	v_lshl_add_u64 v[130:131], s[12:13], 0, v[146:147]
	global_load_lds_dwordx4 v[130:131], off
	s_waitcnt vmcnt(6)
	s_barrier
	v_mfma_f32_16x16x32_bf16 v[52:55], v[234:237], v[190:193], v[52:55]
	v_mfma_f32_16x16x32_bf16 v[48:51], v[242:245], v[190:193], v[48:51]
	v_mfma_f32_16x16x32_bf16 v[36:39], v[234:237], v[198:201], v[36:39]
	v_mfma_f32_16x16x32_bf16 v[32:35], v[242:245], v[198:201], v[32:35]
	v_mfma_f32_16x16x32_bf16 v[20:23], v[234:237], v[218:221], v[20:23]
	v_mfma_f32_16x16x32_bf16 v[16:19], v[242:245], v[218:221], v[16:19]
	v_mfma_f32_16x16x32_bf16 v[4:7], v[234:237], v[226:229], v[4:7]
	v_mfma_f32_16x16x32_bf16 v[0:3], v[242:245], v[226:229], v[0:3]
	v_mfma_f32_16x16x32_bf16 v[52:55], v[238:241], v[194:197], v[52:55]
	v_mfma_f32_16x16x32_bf16 v[48:51], v[246:249], v[194:197], v[48:51]
	v_mfma_f32_16x16x32_bf16 v[36:39], v[238:241], v[202:205], v[36:39]
	v_mfma_f32_16x16x32_bf16 v[32:35], v[246:249], v[202:205], v[32:35]
	v_mfma_f32_16x16x32_bf16 v[20:23], v[238:241], v[222:225], v[20:23]
	v_mfma_f32_16x16x32_bf16 v[16:19], v[246:249], v[222:225], v[16:19]
	v_mfma_f32_16x16x32_bf16 v[4:7], v[238:241], v[230:233], v[4:7]
	v_mfma_f32_16x16x32_bf16 v[0:3], v[246:249], v[230:233], v[0:3]
	s_add_i32 s5, s5, 2
	s_add_u32 s0, s0, 0x100
	s_addc_u32 s1, s1, 0
	s_add_u32 vcc_hi, vcc_hi, 0x100
	s_addc_u32 s55, s55, 0
	s_cmp_lt_u32 s5, 14
	s_barrier
	s_cbranch_scc0 .LBB0_1850

; #define PG8_STAGE(bufoff, gbase, voff) do { _Pragma("unroll") for (int _i = 0; _i < 2; ++_i) \
;         __builtin_amdgcn_global_load_lds((const unsigned*)((const char*)(gbase) + (voff)[_i]), (PG8_LAS unsigned*)(lds + (bufoff) + ldsw + _i * 8192), 16, 0, 0); } while (0)
; #define PG8_LDA(dst, b, h) do { _Pragma("unroll") for (int m = 0; m < 4; ++m) _Pragma("unroll") for (int k = 0; k < 2; ++k) dst[m][k] = *(const PG8_LAS bf16x8*)(lds + PG8_SA(b, h) + aoff + m * 2048 + k * 1024); } while (0)
; #define PG8_LDB(dst, b, h) do { _Pragma("unroll") for (int n = 0; n < 2; ++n) _Pragma("unroll") for (int k = 0; k < 2; ++k) dst[n][k] = *(const PG8_LAS bf16x8*)(lds + PG8_SB(b, h) + boff + n * 2048 + k * 1024); } while (0)
; #define PG8_MMA(ai, bj, At, Bt) do { __builtin_amdgcn_s_setprio(1); _Pragma("unroll") for (int m = 0; m < 4; ++m) _Pragma("unroll") for (int n = 0; n < 2; ++n) _Pragma("unroll") for (int k = 0; k < 2; ++k) \
;         acc[ai][bj][m][n] = __builtin_amdgcn_mfma_f32_16x16x32_bf16(Bt[n][k], At[m][k], acc[ai][bj][m][n], 0, 0, 0); __builtin_amdgcn_s_setprio(0); } while (0)
; #define PG8_WAIT_V(n) asm volatile("s_waitcnt vmcnt(" #n ")" ::: "memory")
; template <class Epi, class Sched>
; __device__ __forceinline__ void gemm_phase(PG8_LAS unsigned char* lds, const Gemm g, const Sched& S, const Epi& E) {
;     ...
;             const bool last = (t == cnk - 2);
;             const char* a1 = cA + (size_t)(t + 1) * kstep;
;             const char* a2 = last ? nA : cA + (size_t)(t + 2) * kstep; const char* b2 = last ? nB : cB + (size_t)(t + 2) * kstep;
;             const char* a3 = a2 + kstep; const char* b3 = b2 + kstep;
;             if (last && has_next) S.a_ready(nxt);
;             if (last) E.prefetch(pre, cur, wr, fr);
;             PG8_LDB(B0, 0, 0); PG8_SCHED; PG8_LDA(At, 0, 0); PG8_STAGE(PG8_SA(1, 1), a1 + hstep, voffA);
;             PG8_WAIT_L(8); PG8_BAR; PG8_WAIT_L(0); PG8_MMA(0, 0, At, B0); PG8_BAR; PG8_SCHED;
;             PG8_LDB(B1, 0, 1); PG8_STAGE(PG8_SB(0, 0), b2, voffB);
;             PG8_BAR; PG8_WAIT_L(0); PG8_MMA(0, 1, At, B1); PG8_BAR;
;             PG8_LDA(At, 0, 1); PG8_STAGE(PG8_SA(0, 0), a2, voffA);
;             PG8_BAR; PG8_WAIT_L(0); PG8_MMA(1, 0, At, B0); PG8_BAR; PG8_SCHED;
;             PG8_STAGE(PG8_SB(0, 1), b2 + hstep, voffB);
;             PG8_WAIT_V(6); PG8_BAR; PG8_MMA(1, 1, At, B1); PG8_BAR;
.LBB0_2251:
	ds_read_b128 v[128:131], v192
	ds_read_b128 v[132:135], v192 offset:1024
	ds_read_b128 v[136:139], v192 offset:2048
	ds_read_b128 v[140:143], v192 offset:3072
	s_add_i32 s70, s43, 2
	s_add_u32 s30, s46, 0xfffc0080
	s_addc_u32 s48, s47, -1
	s_cmp_eq_u32 s25, s43
	s_cselect_b32 s51, s41, s48
	s_cselect_b32 s50, s40, s30
	s_cselect_b32 s49, s45, s37
	s_cselect_b32 s48, s44, s27
	v_lshl_add_u64 v[190:191], s[46:47], 0, v[168:169]
	s_add_i32 m0, s5, 0xc000
	ds_read_b128 v[144:147], v193
	ds_read_b128 v[148:151], v193 offset:1024
	ds_read_b128 v[174:177], v193 offset:2048
	ds_read_b128 v[178:181], v193 offset:3072
	ds_read_b128 v[182:185], v193 offset:4096
	ds_read_b128 v[186:189], v193 offset:5120
	ds_read_b128 v[196:199], v193 offset:6144
	ds_read_b128 v[200:203], v193 offset:7168
	global_load_lds_dwordx4 v[190:191], off
	s_add_i32 m0, s5, 0xe000
	v_lshl_add_u64 v[190:191], s[46:47], 0, v[170:171]
	global_load_lds_dwordx4 v[190:191], off
	s_waitcnt lgkmcnt(8)
	s_barrier
	s_waitcnt lgkmcnt(0)
	v_mfma_f32_16x16x32_bf16 v[124:127], v[128:131], v[144:147], v[124:127]
	v_mfma_f32_16x16x32_bf16 v[120:123], v[136:139], v[144:147], v[120:123]
	v_mfma_f32_16x16x32_bf16 v[108:111], v[128:131], v[174:177], v[108:111]
	v_mfma_f32_16x16x32_bf16 v[104:107], v[136:139], v[174:177], v[104:107]
	v_mfma_f32_16x16x32_bf16 v[92:95], v[128:131], v[182:185], v[92:95]
	v_mfma_f32_16x16x32_bf16 v[88:91], v[136:139], v[182:185], v[88:91]
	v_mfma_f32_16x16x32_bf16 v[76:79], v[128:131], v[196:199], v[76:79]
	v_mfma_f32_16x16x32_bf16 v[72:75], v[136:139], v[196:199], v[72:75]
	v_mfma_f32_16x16x32_bf16 v[124:127], v[132:135], v[148:151], v[124:127]
	v_mfma_f32_16x16x32_bf16 v[120:123], v[140:143], v[148:151], v[120:123]
	v_mfma_f32_16x16x32_bf16 v[108:111], v[132:135], v[178:181], v[108:111]
	v_mfma_f32_16x16x32_bf16 v[104:107], v[140:143], v[178:181], v[104:107]
	v_mfma_f32_16x16x32_bf16 v[92:95], v[132:135], v[186:189], v[92:95]
	v_mfma_f32_16x16x32_bf16 v[88:91], v[140:143], v[186:189], v[88:91]
	v_mfma_f32_16x16x32_bf16 v[76:79], v[132:135], v[200:203], v[76:79]
	v_mfma_f32_16x16x32_bf16 v[72:75], v[140:143], v[200:203], v[72:75]
	s_barrier
	s_add_i32 s30, s53, s4
	v_lshl_add_u64 v[190:191], s[48:49], 0, v[160:161]
	s_mov_b32 m0, s30
	ds_read_b128 v[204:207], v194
	ds_read_b128 v[208:211], v194 offset:1024
	ds_read_b128 v[212:215], v194 offset:2048
	ds_read_b128 v[216:219], v194 offset:3072
	global_load_lds_dwordx4 v[190:191], off
	s_add_i32 m0, s30, 0x2000
	v_lshl_add_u64 v[220:221], s[48:49], 0, v[164:165]
	global_load_lds_dwordx4 v[220:221], off
	s_barrier
	s_waitcnt lgkmcnt(0)
	v_mfma_f32_16x16x32_bf16 v[116:119], v[204:207], v[144:147], v[116:119]
	v_mfma_f32_16x16x32_bf16 v[112:115], v[212:215], v[144:147], v[112:115]
	v_mfma_f32_16x16x32_bf16 v[100:103], v[204:207], v[174:177], v[100:103]
	v_mfma_f32_16x16x32_bf16 v[96:99], v[212:215], v[174:177], v[96:99]
	v_mfma_f32_16x16x32_bf16 v[84:87], v[204:207], v[182:185], v[84:87]
	v_mfma_f32_16x16x32_bf16 v[80:83], v[212:215], v[182:185], v[80:83]
	v_mfma_f32_16x16x32_bf16 v[68:71], v[204:207], v[196:199], v[68:71]
	v_mfma_f32_16x16x32_bf16 v[64:67], v[212:215], v[196:199], v[64:67]
	v_mfma_f32_16x16x32_bf16 v[116:119], v[208:211], v[148:151], v[116:119]
	v_mfma_f32_16x16x32_bf16 v[112:115], v[216:219], v[148:151], v[112:115]
	v_mfma_f32_16x16x32_bf16 v[100:103], v[208:211], v[178:181], v[100:103]
	v_mfma_f32_16x16x32_bf16 v[96:99], v[216:219], v[178:181], v[96:99]
	v_mfma_f32_16x16x32_bf16 v[84:87], v[208:211], v[186:189], v[84:87]
	v_mfma_f32_16x16x32_bf16 v[80:83], v[216:219], v[186:189], v[80:83]
	v_mfma_f32_16x16x32_bf16 v[68:71], v[208:211], v[200:203], v[68:71]
	v_mfma_f32_16x16x32_bf16 v[64:67], v[216:219], v[200:203], v[64:67]
	s_mov_b32 m0, s5
	v_lshl_add_u64 v[222:223], s[50:51], 0, v[158:159]
	s_barrier
	ds_read_b128 v[144:147], v193 offset:16384
	ds_read_b128 v[148:151], v193 offset:17408
	ds_read_b128 v[174:177], v193 offset:18432
	ds_read_b128 v[178:181], v193 offset:19456
	ds_read_b128 v[182:185], v193 offset:20480
	ds_read_b128 v[186:189], v193 offset:21504
	ds_read_b128 v[196:199], v193 offset:22528
	ds_read_b128 v[200:203], v193 offset:23552
	global_load_lds_dwordx4 v[222:223], off
	s_mov_b32 m0, s6
	v_lshl_add_u64 v[224:225], s[50:51], 0, v[162:163]
	global_load_lds_dwordx4 v[224:225], off
	s_barrier
	s_waitcnt lgkmcnt(0)
	v_mfma_f32_16x16x32_bf16 v[60:63], v[128:131], v[144:147], v[60:63]
	v_mfma_f32_16x16x32_bf16 v[56:59], v[136:139], v[144:147], v[56:59]
	v_mfma_f32_16x16x32_bf16 v[44:47], v[128:131], v[174:177], v[44:47]
	v_mfma_f32_16x16x32_bf16 v[40:43], v[136:139], v[174:177], v[40:43]
	v_mfma_f32_16x16x32_bf16 v[28:31], v[128:131], v[182:185], v[28:31]
	v_mfma_f32_16x16x32_bf16 v[24:27], v[136:139], v[182:185], v[24:27]
	v_mfma_f32_16x16x32_bf16 v[12:15], v[128:131], v[196:199], v[12:15]
	v_mfma_f32_16x16x32_bf16 v[8:11], v[136:139], v[196:199], v[8:11]
	v_mfma_f32_16x16x32_bf16 v[60:63], v[132:135], v[148:151], v[60:63]
	v_mfma_f32_16x16x32_bf16 v[56:59], v[140:143], v[148:151], v[56:59]
	v_mfma_f32_16x16x32_bf16 v[44:47], v[132:135], v[178:181], v[44:47]
	v_mfma_f32_16x16x32_bf16 v[40:43], v[140:143], v[178:181], v[40:43]
	v_mfma_f32_16x16x32_bf16 v[28:31], v[132:135], v[186:189], v[28:31]
	v_mfma_f32_16x16x32_bf16 v[24:27], v[140:143], v[186:189], v[24:27]
	v_mfma_f32_16x16x32_bf16 v[12:15], v[132:135], v[200:203], v[12:15]
	v_mfma_f32_16x16x32_bf16 v[8:11], v[140:143], v[200:203], v[8:11]
	s_barrier
	s_add_u32 s72, s48, 0x40000
	s_addc_u32 s73, s49, 0
	s_add_i32 s30, s54, s4
	s_mov_b32 m0, s30
	v_lshl_add_u64 v[128:129], s[72:73], 0, v[160:161]
	global_load_lds_dwordx4 v[128:129], off
	s_add_i32 m0, s30, 0x2000
	v_lshl_add_u64 v[128:129], s[72:73], 0, v[164:165]
	global_load_lds_dwordx4 v[128:129], off
	s_waitcnt vmcnt(6)
	s_barrier
; #define PG8_STAGE(bufoff, gbase, voff) do { _Pragma("unroll") for (int _i = 0; _i < 2; ++_i) \
;         __builtin_amdgcn_global_load_lds((const unsigned*)((const char*)(gbase) + (voff)[_i]), (PG8_LAS unsigned*)(lds + (bufoff) + ldsw + _i * 8192), 16, 0, 0); } while (0)
; #define PG8_LDA(dst, b, h) do { _Pragma("unroll") for (int m = 0; m < 4; ++m) _Pragma("unroll") for (int k = 0; k < 2; ++k) dst[m][k] = *(const PG8_LAS bf16x8*)(lds + PG8_SA(b, h) + aoff + m * 2048 + k * 1024); } while (0)
; #define PG8_LDB(dst, b, h) do { _Pragma("unroll") for (int n = 0; n < 2; ++n) _Pragma("unroll") for (int k = 0; k < 2; ++k) dst[n][k] = *(const PG8_LAS bf16x8*)(lds + PG8_SB(b, h) + boff + n * 2048 + k * 1024); } while (0)
; #define PG8_MMA(ai, bj, At, Bt) do { __builtin_amdgcn_s_setprio(1); _Pragma("unroll") for (int m = 0; m < 4; ++m) _Pragma("unroll") for (int n = 0; n < 2; ++n) _Pragma("unroll") for (int k = 0; k < 2; ++k) \
;         acc[ai][bj][m][n] = __builtin_amdgcn_mfma_f32_16x16x32_bf16(Bt[n][k], At[m][k], acc[ai][bj][m][n], 0, 0, 0); __builtin_amdgcn_s_setprio(0); } while (0)
; #define PG8_WAIT_V(n) asm volatile("s_waitcnt vmcnt(" #n ")" ::: "memory")
; #define PG8_WAIT_L(n) asm volatile("s_waitcnt lgkmcnt(" #n ")" ::: "memory")
; #define PG8_BAR __builtin_amdgcn_s_barrier()
; #define PG8_SCHED __builtin_amdgcn_sched_barrier(0)
; template <class Epi, class Sched>
; __device__ __forceinline__ void gemm_phase(PG8_LAS unsigned char* lds, const Gemm g, const Sched& S, const Epi& E) {
;     ...
;             PG8_WAIT_V(6); PG8_BAR; PG8_MMA(1, 1, At, B1); PG8_BAR;
;             PG8_LDB(B0, 1, 0); PG8_SCHED; PG8_LDA(At, 1, 0); PG8_STAGE(PG8_SA(0, 1), a2 + hstep, voffA);
;             PG8_WAIT_L(8); PG8_BAR; PG8_WAIT_L(0); PG8_MMA(0, 0, At, B0); PG8_BAR; PG8_SCHED;
;             PG8_LDB(B1, 1, 1); PG8_STAGE(PG8_SB(1, 0), b3, voffB);
	v_mfma_f32_16x16x32_bf16 v[52:55], v[204:207], v[144:147], v[52:55]
	v_mfma_f32_16x16x32_bf16 v[48:51], v[212:215], v[144:147], v[48:51]
	v_mfma_f32_16x16x32_bf16 v[36:39], v[204:207], v[174:177], v[36:39]
	v_mfma_f32_16x16x32_bf16 v[32:35], v[212:215], v[174:177], v[32:35]
	v_mfma_f32_16x16x32_bf16 v[20:23], v[204:207], v[182:185], v[20:23]
	v_mfma_f32_16x16x32_bf16 v[16:19], v[212:215], v[182:185], v[16:19]
	v_mfma_f32_16x16x32_bf16 v[4:7], v[204:207], v[196:199], v[4:7]
	v_mfma_f32_16x16x32_bf16 v[0:3], v[212:215], v[196:199], v[0:3]
	v_mfma_f32_16x16x32_bf16 v[52:55], v[208:211], v[148:151], v[52:55]
	v_mfma_f32_16x16x32_bf16 v[48:51], v[216:219], v[148:151], v[48:51]
	v_mfma_f32_16x16x32_bf16 v[36:39], v[208:211], v[178:181], v[36:39]
	v_mfma_f32_16x16x32_bf16 v[32:35], v[216:219], v[178:181], v[32:35]
	v_mfma_f32_16x16x32_bf16 v[20:23], v[208:211], v[186:189], v[20:23]
	v_mfma_f32_16x16x32_bf16 v[16:19], v[216:219], v[186:189], v[16:19]
	v_mfma_f32_16x16x32_bf16 v[4:7], v[208:211], v[200:203], v[4:7]
	v_mfma_f32_16x16x32_bf16 v[0:3], v[216:219], v[200:203], v[0:3]
	s_add_i32 s30, 0, 0x18000
	v_add_u32_e32 v140, s30, v155
	s_barrier
	ds_read_b128 v[128:131], v140
	ds_read_b128 v[132:135], v140 offset:1024
	ds_read_b128 v[136:139], v140 offset:2048
	ds_read_b128 v[140:143], v140 offset:3072
	s_add_u32 s50, s50, 0x40000
	s_addc_u32 s51, s51, 0
	s_mov_b32 m0, s7
	v_lshl_add_u64 v[204:205], s[50:51], 0, v[158:159]
	ds_read_b128 v[144:147], v193 offset:32768
	ds_read_b128 v[148:151], v193 offset:33792
	ds_read_b128 v[174:177], v193 offset:34816
	ds_read_b128 v[178:181], v193 offset:35840
	ds_read_b128 v[182:185], v193 offset:36864
	ds_read_b128 v[186:189], v193 offset:37888
	ds_read_b128 v[196:199], v193 offset:38912
	ds_read_b128 v[200:203], v193 offset:39936
	global_load_lds_dwordx4 v[204:205], off
	s_mov_b32 m0, s16
	v_lshl_add_u64 v[204:205], s[50:51], 0, v[162:163]
	global_load_lds_dwordx4 v[204:205], off
	s_waitcnt lgkmcnt(8)
	s_barrier
	s_waitcnt lgkmcnt(0)
	v_mfma_f32_16x16x32_bf16 v[124:127], v[128:131], v[144:147], v[124:127]
	v_mfma_f32_16x16x32_bf16 v[120:123], v[136:139], v[144:147], v[120:123]
	v_mfma_f32_16x16x32_bf16 v[108:111], v[128:131], v[174:177], v[108:111]
	v_mfma_f32_16x16x32_bf16 v[104:107], v[136:139], v[174:177], v[104:107]
	v_mfma_f32_16x16x32_bf16 v[92:95], v[128:131], v[182:185], v[92:95]
	v_mfma_f32_16x16x32_bf16 v[88:91], v[136:139], v[182:185], v[88:91]
	v_mfma_f32_16x16x32_bf16 v[76:79], v[128:131], v[196:199], v[76:79]
	v_mfma_f32_16x16x32_bf16 v[72:75], v[136:139], v[196:199], v[72:75]
	v_mfma_f32_16x16x32_bf16 v[124:127], v[132:135], v[148:151], v[124:127]
	v_mfma_f32_16x16x32_bf16 v[120:123], v[140:143], v[148:151], v[120:123]
	v_mfma_f32_16x16x32_bf16 v[108:111], v[132:135], v[178:181], v[108:111]
	v_mfma_f32_16x16x32_bf16 v[104:107], v[140:143], v[178:181], v[104:107]
	v_mfma_f32_16x16x32_bf16 v[92:95], v[132:135], v[186:189], v[92:95]
	v_mfma_f32_16x16x32_bf16 v[88:91], v[140:143], v[186:189], v[88:91]
	v_mfma_f32_16x16x32_bf16 v[76:79], v[132:135], v[200:203], v[76:79]
	v_mfma_f32_16x16x32_bf16 v[72:75], v[140:143], v[200:203], v[72:75]
	s_barrier
	s_add_i32 s43, 0, 0x1c000
	s_add_i32 s30, s30, s4
	v_add_u32_e32 v216, s43, v155
	v_lshl_add_u64 v[190:191], v[190:191], 0, s[14:15]
	s_mov_b32 m0, s30
	ds_read_b128 v[204:207], v216
	ds_read_b128 v[208:211], v216 offset:1024
	ds_read_b128 v[212:215], v216 offset:2048
	ds_read_b128 v[216:219], v216 offset:3072
	global_load_lds_dwordx4 v[190:191], off
	s_add_i32 m0, s30, 0x2000
	v_lshl_add_u64 v[190:191], v[220:221], 0, s[14:15]
	global_load_lds_dwordx4 v[190:191], off
	s_barrier
; #define PG8_STAGE(bufoff, gbase, voff) do { _Pragma("unroll") for (int _i = 0; _i < 2; ++_i) \
;         __builtin_amdgcn_global_load_lds((const unsigned*)((const char*)(gbase) + (voff)[_i]), (PG8_LAS unsigned*)(lds + (bufoff) + ldsw + _i * 8192), 16, 0, 0); } while (0)
; #define PG8_LDA(dst, b, h) do { _Pragma("unroll") for (int m = 0; m < 4; ++m) _Pragma("unroll") for (int k = 0; k < 2; ++k) dst[m][k] = *(const PG8_LAS bf16x8*)(lds + PG8_SA(b, h) + aoff + m * 2048 + k * 1024); } while (0)
; #define PG8_MMA(ai, bj, At, Bt) do { __builtin_amdgcn_s_setprio(1); _Pragma("unroll") for (int m = 0; m < 4; ++m) _Pragma("unroll") for (int n = 0; n < 2; ++n) _Pragma("unroll") for (int k = 0; k < 2; ++k) \
;         acc[ai][bj][m][n] = __builtin_amdgcn_mfma_f32_16x16x32_bf16(Bt[n][k], At[m][k], acc[ai][bj][m][n], 0, 0, 0); __builtin_amdgcn_s_setprio(0); } while (0)
; #define PG8_WAIT_V(n) asm volatile("s_waitcnt vmcnt(" #n ")" ::: "memory")
; #define PG8_WAIT_L(n) asm volatile("s_waitcnt lgkmcnt(" #n ")" ::: "memory")
; #define PG8_BAR __builtin_amdgcn_s_barrier()
; #define PG8_SCHED __builtin_amdgcn_sched_barrier(0)
; template <class Epi, class Sched>
; __device__ __forceinline__ void gemm_phase(PG8_LAS unsigned char* lds, const Gemm g, const Sched& S, const Epi& E) {
;     ...
;             PG8_BAR; PG8_WAIT_L(0); PG8_MMA(0, 1, At, B1); PG8_BAR;
;             PG8_LDA(At, 1, 1); PG8_STAGE(PG8_SA(1, 0), a3, voffA);
;             PG8_BAR; PG8_WAIT_L(0); PG8_MMA(1, 0, At, B0); PG8_BAR; PG8_SCHED;
;             PG8_STAGE(PG8_SB(1, 1), b3 + hstep, voffB);
;             PG8_WAIT_V(6); PG8_BAR; PG8_MMA(1, 1, At, B1); PG8_BAR;
;         }
;         if constexpr (!Epi::AFTER_DRAIN) {
;             if (cur.part < 0) E(acc, cur, wr, wc, fr, fq, pre);
	s_waitcnt lgkmcnt(0)
	v_mfma_f32_16x16x32_bf16 v[116:119], v[204:207], v[144:147], v[116:119]
	v_mfma_f32_16x16x32_bf16 v[112:115], v[212:215], v[144:147], v[112:115]
	v_mfma_f32_16x16x32_bf16 v[100:103], v[204:207], v[174:177], v[100:103]
	v_mfma_f32_16x16x32_bf16 v[96:99], v[212:215], v[174:177], v[96:99]
	v_mfma_f32_16x16x32_bf16 v[84:87], v[204:207], v[182:185], v[84:87]
	v_mfma_f32_16x16x32_bf16 v[80:83], v[212:215], v[182:185], v[80:83]
	v_mfma_f32_16x16x32_bf16 v[68:71], v[204:207], v[196:199], v[68:71]
	v_mfma_f32_16x16x32_bf16 v[64:67], v[212:215], v[196:199], v[64:67]
	v_mfma_f32_16x16x32_bf16 v[116:119], v[208:211], v[148:151], v[116:119]
	v_mfma_f32_16x16x32_bf16 v[112:115], v[216:219], v[148:151], v[112:115]
	v_mfma_f32_16x16x32_bf16 v[100:103], v[208:211], v[178:181], v[100:103]
	v_mfma_f32_16x16x32_bf16 v[96:99], v[216:219], v[178:181], v[96:99]
	v_mfma_f32_16x16x32_bf16 v[84:87], v[208:211], v[186:189], v[84:87]
	v_mfma_f32_16x16x32_bf16 v[80:83], v[216:219], v[186:189], v[80:83]
	v_mfma_f32_16x16x32_bf16 v[68:71], v[208:211], v[200:203], v[68:71]
	v_mfma_f32_16x16x32_bf16 v[64:67], v[216:219], v[200:203], v[64:67]
	s_mov_b32 m0, s18
	v_lshl_add_u64 v[190:191], v[222:223], 0, s[14:15]
	s_barrier
	ds_read_b128 v[144:147], v193 offset:49152
	ds_read_b128 v[148:151], v193 offset:50176
	ds_read_b128 v[174:177], v193 offset:51200
	ds_read_b128 v[178:181], v193 offset:52224
	ds_read_b128 v[182:185], v193 offset:53248
	ds_read_b128 v[186:189], v193 offset:54272
	ds_read_b128 v[196:199], v193 offset:55296
	ds_read_b128 v[200:203], v193 offset:56320
	global_load_lds_dwordx4 v[190:191], off
	s_mov_b32 m0, s19
	v_lshl_add_u64 v[190:191], v[224:225], 0, s[14:15]
	global_load_lds_dwordx4 v[190:191], off
	s_barrier
	s_waitcnt lgkmcnt(0)
	v_mfma_f32_16x16x32_bf16 v[60:63], v[128:131], v[144:147], v[60:63]
	v_mfma_f32_16x16x32_bf16 v[56:59], v[136:139], v[144:147], v[56:59]
	v_mfma_f32_16x16x32_bf16 v[44:47], v[128:131], v[174:177], v[44:47]
	v_mfma_f32_16x16x32_bf16 v[40:43], v[136:139], v[174:177], v[40:43]
	v_mfma_f32_16x16x32_bf16 v[28:31], v[128:131], v[182:185], v[28:31]
	v_mfma_f32_16x16x32_bf16 v[24:27], v[136:139], v[182:185], v[24:27]
	v_mfma_f32_16x16x32_bf16 v[12:15], v[128:131], v[196:199], v[12:15]
	v_mfma_f32_16x16x32_bf16 v[8:11], v[136:139], v[196:199], v[8:11]
	v_mfma_f32_16x16x32_bf16 v[60:63], v[132:135], v[148:151], v[60:63]
	v_mfma_f32_16x16x32_bf16 v[56:59], v[140:143], v[148:151], v[56:59]
	v_mfma_f32_16x16x32_bf16 v[44:47], v[132:135], v[178:181], v[44:47]
	v_mfma_f32_16x16x32_bf16 v[40:43], v[140:143], v[178:181], v[40:43]
	v_mfma_f32_16x16x32_bf16 v[28:31], v[132:135], v[186:189], v[28:31]
	v_mfma_f32_16x16x32_bf16 v[24:27], v[140:143], v[186:189], v[24:27]
	v_mfma_f32_16x16x32_bf16 v[12:15], v[132:135], v[200:203], v[12:15]
	v_mfma_f32_16x16x32_bf16 v[8:11], v[140:143], v[200:203], v[8:11]
	s_barrier
	s_add_u32 s48, s48, 0x40080
	s_addc_u32 s49, s49, 0
	s_add_i32 s30, s43, s4
	s_mov_b32 m0, s30
	v_lshl_add_u64 v[128:129], s[48:49], 0, v[160:161]
	global_load_lds_dwordx4 v[128:129], off
	s_add_i32 m0, s30, 0x2000
	v_lshl_add_u64 v[128:129], s[48:49], 0, v[164:165]
	global_load_lds_dwordx4 v[128:129], off
	s_waitcnt vmcnt(6)
	s_barrier
	v_mfma_f32_16x16x32_bf16 v[52:55], v[204:207], v[144:147], v[52:55]
	v_mfma_f32_16x16x32_bf16 v[48:51], v[212:215], v[144:147], v[48:51]
	v_mfma_f32_16x16x32_bf16 v[36:39], v[204:207], v[174:177], v[36:39]
	v_mfma_f32_16x16x32_bf16 v[32:35], v[212:215], v[174:177], v[32:35]
	v_mfma_f32_16x16x32_bf16 v[20:23], v[204:207], v[182:185], v[20:23]
	v_mfma_f32_16x16x32_bf16 v[16:19], v[212:215], v[182:185], v[16:19]
	v_mfma_f32_16x16x32_bf16 v[4:7], v[204:207], v[196:199], v[4:7]
	v_mfma_f32_16x16x32_bf16 v[0:3], v[212:215], v[196:199], v[0:3]
	v_mfma_f32_16x16x32_bf16 v[52:55], v[208:211], v[148:151], v[52:55]
	v_mfma_f32_16x16x32_bf16 v[48:51], v[216:219], v[148:151], v[48:51]
	v_mfma_f32_16x16x32_bf16 v[36:39], v[208:211], v[178:181], v[36:39]
	v_mfma_f32_16x16x32_bf16 v[32:35], v[216:219], v[178:181], v[32:35]
	v_mfma_f32_16x16x32_bf16 v[20:23], v[208:211], v[186:189], v[20:23]
	v_mfma_f32_16x16x32_bf16 v[16:19], v[216:219], v[186:189], v[16:19]
	v_mfma_f32_16x16x32_bf16 v[4:7], v[208:211], v[200:203], v[4:7]
	v_mfma_f32_16x16x32_bf16 v[0:3], v[216:219], v[200:203], v[0:3]
	s_add_u32 s46, s46, 0x100
	s_addc_u32 s47, s47, 0
	s_add_u32 s27, s27, 0x100
	s_addc_u32 s37, s37, 0
	s_cmp_ge_i32 s70, s23
	s_mov_b32 s43, s70
	s_barrier
	s_cbranch_scc0 .LBB0_2251
	s_cmp_gt_i32 s12, -1
	s_mov_b64 s[46:47], -1
	s_cbranch_scc0 .LBB0_2254

; #define PG8_STAGE(bufoff, gbase, voff) do { _Pragma("unroll") for (int _i = 0; _i < 2; ++_i) \
;         __builtin_amdgcn_global_load_lds((const unsigned*)((const char*)(gbase) + (voff)[_i]), (PG8_LAS unsigned*)(lds + (bufoff) + ldsw + _i * 8192), 16, 0, 0); } while (0)
; #define PG8_LDA(dst, b, h) do { _Pragma("unroll") for (int m = 0; m < 4; ++m) _Pragma("unroll") for (int k = 0; k < 2; ++k) dst[m][k] = *(const PG8_LAS bf16x8*)(lds + PG8_SA(b, h) + aoff + m * 2048 + k * 1024); } while (0)
; #define PG8_LDB(dst, b, h) do { _Pragma("unroll") for (int n = 0; n < 2; ++n) _Pragma("unroll") for (int k = 0; k < 2; ++k) dst[n][k] = *(const PG8_LAS bf16x8*)(lds + PG8_SB(b, h) + boff + n * 2048 + k * 1024); } while (0)
; #define PG8_MMA(ai, bj, At, Bt) do { __builtin_amdgcn_s_setprio(1); _Pragma("unroll") for (int m = 0; m < 4; ++m) _Pragma("unroll") for (int n = 0; n < 2; ++n) _Pragma("unroll") for (int k = 0; k < 2; ++k) \
;         acc[ai][bj][m][n] = __builtin_amdgcn_mfma_f32_16x16x32_bf16(Bt[n][k], At[m][k], acc[ai][bj][m][n], 0, 0, 0); __builtin_amdgcn_s_setprio(0); } while (0)
; #define PG8_WAIT_L(n) asm volatile("s_waitcnt lgkmcnt(" #n ")" ::: "memory")
; #define PG8_BAR __builtin_amdgcn_s_barrier()
; #define PG8_SCHED __builtin_amdgcn_sched_barrier(0)
; template <class Epi, class Sched>
; __device__ __forceinline__ void gemm_phase(PG8_LAS unsigned char* lds, const Gemm g, const Sched& S, const Epi& E) {
;     ...
;             const bool last = (t == cnk - 2);
;             const char* a1 = cA + (size_t)(t + 1) * kstep;
;             const char* a2 = last ? nA : cA + (size_t)(t + 2) * kstep; const char* b2 = last ? nB : cB + (size_t)(t + 2) * kstep;
;             const char* a3 = a2 + kstep; const char* b3 = b2 + kstep;
;             if (last && has_next) S.a_ready(nxt);
;             if (last) E.prefetch(pre, cur, wr, fr);
;             PG8_LDB(B0, 0, 0); PG8_SCHED; PG8_LDA(At, 0, 0); PG8_STAGE(PG8_SA(1, 1), a1 + hstep, voffA);
;             PG8_WAIT_L(8); PG8_BAR; PG8_WAIT_L(0); PG8_MMA(0, 0, At, B0); PG8_BAR; PG8_SCHED;
;             PG8_LDB(B1, 0, 1); PG8_STAGE(PG8_SB(0, 0), b2, voffB);
;             PG8_BAR; PG8_WAIT_L(0); PG8_MMA(0, 1, At, B1); PG8_BAR;
;             PG8_LDA(At, 0, 1); PG8_STAGE(PG8_SA(0, 0), a2, voffA);
;             PG8_BAR; PG8_WAIT_L(0); PG8_MMA(1, 0, At, B0); PG8_BAR; PG8_SCHED;
.LBB0_2447:
	v_add_u32_e32 v176, s28, v155
	ds_read_b128 v[164:167], v176
	ds_read_b128 v[168:171], v176 offset:1024
	ds_read_b128 v[172:175], v176 offset:2048
	ds_read_b128 v[180:183], v176 offset:3072
	s_add_u32 s12, s6, 0xfffc0080
	s_addc_u32 s13, s7, -1
	s_and_b64 s[8:9], s[8:9], exec
	s_cselect_b32 s13, s37, s13
	s_cselect_b32 s12, s42, s12
	s_cselect_b32 s9, s27, s53
	s_cselect_b32 s8, s43, s52
	v_lshl_add_u64 v[176:177], s[6:7], 0, v[138:139]
	s_add_i32 m0, s17, 0xc000
	ds_read_b128 v[184:187], v178
	ds_read_b128 v[188:191], v178 offset:1024
	ds_read_b128 v[192:195], v178 offset:2048
	ds_read_b128 v[196:199], v178 offset:3072
	ds_read_b128 v[200:203], v178 offset:4096
	ds_read_b128 v[204:207], v178 offset:5120
	ds_read_b128 v[208:211], v178 offset:6144
	ds_read_b128 v[212:215], v178 offset:7168
	global_load_lds_dwordx4 v[176:177], off
	s_add_i32 m0, s17, 0xe000
	v_lshl_add_u64 v[176:177], s[6:7], 0, v[140:141]
	global_load_lds_dwordx4 v[176:177], off
	s_waitcnt lgkmcnt(8)
	s_barrier
	s_waitcnt lgkmcnt(0)
	v_mfma_f32_16x16x32_bf16 v[124:127], v[164:167], v[184:187], v[124:127]
	v_mfma_f32_16x16x32_bf16 v[120:123], v[172:175], v[184:187], v[120:123]
	v_mfma_f32_16x16x32_bf16 v[108:111], v[164:167], v[192:195], v[108:111]
	v_mfma_f32_16x16x32_bf16 v[104:107], v[172:175], v[192:195], v[104:107]
	v_mfma_f32_16x16x32_bf16 v[92:95], v[164:167], v[200:203], v[92:95]
	v_mfma_f32_16x16x32_bf16 v[88:91], v[172:175], v[200:203], v[88:91]
	v_mfma_f32_16x16x32_bf16 v[76:79], v[164:167], v[208:211], v[76:79]
	v_mfma_f32_16x16x32_bf16 v[72:75], v[172:175], v[208:211], v[72:75]
	v_mfma_f32_16x16x32_bf16 v[124:127], v[168:171], v[188:191], v[124:127]
	v_mfma_f32_16x16x32_bf16 v[120:123], v[180:183], v[188:191], v[120:123]
	v_mfma_f32_16x16x32_bf16 v[108:111], v[168:171], v[196:199], v[108:111]
	v_mfma_f32_16x16x32_bf16 v[104:107], v[180:183], v[196:199], v[104:107]
	v_mfma_f32_16x16x32_bf16 v[92:95], v[168:171], v[204:207], v[92:95]
	v_mfma_f32_16x16x32_bf16 v[88:91], v[180:183], v[204:207], v[88:91]
	v_mfma_f32_16x16x32_bf16 v[76:79], v[168:171], v[212:215], v[76:79]
	v_mfma_f32_16x16x32_bf16 v[72:75], v[180:183], v[212:215], v[72:75]
	s_barrier
	v_add_u32_e32 v176, s70, v155
	s_add_i32 s30, s28, s3
	ds_read_b128 v[216:219], v176
	ds_read_b128 v[220:223], v176 offset:1024
	ds_read_b128 v[224:227], v176 offset:2048
	ds_read_b128 v[228:231], v176 offset:3072
	v_lshl_add_u64 v[176:177], s[8:9], 0, v[132:133]
	s_mov_b32 m0, s30
	v_lshl_add_u64 v[232:233], s[8:9], 0, v[128:129]
	global_load_lds_dwordx4 v[176:177], off
	s_add_i32 m0, s30, 0x2000
	s_nop 0
	global_load_lds_dwordx4 v[232:233], off
	s_barrier
	s_waitcnt lgkmcnt(0)
	v_mfma_f32_16x16x32_bf16 v[116:119], v[216:219], v[184:187], v[116:119]
	v_mfma_f32_16x16x32_bf16 v[112:115], v[224:227], v[184:187], v[112:115]
	v_mfma_f32_16x16x32_bf16 v[100:103], v[216:219], v[192:195], v[100:103]
	v_mfma_f32_16x16x32_bf16 v[96:99], v[224:227], v[192:195], v[96:99]
	v_mfma_f32_16x16x32_bf16 v[84:87], v[216:219], v[200:203], v[84:87]
	v_mfma_f32_16x16x32_bf16 v[80:83], v[224:227], v[200:203], v[80:83]
	v_mfma_f32_16x16x32_bf16 v[68:71], v[216:219], v[208:211], v[68:71]
	v_mfma_f32_16x16x32_bf16 v[64:67], v[224:227], v[208:211], v[64:67]
	v_mfma_f32_16x16x32_bf16 v[116:119], v[220:223], v[188:191], v[116:119]
	v_mfma_f32_16x16x32_bf16 v[112:115], v[228:231], v[188:191], v[112:115]
	v_mfma_f32_16x16x32_bf16 v[100:103], v[220:223], v[196:199], v[100:103]
	v_mfma_f32_16x16x32_bf16 v[96:99], v[228:231], v[196:199], v[96:99]
	v_mfma_f32_16x16x32_bf16 v[84:87], v[220:223], v[204:207], v[84:87]
	v_mfma_f32_16x16x32_bf16 v[80:83], v[228:231], v[204:207], v[80:83]
	v_mfma_f32_16x16x32_bf16 v[68:71], v[220:223], v[212:215], v[68:71]
	v_mfma_f32_16x16x32_bf16 v[64:67], v[228:231], v[212:215], v[64:67]
	s_mov_b32 m0, s17
	v_lshl_add_u64 v[234:235], s[12:13], 0, v[134:135]
	s_barrier
	ds_read_b128 v[184:187], v178 offset:16384
	ds_read_b128 v[188:191], v178 offset:17408
	ds_read_b128 v[192:195], v178 offset:18432
	ds_read_b128 v[196:199], v178 offset:19456
	ds_read_b128 v[200:203], v178 offset:20480
	ds_read_b128 v[204:207], v178 offset:21504
	ds_read_b128 v[208:211], v178 offset:22528
	ds_read_b128 v[212:215], v178 offset:23552
	global_load_lds_dwordx4 v[234:235], off
	s_mov_b32 m0, s19
	v_lshl_add_u64 v[236:237], s[12:13], 0, v[130:131]
	global_load_lds_dwordx4 v[236:237], off
	s_barrier
	s_waitcnt lgkmcnt(0)
	v_mfma_f32_16x16x32_bf16 v[60:63], v[164:167], v[184:187], v[60:63]
	v_mfma_f32_16x16x32_bf16 v[56:59], v[172:175], v[184:187], v[56:59]
	v_mfma_f32_16x16x32_bf16 v[44:47], v[164:167], v[192:195], v[44:47]
	v_mfma_f32_16x16x32_bf16 v[40:43], v[172:175], v[192:195], v[40:43]
	v_mfma_f32_16x16x32_bf16 v[28:31], v[164:167], v[200:203], v[28:31]
	v_mfma_f32_16x16x32_bf16 v[24:27], v[172:175], v[200:203], v[24:27]
	v_mfma_f32_16x16x32_bf16 v[12:15], v[164:167], v[208:211], v[12:15]
	v_mfma_f32_16x16x32_bf16 v[8:11], v[172:175], v[208:211], v[8:11]
	v_mfma_f32_16x16x32_bf16 v[60:63], v[168:171], v[188:191], v[60:63]
	v_mfma_f32_16x16x32_bf16 v[56:59], v[180:183], v[188:191], v[56:59]
	v_mfma_f32_16x16x32_bf16 v[44:47], v[168:171], v[196:199], v[44:47]
	v_mfma_f32_16x16x32_bf16 v[40:43], v[180:183], v[196:199], v[40:43]
	v_mfma_f32_16x16x32_bf16 v[28:31], v[168:171], v[204:207], v[28:31]
	v_mfma_f32_16x16x32_bf16 v[24:27], v[180:183], v[204:207], v[24:27]
	v_mfma_f32_16x16x32_bf16 v[12:15], v[168:171], v[212:215], v[12:15]
	v_mfma_f32_16x16x32_bf16 v[8:11], v[180:183], v[212:215], v[8:11]
	s_barrier
; #define PG8_STAGE(bufoff, gbase, voff) do { _Pragma("unroll") for (int _i = 0; _i < 2; ++_i) \
;         __builtin_amdgcn_global_load_lds((const unsigned*)((const char*)(gbase) + (voff)[_i]), (PG8_LAS unsigned*)(lds + (bufoff) + ldsw + _i * 8192), 16, 0, 0); } while (0)
; #define PG8_LDA(dst, b, h) do { _Pragma("unroll") for (int m = 0; m < 4; ++m) _Pragma("unroll") for (int k = 0; k < 2; ++k) dst[m][k] = *(const PG8_LAS bf16x8*)(lds + PG8_SA(b, h) + aoff + m * 2048 + k * 1024); } while (0)
; #define PG8_LDB(dst, b, h) do { _Pragma("unroll") for (int n = 0; n < 2; ++n) _Pragma("unroll") for (int k = 0; k < 2; ++k) dst[n][k] = *(const PG8_LAS bf16x8*)(lds + PG8_SB(b, h) + boff + n * 2048 + k * 1024); } while (0)
; #define PG8_MMA(ai, bj, At, Bt) do { __builtin_amdgcn_s_setprio(1); _Pragma("unroll") for (int m = 0; m < 4; ++m) _Pragma("unroll") for (int n = 0; n < 2; ++n) _Pragma("unroll") for (int k = 0; k < 2; ++k) \
;         acc[ai][bj][m][n] = __builtin_amdgcn_mfma_f32_16x16x32_bf16(Bt[n][k], At[m][k], acc[ai][bj][m][n], 0, 0, 0); __builtin_amdgcn_s_setprio(0); } while (0)
; #define PG8_WAIT_V(n) asm volatile("s_waitcnt vmcnt(" #n ")" ::: "memory")
; #define PG8_WAIT_L(n) asm volatile("s_waitcnt lgkmcnt(" #n ")" ::: "memory")
; #define PG8_BAR __builtin_amdgcn_s_barrier()
; #define PG8_SCHED __builtin_amdgcn_sched_barrier(0)
; template <class Epi, class Sched>
; __device__ __forceinline__ void gemm_phase(PG8_LAS unsigned char* lds, const Gemm g, const Sched& S, const Epi& E) {
;     ...
;             PG8_STAGE(PG8_SB(0, 1), b2 + hstep, voffB);
;             PG8_WAIT_V(6); PG8_BAR; PG8_MMA(1, 1, At, B1); PG8_BAR;
;             PG8_LDB(B0, 1, 0); PG8_SCHED; PG8_LDA(At, 1, 0); PG8_STAGE(PG8_SA(0, 1), a2 + hstep, voffA);
;             PG8_WAIT_L(8); PG8_BAR; PG8_WAIT_L(0); PG8_MMA(0, 0, At, B0); PG8_BAR; PG8_SCHED;
;             PG8_LDB(B1, 1, 1); PG8_STAGE(PG8_SB(1, 0), b3, voffB);
	s_add_u32 s56, s8, 0x40000
	s_addc_u32 s57, s9, 0
	s_add_i32 s30, s70, s3
	s_mov_b32 m0, s30
	v_lshl_add_u64 v[164:165], s[56:57], 0, v[132:133]
	global_load_lds_dwordx4 v[164:165], off
	s_add_i32 m0, s30, 0x2000
	v_lshl_add_u64 v[164:165], s[56:57], 0, v[128:129]
	global_load_lds_dwordx4 v[164:165], off
	s_waitcnt vmcnt(6)
	s_barrier
	v_mfma_f32_16x16x32_bf16 v[52:55], v[216:219], v[184:187], v[52:55]
	v_mfma_f32_16x16x32_bf16 v[48:51], v[224:227], v[184:187], v[48:51]
	v_mfma_f32_16x16x32_bf16 v[36:39], v[216:219], v[192:195], v[36:39]
	v_mfma_f32_16x16x32_bf16 v[32:35], v[224:227], v[192:195], v[32:35]
	v_mfma_f32_16x16x32_bf16 v[20:23], v[216:219], v[200:203], v[20:23]
	v_mfma_f32_16x16x32_bf16 v[16:19], v[224:227], v[200:203], v[16:19]
	v_mfma_f32_16x16x32_bf16 v[4:7], v[216:219], v[208:211], v[4:7]
	v_mfma_f32_16x16x32_bf16 v[0:3], v[224:227], v[208:211], v[0:3]
	v_mfma_f32_16x16x32_bf16 v[52:55], v[220:223], v[188:191], v[52:55]
	v_mfma_f32_16x16x32_bf16 v[48:51], v[228:231], v[188:191], v[48:51]
	v_mfma_f32_16x16x32_bf16 v[36:39], v[220:223], v[196:199], v[36:39]
	v_mfma_f32_16x16x32_bf16 v[32:35], v[228:231], v[196:199], v[32:35]
	v_mfma_f32_16x16x32_bf16 v[20:23], v[220:223], v[204:207], v[20:23]
	v_mfma_f32_16x16x32_bf16 v[16:19], v[228:231], v[204:207], v[16:19]
	v_mfma_f32_16x16x32_bf16 v[4:7], v[220:223], v[212:215], v[4:7]
	v_mfma_f32_16x16x32_bf16 v[0:3], v[228:231], v[212:215], v[0:3]
	s_add_i32 s30, 0, 0x18000
	v_add_u32_e32 v180, s30, v155
	s_barrier
	ds_read_b128 v[164:167], v180
	ds_read_b128 v[168:171], v180 offset:1024
	ds_read_b128 v[172:175], v180 offset:2048
	ds_read_b128 v[180:183], v180 offset:3072
	s_add_u32 s12, s12, 0x40000
	s_addc_u32 s13, s13, 0
	s_mov_b32 m0, s21
	v_lshl_add_u64 v[216:217], s[12:13], 0, v[134:135]
	ds_read_b128 v[184:187], v178 offset:32768
	ds_read_b128 v[188:191], v178 offset:33792
	ds_read_b128 v[192:195], v178 offset:34816
	ds_read_b128 v[196:199], v178 offset:35840
	ds_read_b128 v[200:203], v178 offset:36864
	ds_read_b128 v[204:207], v178 offset:37888
	ds_read_b128 v[208:211], v178 offset:38912
	ds_read_b128 v[212:215], v178 offset:39936
	global_load_lds_dwordx4 v[216:217], off
	s_mov_b32 m0, s29
	v_lshl_add_u64 v[216:217], s[12:13], 0, v[130:131]
	global_load_lds_dwordx4 v[216:217], off
	s_waitcnt lgkmcnt(8)
	s_barrier
	s_waitcnt lgkmcnt(0)
	v_mfma_f32_16x16x32_bf16 v[124:127], v[164:167], v[184:187], v[124:127]
	v_mfma_f32_16x16x32_bf16 v[120:123], v[172:175], v[184:187], v[120:123]
	v_mfma_f32_16x16x32_bf16 v[108:111], v[164:167], v[192:195], v[108:111]
	v_mfma_f32_16x16x32_bf16 v[104:107], v[172:175], v[192:195], v[104:107]
	v_mfma_f32_16x16x32_bf16 v[92:95], v[164:167], v[200:203], v[92:95]
	v_mfma_f32_16x16x32_bf16 v[88:91], v[172:175], v[200:203], v[88:91]
	v_mfma_f32_16x16x32_bf16 v[76:79], v[164:167], v[208:211], v[76:79]
	v_mfma_f32_16x16x32_bf16 v[72:75], v[172:175], v[208:211], v[72:75]
	v_mfma_f32_16x16x32_bf16 v[124:127], v[168:171], v[188:191], v[124:127]
	v_mfma_f32_16x16x32_bf16 v[120:123], v[180:183], v[188:191], v[120:123]
	v_mfma_f32_16x16x32_bf16 v[108:111], v[168:171], v[196:199], v[108:111]
	v_mfma_f32_16x16x32_bf16 v[104:107], v[180:183], v[196:199], v[104:107]
	v_mfma_f32_16x16x32_bf16 v[92:95], v[168:171], v[204:207], v[92:95]
	v_mfma_f32_16x16x32_bf16 v[88:91], v[180:183], v[204:207], v[88:91]
	v_mfma_f32_16x16x32_bf16 v[76:79], v[168:171], v[212:215], v[76:79]
	v_mfma_f32_16x16x32_bf16 v[72:75], v[180:183], v[212:215], v[72:75]
	s_barrier
	s_add_i32 s12, 0, 0x1c000
	s_add_i32 s13, s30, s3
	v_add_u32_e32 v228, s12, v155
	v_lshl_add_u64 v[176:177], v[176:177], 0, s[14:15]
	s_mov_b32 m0, s13
	ds_read_b128 v[216:219], v228
	ds_read_b128 v[220:223], v228 offset:1024
	ds_read_b128 v[224:227], v228 offset:2048
	ds_read_b128 v[228:231], v228 offset:3072
	global_load_lds_dwordx4 v[176:177], off
	s_add_i32 m0, s13, 0x2000
	v_lshl_add_u64 v[176:177], v[232:233], 0, s[14:15]
	global_load_lds_dwordx4 v[176:177], off
	s_barrier
; #define PG8_STAGE(bufoff, gbase, voff) do { _Pragma("unroll") for (int _i = 0; _i < 2; ++_i) \
;         __builtin_amdgcn_global_load_lds((const unsigned*)((const char*)(gbase) + (voff)[_i]), (PG8_LAS unsigned*)(lds + (bufoff) + ldsw + _i * 8192), 16, 0, 0); } while (0)
; #define PG8_LDA(dst, b, h) do { _Pragma("unroll") for (int m = 0; m < 4; ++m) _Pragma("unroll") for (int k = 0; k < 2; ++k) dst[m][k] = *(const PG8_LAS bf16x8*)(lds + PG8_SA(b, h) + aoff + m * 2048 + k * 1024); } while (0)
; #define PG8_MMA(ai, bj, At, Bt) do { __builtin_amdgcn_s_setprio(1); _Pragma("unroll") for (int m = 0; m < 4; ++m) _Pragma("unroll") for (int n = 0; n < 2; ++n) _Pragma("unroll") for (int k = 0; k < 2; ++k) \
;         acc[ai][bj][m][n] = __builtin_amdgcn_mfma_f32_16x16x32_bf16(Bt[n][k], At[m][k], acc[ai][bj][m][n], 0, 0, 0); __builtin_amdgcn_s_setprio(0); } while (0)
; #define PG8_WAIT_V(n) asm volatile("s_waitcnt vmcnt(" #n ")" ::: "memory")
; #define PG8_WAIT_L(n) asm volatile("s_waitcnt lgkmcnt(" #n ")" ::: "memory")
; #define PG8_BAR __builtin_amdgcn_s_barrier()
; #define PG8_SCHED __builtin_amdgcn_sched_barrier(0)
; template <class Epi, class Sched>
; __device__ __forceinline__ void gemm_phase(PG8_LAS unsigned char* lds, const Gemm g, const Sched& S, const Epi& E) {
;     ...
;             PG8_BAR; PG8_WAIT_L(0); PG8_MMA(0, 1, At, B1); PG8_BAR;
;             PG8_LDA(At, 1, 1); PG8_STAGE(PG8_SA(1, 0), a3, voffA);
;             PG8_BAR; PG8_WAIT_L(0); PG8_MMA(1, 0, At, B0); PG8_BAR; PG8_SCHED;
;             PG8_STAGE(PG8_SB(1, 1), b3 + hstep, voffB);
;             PG8_WAIT_V(6); PG8_BAR; PG8_MMA(1, 1, At, B1); PG8_BAR;
;         }
	s_waitcnt lgkmcnt(0)
	v_mfma_f32_16x16x32_bf16 v[116:119], v[216:219], v[184:187], v[116:119]
	v_mfma_f32_16x16x32_bf16 v[112:115], v[224:227], v[184:187], v[112:115]
	v_mfma_f32_16x16x32_bf16 v[100:103], v[216:219], v[192:195], v[100:103]
	v_mfma_f32_16x16x32_bf16 v[96:99], v[224:227], v[192:195], v[96:99]
	v_mfma_f32_16x16x32_bf16 v[84:87], v[216:219], v[200:203], v[84:87]
	v_mfma_f32_16x16x32_bf16 v[80:83], v[224:227], v[200:203], v[80:83]
	v_mfma_f32_16x16x32_bf16 v[68:71], v[216:219], v[208:211], v[68:71]
	v_mfma_f32_16x16x32_bf16 v[64:67], v[224:227], v[208:211], v[64:67]
	v_mfma_f32_16x16x32_bf16 v[116:119], v[220:223], v[188:191], v[116:119]
	v_mfma_f32_16x16x32_bf16 v[112:115], v[228:231], v[188:191], v[112:115]
	v_mfma_f32_16x16x32_bf16 v[100:103], v[220:223], v[196:199], v[100:103]
	v_mfma_f32_16x16x32_bf16 v[96:99], v[228:231], v[196:199], v[96:99]
	v_mfma_f32_16x16x32_bf16 v[84:87], v[220:223], v[204:207], v[84:87]
	v_mfma_f32_16x16x32_bf16 v[80:83], v[228:231], v[204:207], v[80:83]
	v_mfma_f32_16x16x32_bf16 v[68:71], v[220:223], v[212:215], v[68:71]
	v_mfma_f32_16x16x32_bf16 v[64:67], v[228:231], v[212:215], v[64:67]
	s_mov_b32 m0, s34
	v_lshl_add_u64 v[176:177], v[234:235], 0, s[14:15]
	s_barrier
	ds_read_b128 v[184:187], v178 offset:49152
	ds_read_b128 v[188:191], v178 offset:50176
	ds_read_b128 v[192:195], v178 offset:51200
	ds_read_b128 v[196:199], v178 offset:52224
	ds_read_b128 v[200:203], v178 offset:53248
	ds_read_b128 v[204:207], v178 offset:54272
	ds_read_b128 v[208:211], v178 offset:55296
	ds_read_b128 v[212:215], v178 offset:56320
	global_load_lds_dwordx4 v[176:177], off
	s_mov_b32 m0, s35
	v_lshl_add_u64 v[176:177], v[236:237], 0, s[14:15]
	global_load_lds_dwordx4 v[176:177], off
	s_barrier
	s_waitcnt lgkmcnt(0)
	v_mfma_f32_16x16x32_bf16 v[60:63], v[164:167], v[184:187], v[60:63]
	v_mfma_f32_16x16x32_bf16 v[56:59], v[172:175], v[184:187], v[56:59]
	v_mfma_f32_16x16x32_bf16 v[44:47], v[164:167], v[192:195], v[44:47]
	v_mfma_f32_16x16x32_bf16 v[40:43], v[172:175], v[192:195], v[40:43]
	v_mfma_f32_16x16x32_bf16 v[28:31], v[164:167], v[200:203], v[28:31]
	v_mfma_f32_16x16x32_bf16 v[24:27], v[172:175], v[200:203], v[24:27]
	v_mfma_f32_16x16x32_bf16 v[12:15], v[164:167], v[208:211], v[12:15]
	v_mfma_f32_16x16x32_bf16 v[8:11], v[172:175], v[208:211], v[8:11]
	v_mfma_f32_16x16x32_bf16 v[60:63], v[168:171], v[188:191], v[60:63]
	v_mfma_f32_16x16x32_bf16 v[56:59], v[180:183], v[188:191], v[56:59]
	v_mfma_f32_16x16x32_bf16 v[44:47], v[168:171], v[196:199], v[44:47]
	v_mfma_f32_16x16x32_bf16 v[40:43], v[180:183], v[196:199], v[40:43]
	v_mfma_f32_16x16x32_bf16 v[28:31], v[168:171], v[204:207], v[28:31]
	v_mfma_f32_16x16x32_bf16 v[24:27], v[180:183], v[204:207], v[24:27]
	v_mfma_f32_16x16x32_bf16 v[12:15], v[168:171], v[212:215], v[12:15]
	v_mfma_f32_16x16x32_bf16 v[8:11], v[180:183], v[212:215], v[8:11]
	s_barrier
	s_add_u32 s8, s8, 0x40080
	s_addc_u32 s9, s9, 0
	s_add_i32 s12, s12, s3
	s_mov_b32 m0, s12
	v_lshl_add_u64 v[164:165], s[8:9], 0, v[132:133]
	global_load_lds_dwordx4 v[164:165], off
	s_add_i32 m0, s12, 0x2000
	v_lshl_add_u64 v[164:165], s[8:9], 0, v[128:129]
	global_load_lds_dwordx4 v[164:165], off
	s_waitcnt vmcnt(6)
	s_barrier
	v_mfma_f32_16x16x32_bf16 v[52:55], v[216:219], v[184:187], v[52:55]
	v_mfma_f32_16x16x32_bf16 v[48:51], v[224:227], v[184:187], v[48:51]
	v_mfma_f32_16x16x32_bf16 v[36:39], v[216:219], v[192:195], v[36:39]
	v_mfma_f32_16x16x32_bf16 v[32:35], v[224:227], v[192:195], v[32:35]
	v_mfma_f32_16x16x32_bf16 v[20:23], v[216:219], v[200:203], v[20:23]
	v_mfma_f32_16x16x32_bf16 v[16:19], v[224:227], v[200:203], v[16:19]
	v_mfma_f32_16x16x32_bf16 v[4:7], v[216:219], v[208:211], v[4:7]
	v_mfma_f32_16x16x32_bf16 v[0:3], v[224:227], v[208:211], v[0:3]
	v_mfma_f32_16x16x32_bf16 v[52:55], v[220:223], v[188:191], v[52:55]
	v_mfma_f32_16x16x32_bf16 v[48:51], v[228:231], v[188:191], v[48:51]
	v_mfma_f32_16x16x32_bf16 v[36:39], v[220:223], v[196:199], v[36:39]
	v_mfma_f32_16x16x32_bf16 v[32:35], v[228:231], v[196:199], v[32:35]
	v_mfma_f32_16x16x32_bf16 v[20:23], v[220:223], v[204:207], v[20:23]
	v_mfma_f32_16x16x32_bf16 v[16:19], v[228:231], v[204:207], v[16:19]
	v_mfma_f32_16x16x32_bf16 v[4:7], v[220:223], v[212:215], v[4:7]
	v_mfma_f32_16x16x32_bf16 v[0:3], v[228:231], v[212:215], v[0:3]
	s_add_i32 s54, s54, 2
	s_add_u32 s6, s6, 0x100
	s_addc_u32 s7, s7, 0
	s_add_u32 s52, s52, 0x100
	s_addc_u32 s53, s53, 0
	s_cmp_lt_u32 s54, 14
	s_barrier
	s_cbranch_scc0 .LBB0_2450

; #define PG8_STAGE(bufoff, gbase, voff) do { _Pragma("unroll") for (int _i = 0; _i < 2; ++_i) \
;         __builtin_amdgcn_global_load_lds((const unsigned*)((const char*)(gbase) + (voff)[_i]), (PG8_LAS unsigned*)(lds + (bufoff) + ldsw + _i * 8192), 16, 0, 0); } while (0)
; #define PG8_LDA(dst, b, h) do { _Pragma("unroll") for (int m = 0; m < 4; ++m) _Pragma("unroll") for (int k = 0; k < 2; ++k) dst[m][k] = *(const PG8_LAS bf16x8*)(lds + PG8_SA(b, h) + aoff + m * 2048 + k * 1024); } while (0)
; #define PG8_LDB(dst, b, h) do { _Pragma("unroll") for (int n = 0; n < 2; ++n) _Pragma("unroll") for (int k = 0; k < 2; ++k) dst[n][k] = *(const PG8_LAS bf16x8*)(lds + PG8_SB(b, h) + boff + n * 2048 + k * 1024); } while (0)
; #define PG8_MMA(ai, bj, At, Bt) do { __builtin_amdgcn_s_setprio(1); _Pragma("unroll") for (int m = 0; m < 4; ++m) _Pragma("unroll") for (int n = 0; n < 2; ++n) _Pragma("unroll") for (int k = 0; k < 2; ++k) \
;         acc[ai][bj][m][n] = __builtin_amdgcn_mfma_f32_16x16x32_bf16(Bt[n][k], At[m][k], acc[ai][bj][m][n], 0, 0, 0); __builtin_amdgcn_s_setprio(0); } while (0)
; #define PG8_WAIT_L(n) asm volatile("s_waitcnt lgkmcnt(" #n ")" ::: "memory")
; #define PG8_BAR __builtin_amdgcn_s_barrier()
; #define PG8_SCHED __builtin_amdgcn_sched_barrier(0)
; template <class Epi, class Sched>
; __device__ __forceinline__ void gemm_phase(PG8_LAS unsigned char* lds, const Gemm g, const Sched& S, const Epi& E) {
;     ...
;             const bool last = (t == cnk - 2);
;             const char* a1 = cA + (size_t)(t + 1) * kstep;
;             const char* a2 = last ? nA : cA + (size_t)(t + 2) * kstep; const char* b2 = last ? nB : cB + (size_t)(t + 2) * kstep;
;             const char* a3 = a2 + kstep; const char* b3 = b2 + kstep;
;             if (last && has_next) S.a_ready(nxt);
;             if (last) E.prefetch(pre, cur, wr, fr);
;             PG8_LDB(B0, 0, 0); PG8_SCHED; PG8_LDA(At, 0, 0); PG8_STAGE(PG8_SA(1, 1), a1 + hstep, voffA);
;             PG8_WAIT_L(8); PG8_BAR; PG8_WAIT_L(0); PG8_MMA(0, 0, At, B0); PG8_BAR; PG8_SCHED;
;             PG8_LDB(B1, 0, 1); PG8_STAGE(PG8_SB(0, 0), b2, voffB);
;             PG8_BAR; PG8_WAIT_L(0); PG8_MMA(0, 1, At, B1); PG8_BAR;
;             PG8_LDA(At, 0, 1); PG8_STAGE(PG8_SA(0, 0), a2, voffA);
;             PG8_BAR; PG8_WAIT_L(0); PG8_MMA(1, 0, At, B0); PG8_BAR; PG8_SCHED;
.LBB0_2574:
	ds_read_b128 v[128:131], v192
	ds_read_b128 v[132:135], v192 offset:1024
	ds_read_b128 v[136:139], v192 offset:2048
	ds_read_b128 v[140:143], v192 offset:3072
	s_add_i32 s83, s27, 2
	s_add_u32 s30, s38, 0xfff00080
	s_addc_u32 s40, s39, -1
	s_cmp_eq_u32 s17, s27
	s_cselect_b32 s43, s25, s40
	s_cselect_b32 s42, s24, s30
	s_cselect_b32 s41, s37, s21
	s_cselect_b32 s40, s36, s19
	v_lshl_add_u64 v[190:191], s[38:39], 0, v[168:169]
	s_add_i32 m0, s31, 0xc000
	ds_read_b128 v[144:147], v193
	ds_read_b128 v[148:151], v193 offset:1024
	ds_read_b128 v[174:177], v193 offset:2048
	ds_read_b128 v[178:181], v193 offset:3072
	ds_read_b128 v[182:185], v193 offset:4096
	ds_read_b128 v[186:189], v193 offset:5120
	ds_read_b128 v[196:199], v193 offset:6144
	ds_read_b128 v[200:203], v193 offset:7168
	global_load_lds_dwordx4 v[190:191], off
	s_add_i32 m0, s31, 0xe000
	v_lshl_add_u64 v[190:191], s[38:39], 0, v[170:171]
	global_load_lds_dwordx4 v[190:191], off
	s_waitcnt lgkmcnt(8)
	s_barrier
	s_waitcnt lgkmcnt(0)
	v_mfma_f32_16x16x32_bf16 v[124:127], v[128:131], v[144:147], v[124:127]
	v_mfma_f32_16x16x32_bf16 v[120:123], v[136:139], v[144:147], v[120:123]
	v_mfma_f32_16x16x32_bf16 v[108:111], v[128:131], v[174:177], v[108:111]
	v_mfma_f32_16x16x32_bf16 v[104:107], v[136:139], v[174:177], v[104:107]
	v_mfma_f32_16x16x32_bf16 v[92:95], v[128:131], v[182:185], v[92:95]
	v_mfma_f32_16x16x32_bf16 v[88:91], v[136:139], v[182:185], v[88:91]
	v_mfma_f32_16x16x32_bf16 v[76:79], v[128:131], v[196:199], v[76:79]
	v_mfma_f32_16x16x32_bf16 v[72:75], v[136:139], v[196:199], v[72:75]
	v_mfma_f32_16x16x32_bf16 v[124:127], v[132:135], v[148:151], v[124:127]
	v_mfma_f32_16x16x32_bf16 v[120:123], v[140:143], v[148:151], v[120:123]
	v_mfma_f32_16x16x32_bf16 v[108:111], v[132:135], v[178:181], v[108:111]
	v_mfma_f32_16x16x32_bf16 v[104:107], v[140:143], v[178:181], v[104:107]
	v_mfma_f32_16x16x32_bf16 v[92:95], v[132:135], v[186:189], v[92:95]
	v_mfma_f32_16x16x32_bf16 v[88:91], v[140:143], v[186:189], v[88:91]
	v_mfma_f32_16x16x32_bf16 v[76:79], v[132:135], v[200:203], v[76:79]
	v_mfma_f32_16x16x32_bf16 v[72:75], v[140:143], v[200:203], v[72:75]
	s_barrier
	s_add_i32 s27, s53, s29
	v_lshl_add_u64 v[190:191], s[40:41], 0, v[160:161]
	s_mov_b32 m0, s27
	ds_read_b128 v[204:207], v194
	ds_read_b128 v[208:211], v194 offset:1024
	ds_read_b128 v[212:215], v194 offset:2048
	ds_read_b128 v[216:219], v194 offset:3072
	global_load_lds_dwordx4 v[190:191], off
	s_add_i32 m0, s27, 0x2000
	v_lshl_add_u64 v[220:221], s[40:41], 0, v[164:165]
	global_load_lds_dwordx4 v[220:221], off
	s_barrier
	s_waitcnt lgkmcnt(0)
	v_mfma_f32_16x16x32_bf16 v[116:119], v[204:207], v[144:147], v[116:119]
	v_mfma_f32_16x16x32_bf16 v[112:115], v[212:215], v[144:147], v[112:115]
	v_mfma_f32_16x16x32_bf16 v[100:103], v[204:207], v[174:177], v[100:103]
	v_mfma_f32_16x16x32_bf16 v[96:99], v[212:215], v[174:177], v[96:99]
	v_mfma_f32_16x16x32_bf16 v[84:87], v[204:207], v[182:185], v[84:87]
	v_mfma_f32_16x16x32_bf16 v[80:83], v[212:215], v[182:185], v[80:83]
	v_mfma_f32_16x16x32_bf16 v[68:71], v[204:207], v[196:199], v[68:71]
	v_mfma_f32_16x16x32_bf16 v[64:67], v[212:215], v[196:199], v[64:67]
	v_mfma_f32_16x16x32_bf16 v[116:119], v[208:211], v[148:151], v[116:119]
	v_mfma_f32_16x16x32_bf16 v[112:115], v[216:219], v[148:151], v[112:115]
	v_mfma_f32_16x16x32_bf16 v[100:103], v[208:211], v[178:181], v[100:103]
	v_mfma_f32_16x16x32_bf16 v[96:99], v[216:219], v[178:181], v[96:99]
	v_mfma_f32_16x16x32_bf16 v[84:87], v[208:211], v[186:189], v[84:87]
	v_mfma_f32_16x16x32_bf16 v[80:83], v[216:219], v[186:189], v[80:83]
	v_mfma_f32_16x16x32_bf16 v[68:71], v[208:211], v[200:203], v[68:71]
	v_mfma_f32_16x16x32_bf16 v[64:67], v[216:219], v[200:203], v[64:67]
	s_mov_b32 m0, s31
	v_lshl_add_u64 v[222:223], s[42:43], 0, v[158:159]
	s_barrier
	ds_read_b128 v[144:147], v193 offset:16384
	ds_read_b128 v[148:151], v193 offset:17408
	ds_read_b128 v[174:177], v193 offset:18432
	ds_read_b128 v[178:181], v193 offset:19456
	ds_read_b128 v[182:185], v193 offset:20480
	ds_read_b128 v[186:189], v193 offset:21504
	ds_read_b128 v[196:199], v193 offset:22528
	ds_read_b128 v[200:203], v193 offset:23552
	global_load_lds_dwordx4 v[222:223], off
	s_mov_b32 m0, s33
	v_lshl_add_u64 v[224:225], s[42:43], 0, v[162:163]
	global_load_lds_dwordx4 v[224:225], off
	s_barrier
	s_waitcnt lgkmcnt(0)
	v_mfma_f32_16x16x32_bf16 v[60:63], v[128:131], v[144:147], v[60:63]
	v_mfma_f32_16x16x32_bf16 v[56:59], v[136:139], v[144:147], v[56:59]
	v_mfma_f32_16x16x32_bf16 v[44:47], v[128:131], v[174:177], v[44:47]
	v_mfma_f32_16x16x32_bf16 v[40:43], v[136:139], v[174:177], v[40:43]
	v_mfma_f32_16x16x32_bf16 v[28:31], v[128:131], v[182:185], v[28:31]
	v_mfma_f32_16x16x32_bf16 v[24:27], v[136:139], v[182:185], v[24:27]
	v_mfma_f32_16x16x32_bf16 v[12:15], v[128:131], v[196:199], v[12:15]
	v_mfma_f32_16x16x32_bf16 v[8:11], v[136:139], v[196:199], v[8:11]
	v_mfma_f32_16x16x32_bf16 v[60:63], v[132:135], v[148:151], v[60:63]
	v_mfma_f32_16x16x32_bf16 v[56:59], v[140:143], v[148:151], v[56:59]
	v_mfma_f32_16x16x32_bf16 v[44:47], v[132:135], v[178:181], v[44:47]
	v_mfma_f32_16x16x32_bf16 v[40:43], v[140:143], v[178:181], v[40:43]
	v_mfma_f32_16x16x32_bf16 v[28:31], v[132:135], v[186:189], v[28:31]
	v_mfma_f32_16x16x32_bf16 v[24:27], v[140:143], v[186:189], v[24:27]
	v_mfma_f32_16x16x32_bf16 v[12:15], v[132:135], v[200:203], v[12:15]
	v_mfma_f32_16x16x32_bf16 v[8:11], v[140:143], v[200:203], v[8:11]
	s_barrier
; #define PG8_STAGE(bufoff, gbase, voff) do { _Pragma("unroll") for (int _i = 0; _i < 2; ++_i) \
;         __builtin_amdgcn_global_load_lds((const unsigned*)((const char*)(gbase) + (voff)[_i]), (PG8_LAS unsigned*)(lds + (bufoff) + ldsw + _i * 8192), 16, 0, 0); } while (0)
; #define PG8_LDA(dst, b, h) do { _Pragma("unroll") for (int m = 0; m < 4; ++m) _Pragma("unroll") for (int k = 0; k < 2; ++k) dst[m][k] = *(const PG8_LAS bf16x8*)(lds + PG8_SA(b, h) + aoff + m * 2048 + k * 1024); } while (0)
; #define PG8_LDB(dst, b, h) do { _Pragma("unroll") for (int n = 0; n < 2; ++n) _Pragma("unroll") for (int k = 0; k < 2; ++k) dst[n][k] = *(const PG8_LAS bf16x8*)(lds + PG8_SB(b, h) + boff + n * 2048 + k * 1024); } while (0)
; #define PG8_MMA(ai, bj, At, Bt) do { __builtin_amdgcn_s_setprio(1); _Pragma("unroll") for (int m = 0; m < 4; ++m) _Pragma("unroll") for (int n = 0; n < 2; ++n) _Pragma("unroll") for (int k = 0; k < 2; ++k) \
;         acc[ai][bj][m][n] = __builtin_amdgcn_mfma_f32_16x16x32_bf16(Bt[n][k], At[m][k], acc[ai][bj][m][n], 0, 0, 0); __builtin_amdgcn_s_setprio(0); } while (0)
; #define PG8_WAIT_V(n) asm volatile("s_waitcnt vmcnt(" #n ")" ::: "memory")
; #define PG8_WAIT_L(n) asm volatile("s_waitcnt lgkmcnt(" #n ")" ::: "memory")
; #define PG8_BAR __builtin_amdgcn_s_barrier()
; #define PG8_SCHED __builtin_amdgcn_sched_barrier(0)
; template <class Epi, class Sched>
; __device__ __forceinline__ void gemm_phase(PG8_LAS unsigned char* lds, const Gemm g, const Sched& S, const Epi& E) {
;     ...
;             PG8_STAGE(PG8_SB(0, 1), b2 + hstep, voffB);
;             PG8_WAIT_V(6); PG8_BAR; PG8_MMA(1, 1, At, B1); PG8_BAR;
;             PG8_LDB(B0, 1, 0); PG8_SCHED; PG8_LDA(At, 1, 0); PG8_STAGE(PG8_SA(0, 1), a2 + hstep, voffA);
;             PG8_WAIT_L(8); PG8_BAR; PG8_WAIT_L(0); PG8_MMA(0, 0, At, B0); PG8_BAR; PG8_SCHED;
;             PG8_LDB(B1, 1, 1); PG8_STAGE(PG8_SB(1, 0), b3, voffB);
	s_add_u32 s84, s40, 0x100000
	s_addc_u32 s85, s41, 0
	s_add_i32 s27, s54, s29
	s_mov_b32 m0, s27
	v_lshl_add_u64 v[128:129], s[84:85], 0, v[160:161]
	global_load_lds_dwordx4 v[128:129], off
	s_add_i32 m0, s27, 0x2000
	v_lshl_add_u64 v[128:129], s[84:85], 0, v[164:165]
	global_load_lds_dwordx4 v[128:129], off
	s_waitcnt vmcnt(6)
	s_barrier
	v_mfma_f32_16x16x32_bf16 v[52:55], v[204:207], v[144:147], v[52:55]
	v_mfma_f32_16x16x32_bf16 v[48:51], v[212:215], v[144:147], v[48:51]
	v_mfma_f32_16x16x32_bf16 v[36:39], v[204:207], v[174:177], v[36:39]
	v_mfma_f32_16x16x32_bf16 v[32:35], v[212:215], v[174:177], v[32:35]
	v_mfma_f32_16x16x32_bf16 v[20:23], v[204:207], v[182:185], v[20:23]
	v_mfma_f32_16x16x32_bf16 v[16:19], v[212:215], v[182:185], v[16:19]
	v_mfma_f32_16x16x32_bf16 v[4:7], v[204:207], v[196:199], v[4:7]
	v_mfma_f32_16x16x32_bf16 v[0:3], v[212:215], v[196:199], v[0:3]
	v_mfma_f32_16x16x32_bf16 v[52:55], v[208:211], v[148:151], v[52:55]
	v_mfma_f32_16x16x32_bf16 v[48:51], v[216:219], v[148:151], v[48:51]
	v_mfma_f32_16x16x32_bf16 v[36:39], v[208:211], v[178:181], v[36:39]
	v_mfma_f32_16x16x32_bf16 v[32:35], v[216:219], v[178:181], v[32:35]
	v_mfma_f32_16x16x32_bf16 v[20:23], v[208:211], v[186:189], v[20:23]
	v_mfma_f32_16x16x32_bf16 v[16:19], v[216:219], v[186:189], v[16:19]
	v_mfma_f32_16x16x32_bf16 v[4:7], v[208:211], v[200:203], v[4:7]
	v_mfma_f32_16x16x32_bf16 v[0:3], v[216:219], v[200:203], v[0:3]
	s_add_i32 s27, 0, 0x18000
	v_add_u32_e32 v140, s27, v155
	s_barrier
	ds_read_b128 v[128:131], v140
	ds_read_b128 v[132:135], v140 offset:1024
	ds_read_b128 v[136:139], v140 offset:2048
	ds_read_b128 v[140:143], v140 offset:3072
	s_add_u32 s42, s42, 0x100000
	s_addc_u32 s43, s43, 0
	s_mov_b32 m0, s34
	v_lshl_add_u64 v[204:205], s[42:43], 0, v[158:159]
	ds_read_b128 v[144:147], v193 offset:32768
	ds_read_b128 v[148:151], v193 offset:33792
	ds_read_b128 v[174:177], v193 offset:34816
	ds_read_b128 v[178:181], v193 offset:35840
	ds_read_b128 v[182:185], v193 offset:36864
	ds_read_b128 v[186:189], v193 offset:37888
	ds_read_b128 v[196:199], v193 offset:38912
	ds_read_b128 v[200:203], v193 offset:39936
	global_load_lds_dwordx4 v[204:205], off
	s_mov_b32 m0, s35
	v_lshl_add_u64 v[204:205], s[42:43], 0, v[162:163]
	global_load_lds_dwordx4 v[204:205], off
	s_waitcnt lgkmcnt(8)
	s_barrier
	s_waitcnt lgkmcnt(0)
	v_mfma_f32_16x16x32_bf16 v[124:127], v[128:131], v[144:147], v[124:127]
	v_mfma_f32_16x16x32_bf16 v[120:123], v[136:139], v[144:147], v[120:123]
	v_mfma_f32_16x16x32_bf16 v[108:111], v[128:131], v[174:177], v[108:111]
	v_mfma_f32_16x16x32_bf16 v[104:107], v[136:139], v[174:177], v[104:107]
	v_mfma_f32_16x16x32_bf16 v[92:95], v[128:131], v[182:185], v[92:95]
	v_mfma_f32_16x16x32_bf16 v[88:91], v[136:139], v[182:185], v[88:91]
	v_mfma_f32_16x16x32_bf16 v[76:79], v[128:131], v[196:199], v[76:79]
	v_mfma_f32_16x16x32_bf16 v[72:75], v[136:139], v[196:199], v[72:75]
	v_mfma_f32_16x16x32_bf16 v[124:127], v[132:135], v[148:151], v[124:127]
	v_mfma_f32_16x16x32_bf16 v[120:123], v[140:143], v[148:151], v[120:123]
	v_mfma_f32_16x16x32_bf16 v[108:111], v[132:135], v[178:181], v[108:111]
	v_mfma_f32_16x16x32_bf16 v[104:107], v[140:143], v[178:181], v[104:107]
	v_mfma_f32_16x16x32_bf16 v[92:95], v[132:135], v[186:189], v[92:95]
	v_mfma_f32_16x16x32_bf16 v[88:91], v[140:143], v[186:189], v[88:91]
	v_mfma_f32_16x16x32_bf16 v[76:79], v[132:135], v[200:203], v[76:79]
	v_mfma_f32_16x16x32_bf16 v[72:75], v[140:143], v[200:203], v[72:75]
	s_barrier
	s_add_i32 s30, 0, 0x1c000
	s_add_i32 s27, s27, s29
	v_add_u32_e32 v216, s30, v155
	v_lshl_add_u64 v[190:191], v[190:191], 0, s[10:11]
	s_mov_b32 m0, s27
	ds_read_b128 v[204:207], v216
	ds_read_b128 v[208:211], v216 offset:1024
	ds_read_b128 v[212:215], v216 offset:2048
	ds_read_b128 v[216:219], v216 offset:3072
	global_load_lds_dwordx4 v[190:191], off
	s_add_i32 m0, s27, 0x2000
	v_lshl_add_u64 v[190:191], v[220:221], 0, s[10:11]
	global_load_lds_dwordx4 v[190:191], off
	s_barrier
; #define PG8_STAGE(bufoff, gbase, voff) do { _Pragma("unroll") for (int _i = 0; _i < 2; ++_i) \
;         __builtin_amdgcn_global_load_lds((const unsigned*)((const char*)(gbase) + (voff)[_i]), (PG8_LAS unsigned*)(lds + (bufoff) + ldsw + _i * 8192), 16, 0, 0); } while (0)
; #define PG8_LDA(dst, b, h) do { _Pragma("unroll") for (int m = 0; m < 4; ++m) _Pragma("unroll") for (int k = 0; k < 2; ++k) dst[m][k] = *(const PG8_LAS bf16x8*)(lds + PG8_SA(b, h) + aoff + m * 2048 + k * 1024); } while (0)
; #define PG8_MMA(ai, bj, At, Bt) do { __builtin_amdgcn_s_setprio(1); _Pragma("unroll") for (int m = 0; m < 4; ++m) _Pragma("unroll") for (int n = 0; n < 2; ++n) _Pragma("unroll") for (int k = 0; k < 2; ++k) \
;         acc[ai][bj][m][n] = __builtin_amdgcn_mfma_f32_16x16x32_bf16(Bt[n][k], At[m][k], acc[ai][bj][m][n], 0, 0, 0); __builtin_amdgcn_s_setprio(0); } while (0)
; #define PG8_WAIT_V(n) asm volatile("s_waitcnt vmcnt(" #n ")" ::: "memory")
; #define PG8_WAIT_L(n) asm volatile("s_waitcnt lgkmcnt(" #n ")" ::: "memory")
; #define PG8_BAR __builtin_amdgcn_s_barrier()
; #define PG8_SCHED __builtin_amdgcn_sched_barrier(0)
; template <class Epi, class Sched>
; __device__ __forceinline__ void gemm_phase(PG8_LAS unsigned char* lds, const Gemm g, const Sched& S, const Epi& E) {
;     ...
;             PG8_BAR; PG8_WAIT_L(0); PG8_MMA(0, 1, At, B1); PG8_BAR;
;             PG8_LDA(At, 1, 1); PG8_STAGE(PG8_SA(1, 0), a3, voffA);
;             PG8_BAR; PG8_WAIT_L(0); PG8_MMA(1, 0, At, B0); PG8_BAR; PG8_SCHED;
;             PG8_STAGE(PG8_SB(1, 1), b3 + hstep, voffB);
;             PG8_WAIT_V(6); PG8_BAR; PG8_MMA(1, 1, At, B1); PG8_BAR;
;         }
;         if constexpr (!Epi::AFTER_DRAIN) {
;             if (cur.part < 0) E(acc, cur, wr, wc, fr, fq, pre);
	s_waitcnt lgkmcnt(0)
	v_mfma_f32_16x16x32_bf16 v[116:119], v[204:207], v[144:147], v[116:119]
	v_mfma_f32_16x16x32_bf16 v[112:115], v[212:215], v[144:147], v[112:115]
	v_mfma_f32_16x16x32_bf16 v[100:103], v[204:207], v[174:177], v[100:103]
	v_mfma_f32_16x16x32_bf16 v[96:99], v[212:215], v[174:177], v[96:99]
	v_mfma_f32_16x16x32_bf16 v[84:87], v[204:207], v[182:185], v[84:87]
	v_mfma_f32_16x16x32_bf16 v[80:83], v[212:215], v[182:185], v[80:83]
	v_mfma_f32_16x16x32_bf16 v[68:71], v[204:207], v[196:199], v[68:71]
	v_mfma_f32_16x16x32_bf16 v[64:67], v[212:215], v[196:199], v[64:67]
	v_mfma_f32_16x16x32_bf16 v[116:119], v[208:211], v[148:151], v[116:119]
	v_mfma_f32_16x16x32_bf16 v[112:115], v[216:219], v[148:151], v[112:115]
	v_mfma_f32_16x16x32_bf16 v[100:103], v[208:211], v[178:181], v[100:103]
	v_mfma_f32_16x16x32_bf16 v[96:99], v[216:219], v[178:181], v[96:99]
	v_mfma_f32_16x16x32_bf16 v[84:87], v[208:211], v[186:189], v[84:87]
	v_mfma_f32_16x16x32_bf16 v[80:83], v[216:219], v[186:189], v[80:83]
	v_mfma_f32_16x16x32_bf16 v[68:71], v[208:211], v[200:203], v[68:71]
	v_mfma_f32_16x16x32_bf16 v[64:67], v[216:219], v[200:203], v[64:67]
	s_mov_b32 m0, s45
	v_lshl_add_u64 v[190:191], v[222:223], 0, s[10:11]
	s_barrier
	ds_read_b128 v[144:147], v193 offset:49152
	ds_read_b128 v[148:151], v193 offset:50176
	ds_read_b128 v[174:177], v193 offset:51200
	ds_read_b128 v[178:181], v193 offset:52224
	ds_read_b128 v[182:185], v193 offset:53248
	ds_read_b128 v[186:189], v193 offset:54272
	ds_read_b128 v[196:199], v193 offset:55296
	ds_read_b128 v[200:203], v193 offset:56320
	global_load_lds_dwordx4 v[190:191], off
	s_mov_b32 m0, s46
	v_lshl_add_u64 v[190:191], v[224:225], 0, s[10:11]
	global_load_lds_dwordx4 v[190:191], off
	s_barrier
	s_waitcnt lgkmcnt(0)
	v_mfma_f32_16x16x32_bf16 v[60:63], v[128:131], v[144:147], v[60:63]
	v_mfma_f32_16x16x32_bf16 v[56:59], v[136:139], v[144:147], v[56:59]
	v_mfma_f32_16x16x32_bf16 v[44:47], v[128:131], v[174:177], v[44:47]
	v_mfma_f32_16x16x32_bf16 v[40:43], v[136:139], v[174:177], v[40:43]
	v_mfma_f32_16x16x32_bf16 v[28:31], v[128:131], v[182:185], v[28:31]
	v_mfma_f32_16x16x32_bf16 v[24:27], v[136:139], v[182:185], v[24:27]
	v_mfma_f32_16x16x32_bf16 v[12:15], v[128:131], v[196:199], v[12:15]
	v_mfma_f32_16x16x32_bf16 v[8:11], v[136:139], v[196:199], v[8:11]
	v_mfma_f32_16x16x32_bf16 v[60:63], v[132:135], v[148:151], v[60:63]
	v_mfma_f32_16x16x32_bf16 v[56:59], v[140:143], v[148:151], v[56:59]
	v_mfma_f32_16x16x32_bf16 v[44:47], v[132:135], v[178:181], v[44:47]
	v_mfma_f32_16x16x32_bf16 v[40:43], v[140:143], v[178:181], v[40:43]
	v_mfma_f32_16x16x32_bf16 v[28:31], v[132:135], v[186:189], v[28:31]
	v_mfma_f32_16x16x32_bf16 v[24:27], v[140:143], v[186:189], v[24:27]
	v_mfma_f32_16x16x32_bf16 v[12:15], v[132:135], v[200:203], v[12:15]
	v_mfma_f32_16x16x32_bf16 v[8:11], v[140:143], v[200:203], v[8:11]
	s_barrier
	s_add_u32 s40, s40, 0x100080
	s_addc_u32 s41, s41, 0
	s_add_i32 s27, s30, s29
	s_mov_b32 m0, s27
	v_lshl_add_u64 v[128:129], s[40:41], 0, v[160:161]
	global_load_lds_dwordx4 v[128:129], off
	s_add_i32 m0, s27, 0x2000
	v_lshl_add_u64 v[128:129], s[40:41], 0, v[164:165]
	global_load_lds_dwordx4 v[128:129], off
	s_waitcnt vmcnt(6)
	s_barrier
	v_mfma_f32_16x16x32_bf16 v[52:55], v[204:207], v[144:147], v[52:55]
	v_mfma_f32_16x16x32_bf16 v[48:51], v[212:215], v[144:147], v[48:51]
	v_mfma_f32_16x16x32_bf16 v[36:39], v[204:207], v[174:177], v[36:39]
	v_mfma_f32_16x16x32_bf16 v[32:35], v[212:215], v[174:177], v[32:35]
	v_mfma_f32_16x16x32_bf16 v[20:23], v[204:207], v[182:185], v[20:23]
	v_mfma_f32_16x16x32_bf16 v[16:19], v[212:215], v[182:185], v[16:19]
	v_mfma_f32_16x16x32_bf16 v[4:7], v[204:207], v[196:199], v[4:7]
	v_mfma_f32_16x16x32_bf16 v[0:3], v[212:215], v[196:199], v[0:3]
	v_mfma_f32_16x16x32_bf16 v[52:55], v[208:211], v[148:151], v[52:55]
	v_mfma_f32_16x16x32_bf16 v[48:51], v[216:219], v[148:151], v[48:51]
	v_mfma_f32_16x16x32_bf16 v[36:39], v[208:211], v[178:181], v[36:39]
	v_mfma_f32_16x16x32_bf16 v[32:35], v[216:219], v[178:181], v[32:35]
	v_mfma_f32_16x16x32_bf16 v[20:23], v[208:211], v[186:189], v[20:23]
	v_mfma_f32_16x16x32_bf16 v[16:19], v[216:219], v[186:189], v[16:19]
	v_mfma_f32_16x16x32_bf16 v[4:7], v[208:211], v[200:203], v[4:7]
	v_mfma_f32_16x16x32_bf16 v[0:3], v[216:219], v[200:203], v[0:3]
	s_add_u32 s38, s38, 0x100
	s_addc_u32 s39, s39, 0
	s_add_u32 s19, s19, 0x100
	s_addc_u32 s21, s21, 0
	s_cmp_ge_i32 s83, s15
	s_mov_b32 s27, s83
	s_barrier
	s_cbranch_scc0 .LBB0_2574
	s_mov_b32 s84, s68
	s_cmp_gt_i32 s8, -1
	s_mov_b64 s[38:39], -1
	s_cbranch_scc0 .LBB0_2577
